# packed-FMA forward substitution with the mid-solve barrier at row pair 31 of 32
# baseline (speedup 1.0000x reference)
.LBB0_416:
	s_andn2_saveexec_b64 s[6:7], s[6:7]
	s_cbranch_execz .LBB0_284
	v_cmp_gt_i32_e64 s[0:1], s96, v77
	v_add_u32_e32 v39, 0xffffff80, v77
	v_cmp_lt_i32_e32 vcc, s93, v77
	v_cndmask_b32_e64 v0, v65, v74, s[0:1]
	v_cndmask_b32_e64 v1, v39, v77, s[0:1]
	v_lshl_add_u32 v0, v1, 1, v0
	v_cndmask_b32_e64 v1, v75, v76, s[0:1]
	s_nop 0
	v_add_u32_e32 v11, 0, v1
	v_add_u32_e32 v10, 0, v0
	ds_read_b128 v[24:27], v11 offset:0
	ds_read_b128 v[28:31], v11 offset:16
	ds_read_u16 v0, v10 offset:0
	ds_read_u16 v1, v10 offset:272
	ds_read_u16 v2, v10 offset:544
	ds_read_u16 v3, v10 offset:816
	ds_read_u16 v4, v10 offset:1088
	ds_read_u16 v5, v10 offset:1360
	ds_read_u16 v6, v10 offset:1632
	ds_read_u16 v7, v10 offset:1904
	ds_read_b128 v[40:43], v11 offset:32
	ds_read_b128 v[44:47], v11 offset:48
	ds_read_u16 v80, v10 offset:2176
	ds_read_u16 v81, v10 offset:2448
	ds_read_u16 v82, v10 offset:2720
	ds_read_u16 v83, v10 offset:2992
	ds_read_u16 v84, v10 offset:3264
	ds_read_u16 v85, v10 offset:3536
	ds_read_u16 v86, v10 offset:3808
	ds_read_u16 v87, v10 offset:4080
	s_waitcnt lgkmcnt(10)
	v_lshlrev_b32_e32 v0, 16, v0
	v_lshlrev_b32_e32 v1, 16, v1
	v_lshlrev_b32_e32 v2, 16, v2
	v_lshlrev_b32_e32 v3, 16, v3
	v_lshlrev_b32_e32 v4, 16, v4
	v_lshlrev_b32_e32 v5, 16, v5
	v_lshlrev_b32_e32 v6, 16, v6
	v_lshlrev_b32_e32 v7, 16, v7
	v_pk_mul_f32 v[100:101], v[24:25], v[0:1]
	v_pk_mul_f32 v[102:103], v[26:27], v[2:3]
	v_pk_mul_f32 v[104:105], v[28:29], v[4:5]
	v_pk_mul_f32 v[106:107], v[30:31], v[6:7]
	ds_read_b128 v[24:27], v11 offset:64
	ds_read_b128 v[28:31], v11 offset:80
	ds_read_u16 v0, v10 offset:4352
	ds_read_u16 v1, v10 offset:4624
	ds_read_u16 v2, v10 offset:4896
	ds_read_u16 v3, v10 offset:5168
	ds_read_u16 v4, v10 offset:5440
	ds_read_u16 v5, v10 offset:5712
	ds_read_u16 v6, v10 offset:5984
	ds_read_u16 v7, v10 offset:6256
	s_waitcnt lgkmcnt(10)
	v_lshlrev_b32_e32 v80, 16, v80
	v_lshlrev_b32_e32 v81, 16, v81
	v_lshlrev_b32_e32 v82, 16, v82
	v_lshlrev_b32_e32 v83, 16, v83
	v_lshlrev_b32_e32 v84, 16, v84
	v_lshlrev_b32_e32 v85, 16, v85
	v_lshlrev_b32_e32 v86, 16, v86
	v_lshlrev_b32_e32 v87, 16, v87
	v_pk_mul_f32 v[108:109], v[40:41], v[80:81]
	v_pk_mul_f32 v[110:111], v[42:43], v[82:83]
	v_pk_mul_f32 v[112:113], v[44:45], v[84:85]
	v_pk_mul_f32 v[114:115], v[46:47], v[86:87]
	ds_read_b128 v[40:43], v11 offset:96
	ds_read_b128 v[44:47], v11 offset:112
	ds_read_u16 v80, v10 offset:6528
	ds_read_u16 v81, v10 offset:6800
	ds_read_u16 v82, v10 offset:7072
	ds_read_u16 v83, v10 offset:7344
	ds_read_u16 v84, v10 offset:7616
	ds_read_u16 v85, v10 offset:7888
	ds_read_u16 v86, v10 offset:8160
	ds_read_u16 v87, v10 offset:8432
	s_waitcnt lgkmcnt(10)
	v_lshlrev_b32_e32 v0, 16, v0
	v_lshlrev_b32_e32 v1, 16, v1
	v_lshlrev_b32_e32 v2, 16, v2
	v_lshlrev_b32_e32 v3, 16, v3
	v_lshlrev_b32_e32 v4, 16, v4
	v_lshlrev_b32_e32 v5, 16, v5
	v_lshlrev_b32_e32 v6, 16, v6
	v_lshlrev_b32_e32 v7, 16, v7
	v_pk_mul_f32 v[116:117], v[24:25], v[0:1]
	v_pk_mul_f32 v[118:119], v[26:27], v[2:3]
	v_pk_mul_f32 v[120:121], v[28:29], v[4:5]
	v_pk_mul_f32 v[122:123], v[30:31], v[6:7]
	ds_read_b128 v[24:27], v11 offset:128
	ds_read_b128 v[28:31], v11 offset:144
	ds_read_u16 v0, v10 offset:8704
	ds_read_u16 v1, v10 offset:8976
	ds_read_u16 v2, v10 offset:9248
	ds_read_u16 v3, v10 offset:9520
	ds_read_u16 v4, v10 offset:9792
	ds_read_u16 v5, v10 offset:10064
	ds_read_u16 v6, v10 offset:10336
	ds_read_u16 v7, v10 offset:10608
	s_waitcnt lgkmcnt(10)
	v_lshlrev_b32_e32 v80, 16, v80
	v_lshlrev_b32_e32 v81, 16, v81
	v_lshlrev_b32_e32 v82, 16, v82
	v_lshlrev_b32_e32 v83, 16, v83
	v_lshlrev_b32_e32 v84, 16, v84
	v_lshlrev_b32_e32 v85, 16, v85
	v_lshlrev_b32_e32 v86, 16, v86
	v_lshlrev_b32_e32 v87, 16, v87
	v_pk_mul_f32 v[124:125], v[40:41], v[80:81]
	v_pk_mul_f32 v[126:127], v[42:43], v[82:83]
	v_pk_mul_f32 v[128:129], v[44:45], v[84:85]
	v_pk_mul_f32 v[130:131], v[46:47], v[86:87]
	ds_read_b128 v[40:43], v11 offset:160
	ds_read_b128 v[44:47], v11 offset:176
	ds_read_u16 v80, v10 offset:10880
	ds_read_u16 v81, v10 offset:11152
	ds_read_u16 v82, v10 offset:11424
	ds_read_u16 v83, v10 offset:11696
	ds_read_u16 v84, v10 offset:11968
	ds_read_u16 v85, v10 offset:12240
	ds_read_u16 v86, v10 offset:12512
	ds_read_u16 v87, v10 offset:12784
	s_waitcnt lgkmcnt(10)
	v_lshlrev_b32_e32 v0, 16, v0
	v_lshlrev_b32_e32 v1, 16, v1
	v_lshlrev_b32_e32 v2, 16, v2
	v_lshlrev_b32_e32 v3, 16, v3
	v_lshlrev_b32_e32 v4, 16, v4
	v_lshlrev_b32_e32 v5, 16, v5
	v_lshlrev_b32_e32 v6, 16, v6
	v_lshlrev_b32_e32 v7, 16, v7
	v_pk_mul_f32 v[132:133], v[24:25], v[0:1]
	v_pk_mul_f32 v[134:135], v[26:27], v[2:3]
	v_pk_mul_f32 v[136:137], v[28:29], v[4:5]
	v_pk_mul_f32 v[138:139], v[30:31], v[6:7]
	ds_read_b128 v[24:27], v11 offset:192
	ds_read_b128 v[28:31], v11 offset:208
	ds_read_u16 v0, v10 offset:13056
	ds_read_u16 v1, v10 offset:13328
	ds_read_u16 v2, v10 offset:13600
	ds_read_u16 v3, v10 offset:13872
	ds_read_u16 v4, v10 offset:14144
	ds_read_u16 v5, v10 offset:14416
	ds_read_u16 v6, v10 offset:14688
	ds_read_u16 v7, v10 offset:14960
	s_waitcnt lgkmcnt(10)
	v_lshlrev_b32_e32 v80, 16, v80
	v_lshlrev_b32_e32 v81, 16, v81
	v_lshlrev_b32_e32 v82, 16, v82
	v_lshlrev_b32_e32 v83, 16, v83
	v_lshlrev_b32_e32 v84, 16, v84
	v_lshlrev_b32_e32 v85, 16, v85
	v_lshlrev_b32_e32 v86, 16, v86
	v_lshlrev_b32_e32 v87, 16, v87
	v_pk_mul_f32 v[140:141], v[40:41], v[80:81]
	v_pk_mul_f32 v[142:143], v[42:43], v[82:83]
	v_pk_mul_f32 v[144:145], v[44:45], v[84:85]
	v_pk_mul_f32 v[146:147], v[46:47], v[86:87]
	ds_read_b128 v[40:43], v11 offset:224
	ds_read_b128 v[44:47], v11 offset:240
	ds_read_u16 v80, v10 offset:15232
	ds_read_u16 v81, v10 offset:15504
	ds_read_u16 v82, v10 offset:15776
	ds_read_u16 v83, v10 offset:16048
	ds_read_u16 v84, v10 offset:16320
	ds_read_u16 v85, v10 offset:16592
	ds_read_u16 v86, v10 offset:16864
	ds_read_u16 v87, v10 offset:17136
	s_waitcnt lgkmcnt(10)
	v_lshlrev_b32_e32 v0, 16, v0
	v_lshlrev_b32_e32 v1, 16, v1
	v_lshlrev_b32_e32 v2, 16, v2
	v_lshlrev_b32_e32 v3, 16, v3
	v_lshlrev_b32_e32 v4, 16, v4
	v_lshlrev_b32_e32 v5, 16, v5
	v_lshlrev_b32_e32 v6, 16, v6
	v_lshlrev_b32_e32 v7, 16, v7
	v_pk_mul_f32 v[148:149], v[24:25], v[0:1]
	v_pk_mul_f32 v[150:151], v[26:27], v[2:3]
	v_pk_mul_f32 v[152:153], v[28:29], v[4:5]
	v_pk_mul_f32 v[154:155], v[30:31], v[6:7]
	s_waitcnt lgkmcnt(0)
	v_lshlrev_b32_e32 v80, 16, v80
	v_lshlrev_b32_e32 v81, 16, v81
	v_lshlrev_b32_e32 v82, 16, v82
	v_lshlrev_b32_e32 v83, 16, v83
	v_lshlrev_b32_e32 v84, 16, v84
	v_lshlrev_b32_e32 v85, 16, v85
	v_lshlrev_b32_e32 v86, 16, v86
	v_lshlrev_b32_e32 v87, 16, v87
	v_pk_mul_f32 v[156:157], v[40:41], v[80:81]
	v_pk_mul_f32 v[158:159], v[42:43], v[82:83]
	v_pk_mul_f32 v[160:161], v[44:45], v[84:85]
	v_pk_mul_f32 v[162:163], v[46:47], v[86:87]
	v_mov_b32_e32 v228, 0xcc00
	ds_read_b128 v[164:167], v228 offset:0
	ds_read_b128 v[168:171], v228 offset:512
	ds_read_b128 v[172:175], v228 offset:528
	ds_read_b128 v[176:179], v228 offset:1024
	ds_read_b128 v[180:183], v228 offset:1040
	ds_read_b128 v[184:187], v228 offset:1056
	ds_read_b128 v[188:191], v228 offset:1536
	ds_read_b128 v[192:195], v228 offset:1552
	ds_read_b128 v[196:199], v228 offset:1568
	ds_read_b128 v[200:203], v228 offset:1584
	ds_read_b128 v[204:207], v228 offset:2048
	ds_read_b128 v[208:211], v228 offset:2064
	ds_read_b128 v[212:215], v228 offset:2080
	ds_read_b128 v[216:219], v228 offset:2096
	ds_read_b128 v[220:223], v228 offset:2112
	ds_read_b128 v[224:227], v228 offset:2560
	s_waitcnt lgkmcnt(14)
	v_fma_f32 v101, -v165, v100, v101
	v_pk_fma_f32 v[102:103], v[168:169], v[100:101], v[102:103] op_sel_hi:[1,0,1] neg_lo:[1,0,0] neg_hi:[1,0,0]
	v_pk_fma_f32 v[102:103], v[170:171], v[100:101], v[102:103] op_sel:[0,1,0] neg_lo:[1,0,0] neg_hi:[1,0,0]
	ds_read_b128 v[164:167], v228 offset:2576
	ds_read_b128 v[168:171], v228 offset:2592
	s_waitcnt lgkmcnt(14)
	v_fma_f32 v103, -v173, v102, v103
	v_pk_fma_f32 v[104:105], v[176:177], v[100:101], v[104:105] op_sel_hi:[1,0,1] neg_lo:[1,0,0] neg_hi:[1,0,0]
	v_pk_fma_f32 v[104:105], v[178:179], v[100:101], v[104:105] op_sel:[0,1,0] neg_lo:[1,0,0] neg_hi:[1,0,0]
	ds_read_b128 v[172:175], v228 offset:2608
	ds_read_b128 v[176:179], v228 offset:2624
	s_waitcnt lgkmcnt(14)
	v_pk_fma_f32 v[104:105], v[180:181], v[102:103], v[104:105] op_sel_hi:[1,0,1] neg_lo:[1,0,0] neg_hi:[1,0,0]
	v_pk_fma_f32 v[104:105], v[182:183], v[102:103], v[104:105] op_sel:[0,1,0] neg_lo:[1,0,0] neg_hi:[1,0,0]
	v_fma_f32 v105, -v185, v104, v105
	ds_read_b128 v[180:183], v228 offset:2640
	ds_read_b128 v[184:187], v228 offset:3072
	s_waitcnt lgkmcnt(14)
	v_pk_fma_f32 v[106:107], v[188:189], v[100:101], v[106:107] op_sel_hi:[1,0,1] neg_lo:[1,0,0] neg_hi:[1,0,0]
	v_pk_fma_f32 v[106:107], v[190:191], v[100:101], v[106:107] op_sel:[0,1,0] neg_lo:[1,0,0] neg_hi:[1,0,0]
	v_pk_fma_f32 v[106:107], v[192:193], v[102:103], v[106:107] op_sel_hi:[1,0,1] neg_lo:[1,0,0] neg_hi:[1,0,0]
	v_pk_fma_f32 v[106:107], v[194:195], v[102:103], v[106:107] op_sel:[0,1,0] neg_lo:[1,0,0] neg_hi:[1,0,0]
	ds_read_b128 v[188:191], v228 offset:3088
	ds_read_b128 v[192:195], v228 offset:3104
	s_waitcnt lgkmcnt(14)
	v_pk_fma_f32 v[106:107], v[196:197], v[104:105], v[106:107] op_sel_hi:[1,0,1] neg_lo:[1,0,0] neg_hi:[1,0,0]
	v_pk_fma_f32 v[106:107], v[198:199], v[104:105], v[106:107] op_sel:[0,1,0] neg_lo:[1,0,0] neg_hi:[1,0,0]
	v_fma_f32 v107, -v201, v106, v107
	ds_read_b128 v[196:199], v228 offset:3120
	ds_read_b128 v[200:203], v228 offset:3136
	s_waitcnt lgkmcnt(14)
	v_pk_fma_f32 v[108:109], v[204:205], v[100:101], v[108:109] op_sel_hi:[1,0,1] neg_lo:[1,0,0] neg_hi:[1,0,0]
	v_pk_fma_f32 v[108:109], v[206:207], v[100:101], v[108:109] op_sel:[0,1,0] neg_lo:[1,0,0] neg_hi:[1,0,0]
	v_pk_fma_f32 v[108:109], v[208:209], v[102:103], v[108:109] op_sel_hi:[1,0,1] neg_lo:[1,0,0] neg_hi:[1,0,0]
	v_pk_fma_f32 v[108:109], v[210:211], v[102:103], v[108:109] op_sel:[0,1,0] neg_lo:[1,0,0] neg_hi:[1,0,0]
	ds_read_b128 v[204:207], v228 offset:3152
	ds_read_b128 v[208:211], v228 offset:3168
	s_waitcnt lgkmcnt(14)
	v_pk_fma_f32 v[108:109], v[212:213], v[104:105], v[108:109] op_sel_hi:[1,0,1] neg_lo:[1,0,0] neg_hi:[1,0,0]
	v_pk_fma_f32 v[108:109], v[214:215], v[104:105], v[108:109] op_sel:[0,1,0] neg_lo:[1,0,0] neg_hi:[1,0,0]
	v_pk_fma_f32 v[108:109], v[216:217], v[106:107], v[108:109] op_sel_hi:[1,0,1] neg_lo:[1,0,0] neg_hi:[1,0,0]
	v_pk_fma_f32 v[108:109], v[218:219], v[106:107], v[108:109] op_sel:[0,1,0] neg_lo:[1,0,0] neg_hi:[1,0,0]
	ds_read_b128 v[212:215], v228 offset:3584
	ds_read_b128 v[216:219], v228 offset:3600
	s_waitcnt lgkmcnt(14)
	v_fma_f32 v109, -v221, v108, v109
	v_pk_fma_f32 v[110:111], v[224:225], v[100:101], v[110:111] op_sel_hi:[1,0,1] neg_lo:[1,0,0] neg_hi:[1,0,0]
	v_pk_fma_f32 v[110:111], v[226:227], v[100:101], v[110:111] op_sel:[0,1,0] neg_lo:[1,0,0] neg_hi:[1,0,0]
	ds_read_b128 v[220:223], v228 offset:3616
	ds_read_b128 v[224:227], v228 offset:3632
	s_waitcnt lgkmcnt(14)
	v_pk_fma_f32 v[110:111], v[164:165], v[102:103], v[110:111] op_sel_hi:[1,0,1] neg_lo:[1,0,0] neg_hi:[1,0,0]
	v_pk_fma_f32 v[110:111], v[166:167], v[102:103], v[110:111] op_sel:[0,1,0] neg_lo:[1,0,0] neg_hi:[1,0,0]
	v_pk_fma_f32 v[110:111], v[168:169], v[104:105], v[110:111] op_sel_hi:[1,0,1] neg_lo:[1,0,0] neg_hi:[1,0,0]
	v_pk_fma_f32 v[110:111], v[170:171], v[104:105], v[110:111] op_sel:[0,1,0] neg_lo:[1,0,0] neg_hi:[1,0,0]
	ds_read_b128 v[164:167], v228 offset:3648
	ds_read_b128 v[168:171], v228 offset:3664
	s_waitcnt lgkmcnt(14)
	v_pk_fma_f32 v[110:111], v[172:173], v[106:107], v[110:111] op_sel_hi:[1,0,1] neg_lo:[1,0,0] neg_hi:[1,0,0]
	v_pk_fma_f32 v[110:111], v[174:175], v[106:107], v[110:111] op_sel:[0,1,0] neg_lo:[1,0,0] neg_hi:[1,0,0]
	v_pk_fma_f32 v[110:111], v[176:177], v[108:109], v[110:111] op_sel_hi:[1,0,1] neg_lo:[1,0,0] neg_hi:[1,0,0]
	v_pk_fma_f32 v[110:111], v[178:179], v[108:109], v[110:111] op_sel:[0,1,0] neg_lo:[1,0,0] neg_hi:[1,0,0]
	ds_read_b128 v[172:175], v228 offset:3680
	ds_read_b128 v[176:179], v228 offset:3696
	s_waitcnt lgkmcnt(14)
	v_fma_f32 v111, -v181, v110, v111
	v_pk_fma_f32 v[112:113], v[184:185], v[100:101], v[112:113] op_sel_hi:[1,0,1] neg_lo:[1,0,0] neg_hi:[1,0,0]
	v_pk_fma_f32 v[112:113], v[186:187], v[100:101], v[112:113] op_sel:[0,1,0] neg_lo:[1,0,0] neg_hi:[1,0,0]
	ds_read_b128 v[180:183], v228 offset:4096
	ds_read_b128 v[184:187], v228 offset:4112
	s_waitcnt lgkmcnt(14)
	v_pk_fma_f32 v[112:113], v[188:189], v[102:103], v[112:113] op_sel_hi:[1,0,1] neg_lo:[1,0,0] neg_hi:[1,0,0]
	v_pk_fma_f32 v[112:113], v[190:191], v[102:103], v[112:113] op_sel:[0,1,0] neg_lo:[1,0,0] neg_hi:[1,0,0]
	v_pk_fma_f32 v[112:113], v[192:193], v[104:105], v[112:113] op_sel_hi:[1,0,1] neg_lo:[1,0,0] neg_hi:[1,0,0]
	v_pk_fma_f32 v[112:113], v[194:195], v[104:105], v[112:113] op_sel:[0,1,0] neg_lo:[1,0,0] neg_hi:[1,0,0]
	ds_read_b128 v[188:191], v228 offset:4128
	ds_read_b128 v[192:195], v228 offset:4144
	s_waitcnt lgkmcnt(14)
	v_pk_fma_f32 v[112:113], v[196:197], v[106:107], v[112:113] op_sel_hi:[1,0,1] neg_lo:[1,0,0] neg_hi:[1,0,0]
	v_pk_fma_f32 v[112:113], v[198:199], v[106:107], v[112:113] op_sel:[0,1,0] neg_lo:[1,0,0] neg_hi:[1,0,0]
	v_pk_fma_f32 v[112:113], v[200:201], v[108:109], v[112:113] op_sel_hi:[1,0,1] neg_lo:[1,0,0] neg_hi:[1,0,0]
	v_pk_fma_f32 v[112:113], v[202:203], v[108:109], v[112:113] op_sel:[0,1,0] neg_lo:[1,0,0] neg_hi:[1,0,0]
	ds_read_b128 v[196:199], v228 offset:4160
	ds_read_b128 v[200:203], v228 offset:4176
	s_waitcnt lgkmcnt(14)
	v_pk_fma_f32 v[112:113], v[204:205], v[110:111], v[112:113] op_sel_hi:[1,0,1] neg_lo:[1,0,0] neg_hi:[1,0,0]
	v_pk_fma_f32 v[112:113], v[206:207], v[110:111], v[112:113] op_sel:[0,1,0] neg_lo:[1,0,0] neg_hi:[1,0,0]
	v_fma_f32 v113, -v209, v112, v113
	ds_read_b128 v[204:207], v228 offset:4192
	ds_read_b128 v[208:211], v228 offset:4208
	s_waitcnt lgkmcnt(14)
	v_pk_fma_f32 v[114:115], v[212:213], v[100:101], v[114:115] op_sel_hi:[1,0,1] neg_lo:[1,0,0] neg_hi:[1,0,0]
	v_pk_fma_f32 v[114:115], v[214:215], v[100:101], v[114:115] op_sel:[0,1,0] neg_lo:[1,0,0] neg_hi:[1,0,0]
	v_pk_fma_f32 v[114:115], v[216:217], v[102:103], v[114:115] op_sel_hi:[1,0,1] neg_lo:[1,0,0] neg_hi:[1,0,0]
	v_pk_fma_f32 v[114:115], v[218:219], v[102:103], v[114:115] op_sel:[0,1,0] neg_lo:[1,0,0] neg_hi:[1,0,0]
	ds_read_b128 v[212:215], v228 offset:4224
	ds_read_b128 v[216:219], v228 offset:4608
	s_waitcnt lgkmcnt(14)
	v_pk_fma_f32 v[114:115], v[220:221], v[104:105], v[114:115] op_sel_hi:[1,0,1] neg_lo:[1,0,0] neg_hi:[1,0,0]
	v_pk_fma_f32 v[114:115], v[222:223], v[104:105], v[114:115] op_sel:[0,1,0] neg_lo:[1,0,0] neg_hi:[1,0,0]
	v_pk_fma_f32 v[114:115], v[224:225], v[106:107], v[114:115] op_sel_hi:[1,0,1] neg_lo:[1,0,0] neg_hi:[1,0,0]
	v_pk_fma_f32 v[114:115], v[226:227], v[106:107], v[114:115] op_sel:[0,1,0] neg_lo:[1,0,0] neg_hi:[1,0,0]
	ds_read_b128 v[220:223], v228 offset:4624
	ds_read_b128 v[224:227], v228 offset:4640
	s_waitcnt lgkmcnt(14)
	v_pk_fma_f32 v[114:115], v[164:165], v[108:109], v[114:115] op_sel_hi:[1,0,1] neg_lo:[1,0,0] neg_hi:[1,0,0]
	v_pk_fma_f32 v[114:115], v[166:167], v[108:109], v[114:115] op_sel:[0,1,0] neg_lo:[1,0,0] neg_hi:[1,0,0]
	v_pk_fma_f32 v[114:115], v[168:169], v[110:111], v[114:115] op_sel_hi:[1,0,1] neg_lo:[1,0,0] neg_hi:[1,0,0]
	v_pk_fma_f32 v[114:115], v[170:171], v[110:111], v[114:115] op_sel:[0,1,0] neg_lo:[1,0,0] neg_hi:[1,0,0]
	ds_read_b128 v[164:167], v228 offset:4656
	ds_read_b128 v[168:171], v228 offset:4672
	s_waitcnt lgkmcnt(14)
	v_pk_fma_f32 v[114:115], v[172:173], v[112:113], v[114:115] op_sel_hi:[1,0,1] neg_lo:[1,0,0] neg_hi:[1,0,0]
	v_pk_fma_f32 v[114:115], v[174:175], v[112:113], v[114:115] op_sel:[0,1,0] neg_lo:[1,0,0] neg_hi:[1,0,0]
	v_fma_f32 v115, -v177, v114, v115
	ds_read_b128 v[172:175], v228 offset:4688
	ds_read_b128 v[176:179], v228 offset:4704
	s_waitcnt lgkmcnt(14)
	v_pk_fma_f32 v[116:117], v[180:181], v[100:101], v[116:117] op_sel_hi:[1,0,1] neg_lo:[1,0,0] neg_hi:[1,0,0]
	v_pk_fma_f32 v[116:117], v[182:183], v[100:101], v[116:117] op_sel:[0,1,0] neg_lo:[1,0,0] neg_hi:[1,0,0]
	v_pk_fma_f32 v[116:117], v[184:185], v[102:103], v[116:117] op_sel_hi:[1,0,1] neg_lo:[1,0,0] neg_hi:[1,0,0]
	v_pk_fma_f32 v[116:117], v[186:187], v[102:103], v[116:117] op_sel:[0,1,0] neg_lo:[1,0,0] neg_hi:[1,0,0]
	ds_read_b128 v[180:183], v228 offset:4720
	ds_read_b128 v[184:187], v228 offset:4736
	s_waitcnt lgkmcnt(14)
	v_pk_fma_f32 v[116:117], v[188:189], v[104:105], v[116:117] op_sel_hi:[1,0,1] neg_lo:[1,0,0] neg_hi:[1,0,0]
	v_pk_fma_f32 v[116:117], v[190:191], v[104:105], v[116:117] op_sel:[0,1,0] neg_lo:[1,0,0] neg_hi:[1,0,0]
	v_pk_fma_f32 v[116:117], v[192:193], v[106:107], v[116:117] op_sel_hi:[1,0,1] neg_lo:[1,0,0] neg_hi:[1,0,0]
	v_pk_fma_f32 v[116:117], v[194:195], v[106:107], v[116:117] op_sel:[0,1,0] neg_lo:[1,0,0] neg_hi:[1,0,0]
	ds_read_b128 v[188:191], v228 offset:4752
	ds_read_b128 v[192:195], v228 offset:5120
	s_waitcnt lgkmcnt(14)
	v_pk_fma_f32 v[116:117], v[196:197], v[108:109], v[116:117] op_sel_hi:[1,0,1] neg_lo:[1,0,0] neg_hi:[1,0,0]
	v_pk_fma_f32 v[116:117], v[198:199], v[108:109], v[116:117] op_sel:[0,1,0] neg_lo:[1,0,0] neg_hi:[1,0,0]
	v_pk_fma_f32 v[116:117], v[200:201], v[110:111], v[116:117] op_sel_hi:[1,0,1] neg_lo:[1,0,0] neg_hi:[1,0,0]
	v_pk_fma_f32 v[116:117], v[202:203], v[110:111], v[116:117] op_sel:[0,1,0] neg_lo:[1,0,0] neg_hi:[1,0,0]
	ds_read_b128 v[196:199], v228 offset:5136
	ds_read_b128 v[200:203], v228 offset:5152
	s_waitcnt lgkmcnt(14)
	v_pk_fma_f32 v[116:117], v[204:205], v[112:113], v[116:117] op_sel_hi:[1,0,1] neg_lo:[1,0,0] neg_hi:[1,0,0]
	v_pk_fma_f32 v[116:117], v[206:207], v[112:113], v[116:117] op_sel:[0,1,0] neg_lo:[1,0,0] neg_hi:[1,0,0]
	v_pk_fma_f32 v[116:117], v[208:209], v[114:115], v[116:117] op_sel_hi:[1,0,1] neg_lo:[1,0,0] neg_hi:[1,0,0]
	v_pk_fma_f32 v[116:117], v[210:211], v[114:115], v[116:117] op_sel:[0,1,0] neg_lo:[1,0,0] neg_hi:[1,0,0]
	ds_read_b128 v[204:207], v228 offset:5168
	ds_read_b128 v[208:211], v228 offset:5184
	s_waitcnt lgkmcnt(14)
	v_fma_f32 v117, -v213, v116, v117
	v_pk_fma_f32 v[118:119], v[216:217], v[100:101], v[118:119] op_sel_hi:[1,0,1] neg_lo:[1,0,0] neg_hi:[1,0,0]
	v_pk_fma_f32 v[118:119], v[218:219], v[100:101], v[118:119] op_sel:[0,1,0] neg_lo:[1,0,0] neg_hi:[1,0,0]
	ds_read_b128 v[212:215], v228 offset:5200
	ds_read_b128 v[216:219], v228 offset:5216
	s_waitcnt lgkmcnt(14)
	v_pk_fma_f32 v[118:119], v[220:221], v[102:103], v[118:119] op_sel_hi:[1,0,1] neg_lo:[1,0,0] neg_hi:[1,0,0]
	v_pk_fma_f32 v[118:119], v[222:223], v[102:103], v[118:119] op_sel:[0,1,0] neg_lo:[1,0,0] neg_hi:[1,0,0]
	v_pk_fma_f32 v[118:119], v[224:225], v[104:105], v[118:119] op_sel_hi:[1,0,1] neg_lo:[1,0,0] neg_hi:[1,0,0]
	v_pk_fma_f32 v[118:119], v[226:227], v[104:105], v[118:119] op_sel:[0,1,0] neg_lo:[1,0,0] neg_hi:[1,0,0]
	ds_read_b128 v[220:223], v228 offset:5232
	ds_read_b128 v[224:227], v228 offset:5248
	s_waitcnt lgkmcnt(14)
	v_pk_fma_f32 v[118:119], v[164:165], v[106:107], v[118:119] op_sel_hi:[1,0,1] neg_lo:[1,0,0] neg_hi:[1,0,0]
	v_pk_fma_f32 v[118:119], v[166:167], v[106:107], v[118:119] op_sel:[0,1,0] neg_lo:[1,0,0] neg_hi:[1,0,0]
	v_pk_fma_f32 v[118:119], v[168:169], v[108:109], v[118:119] op_sel_hi:[1,0,1] neg_lo:[1,0,0] neg_hi:[1,0,0]
	v_pk_fma_f32 v[118:119], v[170:171], v[108:109], v[118:119] op_sel:[0,1,0] neg_lo:[1,0,0] neg_hi:[1,0,0]
	ds_read_b128 v[164:167], v228 offset:5264
	ds_read_b128 v[168:171], v228 offset:5280
	s_waitcnt lgkmcnt(14)
	v_pk_fma_f32 v[118:119], v[172:173], v[110:111], v[118:119] op_sel_hi:[1,0,1] neg_lo:[1,0,0] neg_hi:[1,0,0]
	v_pk_fma_f32 v[118:119], v[174:175], v[110:111], v[118:119] op_sel:[0,1,0] neg_lo:[1,0,0] neg_hi:[1,0,0]
	v_pk_fma_f32 v[118:119], v[176:177], v[112:113], v[118:119] op_sel_hi:[1,0,1] neg_lo:[1,0,0] neg_hi:[1,0,0]
	v_pk_fma_f32 v[118:119], v[178:179], v[112:113], v[118:119] op_sel:[0,1,0] neg_lo:[1,0,0] neg_hi:[1,0,0]
	ds_read_b128 v[172:175], v228 offset:5632
	ds_read_b128 v[176:179], v228 offset:5648
	s_waitcnt lgkmcnt(14)
	v_pk_fma_f32 v[118:119], v[180:181], v[114:115], v[118:119] op_sel_hi:[1,0,1] neg_lo:[1,0,0] neg_hi:[1,0,0]
	v_pk_fma_f32 v[118:119], v[182:183], v[114:115], v[118:119] op_sel:[0,1,0] neg_lo:[1,0,0] neg_hi:[1,0,0]
	v_pk_fma_f32 v[118:119], v[184:185], v[116:117], v[118:119] op_sel_hi:[1,0,1] neg_lo:[1,0,0] neg_hi:[1,0,0]
	v_pk_fma_f32 v[118:119], v[186:187], v[116:117], v[118:119] op_sel:[0,1,0] neg_lo:[1,0,0] neg_hi:[1,0,0]
	ds_read_b128 v[180:183], v228 offset:5664
	ds_read_b128 v[184:187], v228 offset:5680
	s_waitcnt lgkmcnt(14)
	v_fma_f32 v119, -v189, v118, v119
	v_pk_fma_f32 v[120:121], v[192:193], v[100:101], v[120:121] op_sel_hi:[1,0,1] neg_lo:[1,0,0] neg_hi:[1,0,0]
	v_pk_fma_f32 v[120:121], v[194:195], v[100:101], v[120:121] op_sel:[0,1,0] neg_lo:[1,0,0] neg_hi:[1,0,0]
	ds_read_b128 v[188:191], v228 offset:5696
	ds_read_b128 v[192:195], v228 offset:5712
	s_waitcnt lgkmcnt(14)
	v_pk_fma_f32 v[120:121], v[196:197], v[102:103], v[120:121] op_sel_hi:[1,0,1] neg_lo:[1,0,0] neg_hi:[1,0,0]
	v_pk_fma_f32 v[120:121], v[198:199], v[102:103], v[120:121] op_sel:[0,1,0] neg_lo:[1,0,0] neg_hi:[1,0,0]
	v_pk_fma_f32 v[120:121], v[200:201], v[104:105], v[120:121] op_sel_hi:[1,0,1] neg_lo:[1,0,0] neg_hi:[1,0,0]
	v_pk_fma_f32 v[120:121], v[202:203], v[104:105], v[120:121] op_sel:[0,1,0] neg_lo:[1,0,0] neg_hi:[1,0,0]
	ds_read_b128 v[196:199], v228 offset:5728
	ds_read_b128 v[200:203], v228 offset:5744
	s_waitcnt lgkmcnt(14)
	v_pk_fma_f32 v[120:121], v[204:205], v[106:107], v[120:121] op_sel_hi:[1,0,1] neg_lo:[1,0,0] neg_hi:[1,0,0]
	v_pk_fma_f32 v[120:121], v[206:207], v[106:107], v[120:121] op_sel:[0,1,0] neg_lo:[1,0,0] neg_hi:[1,0,0]
	v_pk_fma_f32 v[120:121], v[208:209], v[108:109], v[120:121] op_sel_hi:[1,0,1] neg_lo:[1,0,0] neg_hi:[1,0,0]
	v_pk_fma_f32 v[120:121], v[210:211], v[108:109], v[120:121] op_sel:[0,1,0] neg_lo:[1,0,0] neg_hi:[1,0,0]
	ds_read_b128 v[204:207], v228 offset:5760
	ds_read_b128 v[208:211], v228 offset:5776
	s_waitcnt lgkmcnt(14)
	v_pk_fma_f32 v[120:121], v[212:213], v[110:111], v[120:121] op_sel_hi:[1,0,1] neg_lo:[1,0,0] neg_hi:[1,0,0]
	v_pk_fma_f32 v[120:121], v[214:215], v[110:111], v[120:121] op_sel:[0,1,0] neg_lo:[1,0,0] neg_hi:[1,0,0]
	v_pk_fma_f32 v[120:121], v[216:217], v[112:113], v[120:121] op_sel_hi:[1,0,1] neg_lo:[1,0,0] neg_hi:[1,0,0]
	v_pk_fma_f32 v[120:121], v[218:219], v[112:113], v[120:121] op_sel:[0,1,0] neg_lo:[1,0,0] neg_hi:[1,0,0]
	ds_read_b128 v[212:215], v228 offset:5792
	ds_read_b128 v[216:219], v228 offset:5808
	s_waitcnt lgkmcnt(14)
	v_pk_fma_f32 v[120:121], v[220:221], v[114:115], v[120:121] op_sel_hi:[1,0,1] neg_lo:[1,0,0] neg_hi:[1,0,0]
	v_pk_fma_f32 v[120:121], v[222:223], v[114:115], v[120:121] op_sel:[0,1,0] neg_lo:[1,0,0] neg_hi:[1,0,0]
	v_pk_fma_f32 v[120:121], v[224:225], v[116:117], v[120:121] op_sel_hi:[1,0,1] neg_lo:[1,0,0] neg_hi:[1,0,0]
	v_pk_fma_f32 v[120:121], v[226:227], v[116:117], v[120:121] op_sel:[0,1,0] neg_lo:[1,0,0] neg_hi:[1,0,0]
	ds_read_b128 v[220:223], v228 offset:6144
	ds_read_b128 v[224:227], v228 offset:6160
	s_waitcnt lgkmcnt(14)
	v_pk_fma_f32 v[120:121], v[164:165], v[118:119], v[120:121] op_sel_hi:[1,0,1] neg_lo:[1,0,0] neg_hi:[1,0,0]
	v_pk_fma_f32 v[120:121], v[166:167], v[118:119], v[120:121] op_sel:[0,1,0] neg_lo:[1,0,0] neg_hi:[1,0,0]
	v_fma_f32 v121, -v169, v120, v121
	ds_read_b128 v[164:167], v228 offset:6176
	ds_read_b128 v[168:171], v228 offset:6192
	s_waitcnt lgkmcnt(14)
	v_pk_fma_f32 v[122:123], v[172:173], v[100:101], v[122:123] op_sel_hi:[1,0,1] neg_lo:[1,0,0] neg_hi:[1,0,0]
	v_pk_fma_f32 v[122:123], v[174:175], v[100:101], v[122:123] op_sel:[0,1,0] neg_lo:[1,0,0] neg_hi:[1,0,0]
	v_pk_fma_f32 v[122:123], v[176:177], v[102:103], v[122:123] op_sel_hi:[1,0,1] neg_lo:[1,0,0] neg_hi:[1,0,0]
	v_pk_fma_f32 v[122:123], v[178:179], v[102:103], v[122:123] op_sel:[0,1,0] neg_lo:[1,0,0] neg_hi:[1,0,0]
	ds_read_b128 v[172:175], v228 offset:6208
	ds_read_b128 v[176:179], v228 offset:6224
	s_waitcnt lgkmcnt(14)
	v_pk_fma_f32 v[122:123], v[180:181], v[104:105], v[122:123] op_sel_hi:[1,0,1] neg_lo:[1,0,0] neg_hi:[1,0,0]
	v_pk_fma_f32 v[122:123], v[182:183], v[104:105], v[122:123] op_sel:[0,1,0] neg_lo:[1,0,0] neg_hi:[1,0,0]
	v_pk_fma_f32 v[122:123], v[184:185], v[106:107], v[122:123] op_sel_hi:[1,0,1] neg_lo:[1,0,0] neg_hi:[1,0,0]
	v_pk_fma_f32 v[122:123], v[186:187], v[106:107], v[122:123] op_sel:[0,1,0] neg_lo:[1,0,0] neg_hi:[1,0,0]
	ds_read_b128 v[180:183], v228 offset:6240
	ds_read_b128 v[184:187], v228 offset:6256
	s_waitcnt lgkmcnt(14)
	v_pk_fma_f32 v[122:123], v[188:189], v[108:109], v[122:123] op_sel_hi:[1,0,1] neg_lo:[1,0,0] neg_hi:[1,0,0]
	v_pk_fma_f32 v[122:123], v[190:191], v[108:109], v[122:123] op_sel:[0,1,0] neg_lo:[1,0,0] neg_hi:[1,0,0]
	v_pk_fma_f32 v[122:123], v[192:193], v[110:111], v[122:123] op_sel_hi:[1,0,1] neg_lo:[1,0,0] neg_hi:[1,0,0]
	v_pk_fma_f32 v[122:123], v[194:195], v[110:111], v[122:123] op_sel:[0,1,0] neg_lo:[1,0,0] neg_hi:[1,0,0]
	ds_read_b128 v[188:191], v228 offset:6272
	ds_read_b128 v[192:195], v228 offset:6288
	s_waitcnt lgkmcnt(14)
	v_pk_fma_f32 v[122:123], v[196:197], v[112:113], v[122:123] op_sel_hi:[1,0,1] neg_lo:[1,0,0] neg_hi:[1,0,0]
	v_pk_fma_f32 v[122:123], v[198:199], v[112:113], v[122:123] op_sel:[0,1,0] neg_lo:[1,0,0] neg_hi:[1,0,0]
	v_pk_fma_f32 v[122:123], v[200:201], v[114:115], v[122:123] op_sel_hi:[1,0,1] neg_lo:[1,0,0] neg_hi:[1,0,0]
	v_pk_fma_f32 v[122:123], v[202:203], v[114:115], v[122:123] op_sel:[0,1,0] neg_lo:[1,0,0] neg_hi:[1,0,0]
	ds_read_b128 v[196:199], v228 offset:6304
	ds_read_b128 v[200:203], v228 offset:6320
	s_waitcnt lgkmcnt(14)
	v_pk_fma_f32 v[122:123], v[204:205], v[116:117], v[122:123] op_sel_hi:[1,0,1] neg_lo:[1,0,0] neg_hi:[1,0,0]
	v_pk_fma_f32 v[122:123], v[206:207], v[116:117], v[122:123] op_sel:[0,1,0] neg_lo:[1,0,0] neg_hi:[1,0,0]
	v_pk_fma_f32 v[122:123], v[208:209], v[118:119], v[122:123] op_sel_hi:[1,0,1] neg_lo:[1,0,0] neg_hi:[1,0,0]
	v_pk_fma_f32 v[122:123], v[210:211], v[118:119], v[122:123] op_sel:[0,1,0] neg_lo:[1,0,0] neg_hi:[1,0,0]
	ds_read_b128 v[204:207], v228 offset:6336
	ds_read_b128 v[208:211], v228 offset:6656
	s_waitcnt lgkmcnt(14)
	v_pk_fma_f32 v[122:123], v[212:213], v[120:121], v[122:123] op_sel_hi:[1,0,1] neg_lo:[1,0,0] neg_hi:[1,0,0]
	v_pk_fma_f32 v[122:123], v[214:215], v[120:121], v[122:123] op_sel:[0,1,0] neg_lo:[1,0,0] neg_hi:[1,0,0]
	v_fma_f32 v123, -v217, v122, v123
	ds_read_b128 v[212:215], v228 offset:6672
	ds_read_b128 v[216:219], v228 offset:6688
	s_waitcnt lgkmcnt(14)
	v_pk_fma_f32 v[124:125], v[220:221], v[100:101], v[124:125] op_sel_hi:[1,0,1] neg_lo:[1,0,0] neg_hi:[1,0,0]
	v_pk_fma_f32 v[124:125], v[222:223], v[100:101], v[124:125] op_sel:[0,1,0] neg_lo:[1,0,0] neg_hi:[1,0,0]
	v_pk_fma_f32 v[124:125], v[224:225], v[102:103], v[124:125] op_sel_hi:[1,0,1] neg_lo:[1,0,0] neg_hi:[1,0,0]
	v_pk_fma_f32 v[124:125], v[226:227], v[102:103], v[124:125] op_sel:[0,1,0] neg_lo:[1,0,0] neg_hi:[1,0,0]
	ds_read_b128 v[220:223], v228 offset:6704
	ds_read_b128 v[224:227], v228 offset:6720
	s_waitcnt lgkmcnt(14)
	v_pk_fma_f32 v[124:125], v[164:165], v[104:105], v[124:125] op_sel_hi:[1,0,1] neg_lo:[1,0,0] neg_hi:[1,0,0]
	v_pk_fma_f32 v[124:125], v[166:167], v[104:105], v[124:125] op_sel:[0,1,0] neg_lo:[1,0,0] neg_hi:[1,0,0]
	v_pk_fma_f32 v[124:125], v[168:169], v[106:107], v[124:125] op_sel_hi:[1,0,1] neg_lo:[1,0,0] neg_hi:[1,0,0]
	v_pk_fma_f32 v[124:125], v[170:171], v[106:107], v[124:125] op_sel:[0,1,0] neg_lo:[1,0,0] neg_hi:[1,0,0]
	ds_read_b128 v[164:167], v228 offset:6736
	ds_read_b128 v[168:171], v228 offset:6752
	s_waitcnt lgkmcnt(14)
	v_pk_fma_f32 v[124:125], v[172:173], v[108:109], v[124:125] op_sel_hi:[1,0,1] neg_lo:[1,0,0] neg_hi:[1,0,0]
	v_pk_fma_f32 v[124:125], v[174:175], v[108:109], v[124:125] op_sel:[0,1,0] neg_lo:[1,0,0] neg_hi:[1,0,0]
	v_pk_fma_f32 v[124:125], v[176:177], v[110:111], v[124:125] op_sel_hi:[1,0,1] neg_lo:[1,0,0] neg_hi:[1,0,0]
	v_pk_fma_f32 v[124:125], v[178:179], v[110:111], v[124:125] op_sel:[0,1,0] neg_lo:[1,0,0] neg_hi:[1,0,0]
	ds_read_b128 v[172:175], v228 offset:6768
	ds_read_b128 v[176:179], v228 offset:6784
	s_waitcnt lgkmcnt(14)
	v_pk_fma_f32 v[124:125], v[180:181], v[112:113], v[124:125] op_sel_hi:[1,0,1] neg_lo:[1,0,0] neg_hi:[1,0,0]
	v_pk_fma_f32 v[124:125], v[182:183], v[112:113], v[124:125] op_sel:[0,1,0] neg_lo:[1,0,0] neg_hi:[1,0,0]
	v_pk_fma_f32 v[124:125], v[184:185], v[114:115], v[124:125] op_sel_hi:[1,0,1] neg_lo:[1,0,0] neg_hi:[1,0,0]
	v_pk_fma_f32 v[124:125], v[186:187], v[114:115], v[124:125] op_sel:[0,1,0] neg_lo:[1,0,0] neg_hi:[1,0,0]
	ds_read_b128 v[180:183], v228 offset:6800
	ds_read_b128 v[184:187], v228 offset:6816
	s_waitcnt lgkmcnt(14)
	v_pk_fma_f32 v[124:125], v[188:189], v[116:117], v[124:125] op_sel_hi:[1,0,1] neg_lo:[1,0,0] neg_hi:[1,0,0]
	v_pk_fma_f32 v[124:125], v[190:191], v[116:117], v[124:125] op_sel:[0,1,0] neg_lo:[1,0,0] neg_hi:[1,0,0]
	v_pk_fma_f32 v[124:125], v[192:193], v[118:119], v[124:125] op_sel_hi:[1,0,1] neg_lo:[1,0,0] neg_hi:[1,0,0]
	v_pk_fma_f32 v[124:125], v[194:195], v[118:119], v[124:125] op_sel:[0,1,0] neg_lo:[1,0,0] neg_hi:[1,0,0]
	ds_read_b128 v[188:191], v228 offset:6832
	ds_read_b128 v[192:195], v228 offset:6848
	s_waitcnt lgkmcnt(14)
	v_pk_fma_f32 v[124:125], v[196:197], v[120:121], v[124:125] op_sel_hi:[1,0,1] neg_lo:[1,0,0] neg_hi:[1,0,0]
	v_pk_fma_f32 v[124:125], v[198:199], v[120:121], v[124:125] op_sel:[0,1,0] neg_lo:[1,0,0] neg_hi:[1,0,0]
	v_pk_fma_f32 v[124:125], v[200:201], v[122:123], v[124:125] op_sel_hi:[1,0,1] neg_lo:[1,0,0] neg_hi:[1,0,0]
	v_pk_fma_f32 v[124:125], v[202:203], v[122:123], v[124:125] op_sel:[0,1,0] neg_lo:[1,0,0] neg_hi:[1,0,0]
	ds_read_b128 v[196:199], v228 offset:6864
	ds_read_b128 v[200:203], v228 offset:7168
	s_waitcnt lgkmcnt(14)
	v_fma_f32 v125, -v205, v124, v125
	v_pk_fma_f32 v[126:127], v[208:209], v[100:101], v[126:127] op_sel_hi:[1,0,1] neg_lo:[1,0,0] neg_hi:[1,0,0]
	v_pk_fma_f32 v[126:127], v[210:211], v[100:101], v[126:127] op_sel:[0,1,0] neg_lo:[1,0,0] neg_hi:[1,0,0]
	ds_read_b128 v[204:207], v228 offset:7184
	ds_read_b128 v[208:211], v228 offset:7200
	s_waitcnt lgkmcnt(14)
	v_pk_fma_f32 v[126:127], v[212:213], v[102:103], v[126:127] op_sel_hi:[1,0,1] neg_lo:[1,0,0] neg_hi:[1,0,0]
	v_pk_fma_f32 v[126:127], v[214:215], v[102:103], v[126:127] op_sel:[0,1,0] neg_lo:[1,0,0] neg_hi:[1,0,0]
	v_pk_fma_f32 v[126:127], v[216:217], v[104:105], v[126:127] op_sel_hi:[1,0,1] neg_lo:[1,0,0] neg_hi:[1,0,0]
	v_pk_fma_f32 v[126:127], v[218:219], v[104:105], v[126:127] op_sel:[0,1,0] neg_lo:[1,0,0] neg_hi:[1,0,0]
	ds_read_b128 v[212:215], v228 offset:7216
	ds_read_b128 v[216:219], v228 offset:7232
	s_waitcnt lgkmcnt(14)
	v_pk_fma_f32 v[126:127], v[220:221], v[106:107], v[126:127] op_sel_hi:[1,0,1] neg_lo:[1,0,0] neg_hi:[1,0,0]
	v_pk_fma_f32 v[126:127], v[222:223], v[106:107], v[126:127] op_sel:[0,1,0] neg_lo:[1,0,0] neg_hi:[1,0,0]
	v_pk_fma_f32 v[126:127], v[224:225], v[108:109], v[126:127] op_sel_hi:[1,0,1] neg_lo:[1,0,0] neg_hi:[1,0,0]
	v_pk_fma_f32 v[126:127], v[226:227], v[108:109], v[126:127] op_sel:[0,1,0] neg_lo:[1,0,0] neg_hi:[1,0,0]
	ds_read_b128 v[220:223], v228 offset:7248
	ds_read_b128 v[224:227], v228 offset:7264
	s_waitcnt lgkmcnt(14)
	v_pk_fma_f32 v[126:127], v[164:165], v[110:111], v[126:127] op_sel_hi:[1,0,1] neg_lo:[1,0,0] neg_hi:[1,0,0]
	v_pk_fma_f32 v[126:127], v[166:167], v[110:111], v[126:127] op_sel:[0,1,0] neg_lo:[1,0,0] neg_hi:[1,0,0]
	v_pk_fma_f32 v[126:127], v[168:169], v[112:113], v[126:127] op_sel_hi:[1,0,1] neg_lo:[1,0,0] neg_hi:[1,0,0]
	v_pk_fma_f32 v[126:127], v[170:171], v[112:113], v[126:127] op_sel:[0,1,0] neg_lo:[1,0,0] neg_hi:[1,0,0]
	ds_read_b128 v[164:167], v228 offset:7280
	ds_read_b128 v[168:171], v228 offset:7296
	s_waitcnt lgkmcnt(14)
	v_pk_fma_f32 v[126:127], v[172:173], v[114:115], v[126:127] op_sel_hi:[1,0,1] neg_lo:[1,0,0] neg_hi:[1,0,0]
	v_pk_fma_f32 v[126:127], v[174:175], v[114:115], v[126:127] op_sel:[0,1,0] neg_lo:[1,0,0] neg_hi:[1,0,0]
	v_pk_fma_f32 v[126:127], v[176:177], v[116:117], v[126:127] op_sel_hi:[1,0,1] neg_lo:[1,0,0] neg_hi:[1,0,0]
	v_pk_fma_f32 v[126:127], v[178:179], v[116:117], v[126:127] op_sel:[0,1,0] neg_lo:[1,0,0] neg_hi:[1,0,0]
	ds_read_b128 v[172:175], v228 offset:7312
	ds_read_b128 v[176:179], v228 offset:7328
	s_waitcnt lgkmcnt(14)
	v_pk_fma_f32 v[126:127], v[180:181], v[118:119], v[126:127] op_sel_hi:[1,0,1] neg_lo:[1,0,0] neg_hi:[1,0,0]
	v_pk_fma_f32 v[126:127], v[182:183], v[118:119], v[126:127] op_sel:[0,1,0] neg_lo:[1,0,0] neg_hi:[1,0,0]
	v_pk_fma_f32 v[126:127], v[184:185], v[120:121], v[126:127] op_sel_hi:[1,0,1] neg_lo:[1,0,0] neg_hi:[1,0,0]
	v_pk_fma_f32 v[126:127], v[186:187], v[120:121], v[126:127] op_sel:[0,1,0] neg_lo:[1,0,0] neg_hi:[1,0,0]
	ds_read_b128 v[180:183], v228 offset:7344
	ds_read_b128 v[184:187], v228 offset:7360
	s_waitcnt lgkmcnt(14)
	v_pk_fma_f32 v[126:127], v[188:189], v[122:123], v[126:127] op_sel_hi:[1,0,1] neg_lo:[1,0,0] neg_hi:[1,0,0]
	v_pk_fma_f32 v[126:127], v[190:191], v[122:123], v[126:127] op_sel:[0,1,0] neg_lo:[1,0,0] neg_hi:[1,0,0]
	v_pk_fma_f32 v[126:127], v[192:193], v[124:125], v[126:127] op_sel_hi:[1,0,1] neg_lo:[1,0,0] neg_hi:[1,0,0]
	v_pk_fma_f32 v[126:127], v[194:195], v[124:125], v[126:127] op_sel:[0,1,0] neg_lo:[1,0,0] neg_hi:[1,0,0]
	ds_read_b128 v[188:191], v228 offset:7376
	ds_read_b128 v[192:195], v228 offset:7392
	s_waitcnt lgkmcnt(14)
	v_fma_f32 v127, -v197, v126, v127
	v_pk_fma_f32 v[128:129], v[200:201], v[100:101], v[128:129] op_sel_hi:[1,0,1] neg_lo:[1,0,0] neg_hi:[1,0,0]
	v_pk_fma_f32 v[128:129], v[202:203], v[100:101], v[128:129] op_sel:[0,1,0] neg_lo:[1,0,0] neg_hi:[1,0,0]
	ds_read_b128 v[196:199], v228 offset:7680
	ds_read_b128 v[200:203], v228 offset:7696
	s_waitcnt lgkmcnt(14)
	v_pk_fma_f32 v[128:129], v[204:205], v[102:103], v[128:129] op_sel_hi:[1,0,1] neg_lo:[1,0,0] neg_hi:[1,0,0]
	v_pk_fma_f32 v[128:129], v[206:207], v[102:103], v[128:129] op_sel:[0,1,0] neg_lo:[1,0,0] neg_hi:[1,0,0]
	v_pk_fma_f32 v[128:129], v[208:209], v[104:105], v[128:129] op_sel_hi:[1,0,1] neg_lo:[1,0,0] neg_hi:[1,0,0]
	v_pk_fma_f32 v[128:129], v[210:211], v[104:105], v[128:129] op_sel:[0,1,0] neg_lo:[1,0,0] neg_hi:[1,0,0]
	ds_read_b128 v[204:207], v228 offset:7712
	ds_read_b128 v[208:211], v228 offset:7728
	s_waitcnt lgkmcnt(14)
	v_pk_fma_f32 v[128:129], v[212:213], v[106:107], v[128:129] op_sel_hi:[1,0,1] neg_lo:[1,0,0] neg_hi:[1,0,0]
	v_pk_fma_f32 v[128:129], v[214:215], v[106:107], v[128:129] op_sel:[0,1,0] neg_lo:[1,0,0] neg_hi:[1,0,0]
	v_pk_fma_f32 v[128:129], v[216:217], v[108:109], v[128:129] op_sel_hi:[1,0,1] neg_lo:[1,0,0] neg_hi:[1,0,0]
	v_pk_fma_f32 v[128:129], v[218:219], v[108:109], v[128:129] op_sel:[0,1,0] neg_lo:[1,0,0] neg_hi:[1,0,0]
	ds_read_b128 v[212:215], v228 offset:7744
	ds_read_b128 v[216:219], v228 offset:7760
	s_waitcnt lgkmcnt(14)
	v_pk_fma_f32 v[128:129], v[220:221], v[110:111], v[128:129] op_sel_hi:[1,0,1] neg_lo:[1,0,0] neg_hi:[1,0,0]
	v_pk_fma_f32 v[128:129], v[222:223], v[110:111], v[128:129] op_sel:[0,1,0] neg_lo:[1,0,0] neg_hi:[1,0,0]
	v_pk_fma_f32 v[128:129], v[224:225], v[112:113], v[128:129] op_sel_hi:[1,0,1] neg_lo:[1,0,0] neg_hi:[1,0,0]
	v_pk_fma_f32 v[128:129], v[226:227], v[112:113], v[128:129] op_sel:[0,1,0] neg_lo:[1,0,0] neg_hi:[1,0,0]
	ds_read_b128 v[220:223], v228 offset:7776
	ds_read_b128 v[224:227], v228 offset:7792
	s_waitcnt lgkmcnt(14)
	v_pk_fma_f32 v[128:129], v[164:165], v[114:115], v[128:129] op_sel_hi:[1,0,1] neg_lo:[1,0,0] neg_hi:[1,0,0]
	v_pk_fma_f32 v[128:129], v[166:167], v[114:115], v[128:129] op_sel:[0,1,0] neg_lo:[1,0,0] neg_hi:[1,0,0]
	v_pk_fma_f32 v[128:129], v[168:169], v[116:117], v[128:129] op_sel_hi:[1,0,1] neg_lo:[1,0,0] neg_hi:[1,0,0]
	v_pk_fma_f32 v[128:129], v[170:171], v[116:117], v[128:129] op_sel:[0,1,0] neg_lo:[1,0,0] neg_hi:[1,0,0]
	ds_read_b128 v[164:167], v228 offset:7808
	ds_read_b128 v[168:171], v228 offset:7824
	s_waitcnt lgkmcnt(14)
	v_pk_fma_f32 v[128:129], v[172:173], v[118:119], v[128:129] op_sel_hi:[1,0,1] neg_lo:[1,0,0] neg_hi:[1,0,0]
	v_pk_fma_f32 v[128:129], v[174:175], v[118:119], v[128:129] op_sel:[0,1,0] neg_lo:[1,0,0] neg_hi:[1,0,0]
	v_pk_fma_f32 v[128:129], v[176:177], v[120:121], v[128:129] op_sel_hi:[1,0,1] neg_lo:[1,0,0] neg_hi:[1,0,0]
	v_pk_fma_f32 v[128:129], v[178:179], v[120:121], v[128:129] op_sel:[0,1,0] neg_lo:[1,0,0] neg_hi:[1,0,0]
	ds_read_b128 v[172:175], v228 offset:7840
	ds_read_b128 v[176:179], v228 offset:7856
	s_waitcnt lgkmcnt(14)
	v_pk_fma_f32 v[128:129], v[180:181], v[122:123], v[128:129] op_sel_hi:[1,0,1] neg_lo:[1,0,0] neg_hi:[1,0,0]
	v_pk_fma_f32 v[128:129], v[182:183], v[122:123], v[128:129] op_sel:[0,1,0] neg_lo:[1,0,0] neg_hi:[1,0,0]
	v_pk_fma_f32 v[128:129], v[184:185], v[124:125], v[128:129] op_sel_hi:[1,0,1] neg_lo:[1,0,0] neg_hi:[1,0,0]
	v_pk_fma_f32 v[128:129], v[186:187], v[124:125], v[128:129] op_sel:[0,1,0] neg_lo:[1,0,0] neg_hi:[1,0,0]
	ds_read_b128 v[180:183], v228 offset:7872
	ds_read_b128 v[184:187], v228 offset:7888
	s_waitcnt lgkmcnt(14)
	v_pk_fma_f32 v[128:129], v[188:189], v[126:127], v[128:129] op_sel_hi:[1,0,1] neg_lo:[1,0,0] neg_hi:[1,0,0]
	v_pk_fma_f32 v[128:129], v[190:191], v[126:127], v[128:129] op_sel:[0,1,0] neg_lo:[1,0,0] neg_hi:[1,0,0]
	v_fma_f32 v129, -v193, v128, v129
	ds_read_b128 v[188:191], v228 offset:7904
	ds_read_b128 v[192:195], v228 offset:7920
	s_waitcnt lgkmcnt(14)
	v_pk_fma_f32 v[130:131], v[196:197], v[100:101], v[130:131] op_sel_hi:[1,0,1] neg_lo:[1,0,0] neg_hi:[1,0,0]
	v_pk_fma_f32 v[130:131], v[198:199], v[100:101], v[130:131] op_sel:[0,1,0] neg_lo:[1,0,0] neg_hi:[1,0,0]
	v_pk_fma_f32 v[130:131], v[200:201], v[102:103], v[130:131] op_sel_hi:[1,0,1] neg_lo:[1,0,0] neg_hi:[1,0,0]
	v_pk_fma_f32 v[130:131], v[202:203], v[102:103], v[130:131] op_sel:[0,1,0] neg_lo:[1,0,0] neg_hi:[1,0,0]
	ds_read_b128 v[196:199], v228 offset:8192
	ds_read_b128 v[200:203], v228 offset:8208
	s_waitcnt lgkmcnt(14)
	v_pk_fma_f32 v[130:131], v[204:205], v[104:105], v[130:131] op_sel_hi:[1,0,1] neg_lo:[1,0,0] neg_hi:[1,0,0]
	v_pk_fma_f32 v[130:131], v[206:207], v[104:105], v[130:131] op_sel:[0,1,0] neg_lo:[1,0,0] neg_hi:[1,0,0]
	v_pk_fma_f32 v[130:131], v[208:209], v[106:107], v[130:131] op_sel_hi:[1,0,1] neg_lo:[1,0,0] neg_hi:[1,0,0]
	v_pk_fma_f32 v[130:131], v[210:211], v[106:107], v[130:131] op_sel:[0,1,0] neg_lo:[1,0,0] neg_hi:[1,0,0]
	ds_read_b128 v[204:207], v228 offset:8224
	ds_read_b128 v[208:211], v228 offset:8240
	s_waitcnt lgkmcnt(14)
	v_pk_fma_f32 v[130:131], v[212:213], v[108:109], v[130:131] op_sel_hi:[1,0,1] neg_lo:[1,0,0] neg_hi:[1,0,0]
	v_pk_fma_f32 v[130:131], v[214:215], v[108:109], v[130:131] op_sel:[0,1,0] neg_lo:[1,0,0] neg_hi:[1,0,0]
	v_pk_fma_f32 v[130:131], v[216:217], v[110:111], v[130:131] op_sel_hi:[1,0,1] neg_lo:[1,0,0] neg_hi:[1,0,0]
	v_pk_fma_f32 v[130:131], v[218:219], v[110:111], v[130:131] op_sel:[0,1,0] neg_lo:[1,0,0] neg_hi:[1,0,0]
	ds_read_b128 v[212:215], v228 offset:8256
	ds_read_b128 v[216:219], v228 offset:8272
	s_waitcnt lgkmcnt(14)
	v_pk_fma_f32 v[130:131], v[220:221], v[112:113], v[130:131] op_sel_hi:[1,0,1] neg_lo:[1,0,0] neg_hi:[1,0,0]
	v_pk_fma_f32 v[130:131], v[222:223], v[112:113], v[130:131] op_sel:[0,1,0] neg_lo:[1,0,0] neg_hi:[1,0,0]
	v_pk_fma_f32 v[130:131], v[224:225], v[114:115], v[130:131] op_sel_hi:[1,0,1] neg_lo:[1,0,0] neg_hi:[1,0,0]
	v_pk_fma_f32 v[130:131], v[226:227], v[114:115], v[130:131] op_sel:[0,1,0] neg_lo:[1,0,0] neg_hi:[1,0,0]
	ds_read_b128 v[220:223], v228 offset:8288
	ds_read_b128 v[224:227], v228 offset:8304
	s_waitcnt lgkmcnt(14)
	v_pk_fma_f32 v[130:131], v[164:165], v[116:117], v[130:131] op_sel_hi:[1,0,1] neg_lo:[1,0,0] neg_hi:[1,0,0]
	v_pk_fma_f32 v[130:131], v[166:167], v[116:117], v[130:131] op_sel:[0,1,0] neg_lo:[1,0,0] neg_hi:[1,0,0]
	v_pk_fma_f32 v[130:131], v[168:169], v[118:119], v[130:131] op_sel_hi:[1,0,1] neg_lo:[1,0,0] neg_hi:[1,0,0]
	v_pk_fma_f32 v[130:131], v[170:171], v[118:119], v[130:131] op_sel:[0,1,0] neg_lo:[1,0,0] neg_hi:[1,0,0]
	ds_read_b128 v[164:167], v228 offset:8320
	ds_read_b128 v[168:171], v228 offset:8336
	s_waitcnt lgkmcnt(14)
	v_pk_fma_f32 v[130:131], v[172:173], v[120:121], v[130:131] op_sel_hi:[1,0,1] neg_lo:[1,0,0] neg_hi:[1,0,0]
	v_pk_fma_f32 v[130:131], v[174:175], v[120:121], v[130:131] op_sel:[0,1,0] neg_lo:[1,0,0] neg_hi:[1,0,0]
	v_pk_fma_f32 v[130:131], v[176:177], v[122:123], v[130:131] op_sel_hi:[1,0,1] neg_lo:[1,0,0] neg_hi:[1,0,0]
	v_pk_fma_f32 v[130:131], v[178:179], v[122:123], v[130:131] op_sel:[0,1,0] neg_lo:[1,0,0] neg_hi:[1,0,0]
	ds_read_b128 v[172:175], v228 offset:8352
	ds_read_b128 v[176:179], v228 offset:8368
	s_waitcnt lgkmcnt(14)
	v_pk_fma_f32 v[130:131], v[180:181], v[124:125], v[130:131] op_sel_hi:[1,0,1] neg_lo:[1,0,0] neg_hi:[1,0,0]
	v_pk_fma_f32 v[130:131], v[182:183], v[124:125], v[130:131] op_sel:[0,1,0] neg_lo:[1,0,0] neg_hi:[1,0,0]
	v_pk_fma_f32 v[130:131], v[184:185], v[126:127], v[130:131] op_sel_hi:[1,0,1] neg_lo:[1,0,0] neg_hi:[1,0,0]
	v_pk_fma_f32 v[130:131], v[186:187], v[126:127], v[130:131] op_sel:[0,1,0] neg_lo:[1,0,0] neg_hi:[1,0,0]
	ds_read_b128 v[180:183], v228 offset:8384
	ds_read_b128 v[184:187], v228 offset:8400
	s_waitcnt lgkmcnt(14)
	v_pk_fma_f32 v[130:131], v[188:189], v[128:129], v[130:131] op_sel_hi:[1,0,1] neg_lo:[1,0,0] neg_hi:[1,0,0]
	v_pk_fma_f32 v[130:131], v[190:191], v[128:129], v[130:131] op_sel:[0,1,0] neg_lo:[1,0,0] neg_hi:[1,0,0]
	v_fma_f32 v131, -v193, v130, v131
	ds_read_b128 v[188:191], v228 offset:8416
	ds_read_b128 v[192:195], v228 offset:8432
	s_waitcnt lgkmcnt(14)
	v_pk_fma_f32 v[132:133], v[196:197], v[100:101], v[132:133] op_sel_hi:[1,0,1] neg_lo:[1,0,0] neg_hi:[1,0,0]
	v_pk_fma_f32 v[132:133], v[198:199], v[100:101], v[132:133] op_sel:[0,1,0] neg_lo:[1,0,0] neg_hi:[1,0,0]
	v_pk_fma_f32 v[132:133], v[200:201], v[102:103], v[132:133] op_sel_hi:[1,0,1] neg_lo:[1,0,0] neg_hi:[1,0,0]
	v_pk_fma_f32 v[132:133], v[202:203], v[102:103], v[132:133] op_sel:[0,1,0] neg_lo:[1,0,0] neg_hi:[1,0,0]
	ds_read_b128 v[196:199], v228 offset:8448
	ds_read_b128 v[200:203], v228 offset:8704
	s_waitcnt lgkmcnt(14)
	v_pk_fma_f32 v[132:133], v[204:205], v[104:105], v[132:133] op_sel_hi:[1,0,1] neg_lo:[1,0,0] neg_hi:[1,0,0]
	v_pk_fma_f32 v[132:133], v[206:207], v[104:105], v[132:133] op_sel:[0,1,0] neg_lo:[1,0,0] neg_hi:[1,0,0]
	v_pk_fma_f32 v[132:133], v[208:209], v[106:107], v[132:133] op_sel_hi:[1,0,1] neg_lo:[1,0,0] neg_hi:[1,0,0]
	v_pk_fma_f32 v[132:133], v[210:211], v[106:107], v[132:133] op_sel:[0,1,0] neg_lo:[1,0,0] neg_hi:[1,0,0]
	ds_read_b128 v[204:207], v228 offset:8720
	ds_read_b128 v[208:211], v228 offset:8736
	s_waitcnt lgkmcnt(14)
	v_pk_fma_f32 v[132:133], v[212:213], v[108:109], v[132:133] op_sel_hi:[1,0,1] neg_lo:[1,0,0] neg_hi:[1,0,0]
	v_pk_fma_f32 v[132:133], v[214:215], v[108:109], v[132:133] op_sel:[0,1,0] neg_lo:[1,0,0] neg_hi:[1,0,0]
	v_pk_fma_f32 v[132:133], v[216:217], v[110:111], v[132:133] op_sel_hi:[1,0,1] neg_lo:[1,0,0] neg_hi:[1,0,0]
	v_pk_fma_f32 v[132:133], v[218:219], v[110:111], v[132:133] op_sel:[0,1,0] neg_lo:[1,0,0] neg_hi:[1,0,0]
	ds_read_b128 v[212:215], v228 offset:8752
	ds_read_b128 v[216:219], v228 offset:8768
	s_waitcnt lgkmcnt(14)
	v_pk_fma_f32 v[132:133], v[220:221], v[112:113], v[132:133] op_sel_hi:[1,0,1] neg_lo:[1,0,0] neg_hi:[1,0,0]
	v_pk_fma_f32 v[132:133], v[222:223], v[112:113], v[132:133] op_sel:[0,1,0] neg_lo:[1,0,0] neg_hi:[1,0,0]
	v_pk_fma_f32 v[132:133], v[224:225], v[114:115], v[132:133] op_sel_hi:[1,0,1] neg_lo:[1,0,0] neg_hi:[1,0,0]
	v_pk_fma_f32 v[132:133], v[226:227], v[114:115], v[132:133] op_sel:[0,1,0] neg_lo:[1,0,0] neg_hi:[1,0,0]
	ds_read_b128 v[220:223], v228 offset:8784
	ds_read_b128 v[224:227], v228 offset:8800
	s_waitcnt lgkmcnt(14)
	v_pk_fma_f32 v[132:133], v[164:165], v[116:117], v[132:133] op_sel_hi:[1,0,1] neg_lo:[1,0,0] neg_hi:[1,0,0]
	v_pk_fma_f32 v[132:133], v[166:167], v[116:117], v[132:133] op_sel:[0,1,0] neg_lo:[1,0,0] neg_hi:[1,0,0]
	v_pk_fma_f32 v[132:133], v[168:169], v[118:119], v[132:133] op_sel_hi:[1,0,1] neg_lo:[1,0,0] neg_hi:[1,0,0]
	v_pk_fma_f32 v[132:133], v[170:171], v[118:119], v[132:133] op_sel:[0,1,0] neg_lo:[1,0,0] neg_hi:[1,0,0]
	ds_read_b128 v[164:167], v228 offset:8816
	ds_read_b128 v[168:171], v228 offset:8832
	s_waitcnt lgkmcnt(14)
	v_pk_fma_f32 v[132:133], v[172:173], v[120:121], v[132:133] op_sel_hi:[1,0,1] neg_lo:[1,0,0] neg_hi:[1,0,0]
	v_pk_fma_f32 v[132:133], v[174:175], v[120:121], v[132:133] op_sel:[0,1,0] neg_lo:[1,0,0] neg_hi:[1,0,0]
	v_pk_fma_f32 v[132:133], v[176:177], v[122:123], v[132:133] op_sel_hi:[1,0,1] neg_lo:[1,0,0] neg_hi:[1,0,0]
	v_pk_fma_f32 v[132:133], v[178:179], v[122:123], v[132:133] op_sel:[0,1,0] neg_lo:[1,0,0] neg_hi:[1,0,0]
	ds_read_b128 v[172:175], v228 offset:8848
	ds_read_b128 v[176:179], v228 offset:8864
	s_waitcnt lgkmcnt(14)
	v_pk_fma_f32 v[132:133], v[180:181], v[124:125], v[132:133] op_sel_hi:[1,0,1] neg_lo:[1,0,0] neg_hi:[1,0,0]
	v_pk_fma_f32 v[132:133], v[182:183], v[124:125], v[132:133] op_sel:[0,1,0] neg_lo:[1,0,0] neg_hi:[1,0,0]
	v_pk_fma_f32 v[132:133], v[184:185], v[126:127], v[132:133] op_sel_hi:[1,0,1] neg_lo:[1,0,0] neg_hi:[1,0,0]
	v_pk_fma_f32 v[132:133], v[186:187], v[126:127], v[132:133] op_sel:[0,1,0] neg_lo:[1,0,0] neg_hi:[1,0,0]
	ds_read_b128 v[180:183], v228 offset:8880
	ds_read_b128 v[184:187], v228 offset:8896
	s_waitcnt lgkmcnt(14)
	v_pk_fma_f32 v[132:133], v[188:189], v[128:129], v[132:133] op_sel_hi:[1,0,1] neg_lo:[1,0,0] neg_hi:[1,0,0]
	v_pk_fma_f32 v[132:133], v[190:191], v[128:129], v[132:133] op_sel:[0,1,0] neg_lo:[1,0,0] neg_hi:[1,0,0]
	v_pk_fma_f32 v[132:133], v[192:193], v[130:131], v[132:133] op_sel_hi:[1,0,1] neg_lo:[1,0,0] neg_hi:[1,0,0]
	v_pk_fma_f32 v[132:133], v[194:195], v[130:131], v[132:133] op_sel:[0,1,0] neg_lo:[1,0,0] neg_hi:[1,0,0]
	ds_read_b128 v[188:191], v228 offset:8912
	ds_read_b128 v[192:195], v228 offset:8928
	s_waitcnt lgkmcnt(14)
	v_fma_f32 v133, -v197, v132, v133
	v_pk_fma_f32 v[134:135], v[200:201], v[100:101], v[134:135] op_sel_hi:[1,0,1] neg_lo:[1,0,0] neg_hi:[1,0,0]
	v_pk_fma_f32 v[134:135], v[202:203], v[100:101], v[134:135] op_sel:[0,1,0] neg_lo:[1,0,0] neg_hi:[1,0,0]
	ds_read_b128 v[196:199], v228 offset:8944
	ds_read_b128 v[200:203], v228 offset:8960
	s_waitcnt lgkmcnt(14)
	v_pk_fma_f32 v[134:135], v[204:205], v[102:103], v[134:135] op_sel_hi:[1,0,1] neg_lo:[1,0,0] neg_hi:[1,0,0]
	v_pk_fma_f32 v[134:135], v[206:207], v[102:103], v[134:135] op_sel:[0,1,0] neg_lo:[1,0,0] neg_hi:[1,0,0]
	v_pk_fma_f32 v[134:135], v[208:209], v[104:105], v[134:135] op_sel_hi:[1,0,1] neg_lo:[1,0,0] neg_hi:[1,0,0]
	v_pk_fma_f32 v[134:135], v[210:211], v[104:105], v[134:135] op_sel:[0,1,0] neg_lo:[1,0,0] neg_hi:[1,0,0]
	ds_read_b128 v[204:207], v228 offset:8976
	ds_read_b128 v[208:211], v228 offset:9216
	s_waitcnt lgkmcnt(14)
	v_pk_fma_f32 v[134:135], v[212:213], v[106:107], v[134:135] op_sel_hi:[1,0,1] neg_lo:[1,0,0] neg_hi:[1,0,0]
	v_pk_fma_f32 v[134:135], v[214:215], v[106:107], v[134:135] op_sel:[0,1,0] neg_lo:[1,0,0] neg_hi:[1,0,0]
	v_pk_fma_f32 v[134:135], v[216:217], v[108:109], v[134:135] op_sel_hi:[1,0,1] neg_lo:[1,0,0] neg_hi:[1,0,0]
	v_pk_fma_f32 v[134:135], v[218:219], v[108:109], v[134:135] op_sel:[0,1,0] neg_lo:[1,0,0] neg_hi:[1,0,0]
	ds_read_b128 v[212:215], v228 offset:9232
	ds_read_b128 v[216:219], v228 offset:9248
	s_waitcnt lgkmcnt(14)
	v_pk_fma_f32 v[134:135], v[220:221], v[110:111], v[134:135] op_sel_hi:[1,0,1] neg_lo:[1,0,0] neg_hi:[1,0,0]
	v_pk_fma_f32 v[134:135], v[222:223], v[110:111], v[134:135] op_sel:[0,1,0] neg_lo:[1,0,0] neg_hi:[1,0,0]
	v_pk_fma_f32 v[134:135], v[224:225], v[112:113], v[134:135] op_sel_hi:[1,0,1] neg_lo:[1,0,0] neg_hi:[1,0,0]
	v_pk_fma_f32 v[134:135], v[226:227], v[112:113], v[134:135] op_sel:[0,1,0] neg_lo:[1,0,0] neg_hi:[1,0,0]
	ds_read_b128 v[220:223], v228 offset:9264
	ds_read_b128 v[224:227], v228 offset:9280
	s_waitcnt lgkmcnt(14)
	v_pk_fma_f32 v[134:135], v[164:165], v[114:115], v[134:135] op_sel_hi:[1,0,1] neg_lo:[1,0,0] neg_hi:[1,0,0]
	v_pk_fma_f32 v[134:135], v[166:167], v[114:115], v[134:135] op_sel:[0,1,0] neg_lo:[1,0,0] neg_hi:[1,0,0]
	v_pk_fma_f32 v[134:135], v[168:169], v[116:117], v[134:135] op_sel_hi:[1,0,1] neg_lo:[1,0,0] neg_hi:[1,0,0]
	v_pk_fma_f32 v[134:135], v[170:171], v[116:117], v[134:135] op_sel:[0,1,0] neg_lo:[1,0,0] neg_hi:[1,0,0]
	ds_read_b128 v[164:167], v228 offset:9296
	ds_read_b128 v[168:171], v228 offset:9312
	s_waitcnt lgkmcnt(14)
	v_pk_fma_f32 v[134:135], v[172:173], v[118:119], v[134:135] op_sel_hi:[1,0,1] neg_lo:[1,0,0] neg_hi:[1,0,0]
	v_pk_fma_f32 v[134:135], v[174:175], v[118:119], v[134:135] op_sel:[0,1,0] neg_lo:[1,0,0] neg_hi:[1,0,0]
	v_pk_fma_f32 v[134:135], v[176:177], v[120:121], v[134:135] op_sel_hi:[1,0,1] neg_lo:[1,0,0] neg_hi:[1,0,0]
	v_pk_fma_f32 v[134:135], v[178:179], v[120:121], v[134:135] op_sel:[0,1,0] neg_lo:[1,0,0] neg_hi:[1,0,0]
	ds_read_b128 v[172:175], v228 offset:9328
	ds_read_b128 v[176:179], v228 offset:9344
	s_waitcnt lgkmcnt(14)
	v_pk_fma_f32 v[134:135], v[180:181], v[122:123], v[134:135] op_sel_hi:[1,0,1] neg_lo:[1,0,0] neg_hi:[1,0,0]
	v_pk_fma_f32 v[134:135], v[182:183], v[122:123], v[134:135] op_sel:[0,1,0] neg_lo:[1,0,0] neg_hi:[1,0,0]
	v_pk_fma_f32 v[134:135], v[184:185], v[124:125], v[134:135] op_sel_hi:[1,0,1] neg_lo:[1,0,0] neg_hi:[1,0,0]
	v_pk_fma_f32 v[134:135], v[186:187], v[124:125], v[134:135] op_sel:[0,1,0] neg_lo:[1,0,0] neg_hi:[1,0,0]
	ds_read_b128 v[180:183], v228 offset:9360
	ds_read_b128 v[184:187], v228 offset:9376
	s_waitcnt lgkmcnt(14)
	v_pk_fma_f32 v[134:135], v[188:189], v[126:127], v[134:135] op_sel_hi:[1,0,1] neg_lo:[1,0,0] neg_hi:[1,0,0]
	v_pk_fma_f32 v[134:135], v[190:191], v[126:127], v[134:135] op_sel:[0,1,0] neg_lo:[1,0,0] neg_hi:[1,0,0]
	v_pk_fma_f32 v[134:135], v[192:193], v[128:129], v[134:135] op_sel_hi:[1,0,1] neg_lo:[1,0,0] neg_hi:[1,0,0]
	v_pk_fma_f32 v[134:135], v[194:195], v[128:129], v[134:135] op_sel:[0,1,0] neg_lo:[1,0,0] neg_hi:[1,0,0]
	ds_read_b128 v[188:191], v228 offset:9392
	ds_read_b128 v[192:195], v228 offset:9408
	s_waitcnt lgkmcnt(14)
	v_pk_fma_f32 v[134:135], v[196:197], v[130:131], v[134:135] op_sel_hi:[1,0,1] neg_lo:[1,0,0] neg_hi:[1,0,0]
	v_pk_fma_f32 v[134:135], v[198:199], v[130:131], v[134:135] op_sel:[0,1,0] neg_lo:[1,0,0] neg_hi:[1,0,0]
	v_pk_fma_f32 v[134:135], v[200:201], v[132:133], v[134:135] op_sel_hi:[1,0,1] neg_lo:[1,0,0] neg_hi:[1,0,0]
	v_pk_fma_f32 v[134:135], v[202:203], v[132:133], v[134:135] op_sel:[0,1,0] neg_lo:[1,0,0] neg_hi:[1,0,0]
	ds_read_b128 v[196:199], v228 offset:9424
	ds_read_b128 v[200:203], v228 offset:9440
	s_waitcnt lgkmcnt(14)
	v_fma_f32 v135, -v205, v134, v135
	v_pk_fma_f32 v[136:137], v[208:209], v[100:101], v[136:137] op_sel_hi:[1,0,1] neg_lo:[1,0,0] neg_hi:[1,0,0]
	v_pk_fma_f32 v[136:137], v[210:211], v[100:101], v[136:137] op_sel:[0,1,0] neg_lo:[1,0,0] neg_hi:[1,0,0]
	ds_read_b128 v[204:207], v228 offset:9456
	ds_read_b128 v[208:211], v228 offset:9472
	s_waitcnt lgkmcnt(14)
	v_pk_fma_f32 v[136:137], v[212:213], v[102:103], v[136:137] op_sel_hi:[1,0,1] neg_lo:[1,0,0] neg_hi:[1,0,0]
	v_pk_fma_f32 v[136:137], v[214:215], v[102:103], v[136:137] op_sel:[0,1,0] neg_lo:[1,0,0] neg_hi:[1,0,0]
	v_pk_fma_f32 v[136:137], v[216:217], v[104:105], v[136:137] op_sel_hi:[1,0,1] neg_lo:[1,0,0] neg_hi:[1,0,0]
	v_pk_fma_f32 v[136:137], v[218:219], v[104:105], v[136:137] op_sel:[0,1,0] neg_lo:[1,0,0] neg_hi:[1,0,0]
	ds_read_b128 v[212:215], v228 offset:9488
	ds_read_b128 v[216:219], v228 offset:9504
	s_waitcnt lgkmcnt(14)
	v_pk_fma_f32 v[136:137], v[220:221], v[106:107], v[136:137] op_sel_hi:[1,0,1] neg_lo:[1,0,0] neg_hi:[1,0,0]
	v_pk_fma_f32 v[136:137], v[222:223], v[106:107], v[136:137] op_sel:[0,1,0] neg_lo:[1,0,0] neg_hi:[1,0,0]
	v_pk_fma_f32 v[136:137], v[224:225], v[108:109], v[136:137] op_sel_hi:[1,0,1] neg_lo:[1,0,0] neg_hi:[1,0,0]
	v_pk_fma_f32 v[136:137], v[226:227], v[108:109], v[136:137] op_sel:[0,1,0] neg_lo:[1,0,0] neg_hi:[1,0,0]
	ds_read_b128 v[220:223], v228 offset:9728
	ds_read_b128 v[224:227], v228 offset:9744
	s_waitcnt lgkmcnt(14)
	v_pk_fma_f32 v[136:137], v[164:165], v[110:111], v[136:137] op_sel_hi:[1,0,1] neg_lo:[1,0,0] neg_hi:[1,0,0]
	v_pk_fma_f32 v[136:137], v[166:167], v[110:111], v[136:137] op_sel:[0,1,0] neg_lo:[1,0,0] neg_hi:[1,0,0]
	v_pk_fma_f32 v[136:137], v[168:169], v[112:113], v[136:137] op_sel_hi:[1,0,1] neg_lo:[1,0,0] neg_hi:[1,0,0]
	v_pk_fma_f32 v[136:137], v[170:171], v[112:113], v[136:137] op_sel:[0,1,0] neg_lo:[1,0,0] neg_hi:[1,0,0]
	ds_read_b128 v[164:167], v228 offset:9760
	ds_read_b128 v[168:171], v228 offset:9776
	s_waitcnt lgkmcnt(14)
	v_pk_fma_f32 v[136:137], v[172:173], v[114:115], v[136:137] op_sel_hi:[1,0,1] neg_lo:[1,0,0] neg_hi:[1,0,0]
	v_pk_fma_f32 v[136:137], v[174:175], v[114:115], v[136:137] op_sel:[0,1,0] neg_lo:[1,0,0] neg_hi:[1,0,0]
	v_pk_fma_f32 v[136:137], v[176:177], v[116:117], v[136:137] op_sel_hi:[1,0,1] neg_lo:[1,0,0] neg_hi:[1,0,0]
	v_pk_fma_f32 v[136:137], v[178:179], v[116:117], v[136:137] op_sel:[0,1,0] neg_lo:[1,0,0] neg_hi:[1,0,0]
	ds_read_b128 v[172:175], v228 offset:9792
	ds_read_b128 v[176:179], v228 offset:9808
	s_waitcnt lgkmcnt(14)
	v_pk_fma_f32 v[136:137], v[180:181], v[118:119], v[136:137] op_sel_hi:[1,0,1] neg_lo:[1,0,0] neg_hi:[1,0,0]
	v_pk_fma_f32 v[136:137], v[182:183], v[118:119], v[136:137] op_sel:[0,1,0] neg_lo:[1,0,0] neg_hi:[1,0,0]
	v_pk_fma_f32 v[136:137], v[184:185], v[120:121], v[136:137] op_sel_hi:[1,0,1] neg_lo:[1,0,0] neg_hi:[1,0,0]
	v_pk_fma_f32 v[136:137], v[186:187], v[120:121], v[136:137] op_sel:[0,1,0] neg_lo:[1,0,0] neg_hi:[1,0,0]
	ds_read_b128 v[180:183], v228 offset:9824
	ds_read_b128 v[184:187], v228 offset:9840
	s_waitcnt lgkmcnt(14)
	v_pk_fma_f32 v[136:137], v[188:189], v[122:123], v[136:137] op_sel_hi:[1,0,1] neg_lo:[1,0,0] neg_hi:[1,0,0]
	v_pk_fma_f32 v[136:137], v[190:191], v[122:123], v[136:137] op_sel:[0,1,0] neg_lo:[1,0,0] neg_hi:[1,0,0]
	v_pk_fma_f32 v[136:137], v[192:193], v[124:125], v[136:137] op_sel_hi:[1,0,1] neg_lo:[1,0,0] neg_hi:[1,0,0]
	v_pk_fma_f32 v[136:137], v[194:195], v[124:125], v[136:137] op_sel:[0,1,0] neg_lo:[1,0,0] neg_hi:[1,0,0]
	ds_read_b128 v[188:191], v228 offset:9856
	ds_read_b128 v[192:195], v228 offset:9872
	s_waitcnt lgkmcnt(14)
	v_pk_fma_f32 v[136:137], v[196:197], v[126:127], v[136:137] op_sel_hi:[1,0,1] neg_lo:[1,0,0] neg_hi:[1,0,0]
	v_pk_fma_f32 v[136:137], v[198:199], v[126:127], v[136:137] op_sel:[0,1,0] neg_lo:[1,0,0] neg_hi:[1,0,0]
	v_pk_fma_f32 v[136:137], v[200:201], v[128:129], v[136:137] op_sel_hi:[1,0,1] neg_lo:[1,0,0] neg_hi:[1,0,0]
	v_pk_fma_f32 v[136:137], v[202:203], v[128:129], v[136:137] op_sel:[0,1,0] neg_lo:[1,0,0] neg_hi:[1,0,0]
	ds_read_b128 v[196:199], v228 offset:9888
	ds_read_b128 v[200:203], v228 offset:9904
	s_waitcnt lgkmcnt(14)
	v_pk_fma_f32 v[136:137], v[204:205], v[130:131], v[136:137] op_sel_hi:[1,0,1] neg_lo:[1,0,0] neg_hi:[1,0,0]
	v_pk_fma_f32 v[136:137], v[206:207], v[130:131], v[136:137] op_sel:[0,1,0] neg_lo:[1,0,0] neg_hi:[1,0,0]
	v_pk_fma_f32 v[136:137], v[208:209], v[132:133], v[136:137] op_sel_hi:[1,0,1] neg_lo:[1,0,0] neg_hi:[1,0,0]
	v_pk_fma_f32 v[136:137], v[210:211], v[132:133], v[136:137] op_sel:[0,1,0] neg_lo:[1,0,0] neg_hi:[1,0,0]
	ds_read_b128 v[204:207], v228 offset:9920
	ds_read_b128 v[208:211], v228 offset:9936
	s_waitcnt lgkmcnt(14)
	v_pk_fma_f32 v[136:137], v[212:213], v[134:135], v[136:137] op_sel_hi:[1,0,1] neg_lo:[1,0,0] neg_hi:[1,0,0]
	v_pk_fma_f32 v[136:137], v[214:215], v[134:135], v[136:137] op_sel:[0,1,0] neg_lo:[1,0,0] neg_hi:[1,0,0]
	v_fma_f32 v137, -v217, v136, v137
	ds_read_b128 v[212:215], v228 offset:9952
	ds_read_b128 v[216:219], v228 offset:9968
	s_waitcnt lgkmcnt(14)
	v_pk_fma_f32 v[138:139], v[220:221], v[100:101], v[138:139] op_sel_hi:[1,0,1] neg_lo:[1,0,0] neg_hi:[1,0,0]
	v_pk_fma_f32 v[138:139], v[222:223], v[100:101], v[138:139] op_sel:[0,1,0] neg_lo:[1,0,0] neg_hi:[1,0,0]
	v_pk_fma_f32 v[138:139], v[224:225], v[102:103], v[138:139] op_sel_hi:[1,0,1] neg_lo:[1,0,0] neg_hi:[1,0,0]
	v_pk_fma_f32 v[138:139], v[226:227], v[102:103], v[138:139] op_sel:[0,1,0] neg_lo:[1,0,0] neg_hi:[1,0,0]
	ds_read_b128 v[220:223], v228 offset:9984
	ds_read_b128 v[224:227], v228 offset:10000
	s_waitcnt lgkmcnt(14)
	v_pk_fma_f32 v[138:139], v[164:165], v[104:105], v[138:139] op_sel_hi:[1,0,1] neg_lo:[1,0,0] neg_hi:[1,0,0]
	v_pk_fma_f32 v[138:139], v[166:167], v[104:105], v[138:139] op_sel:[0,1,0] neg_lo:[1,0,0] neg_hi:[1,0,0]
	v_pk_fma_f32 v[138:139], v[168:169], v[106:107], v[138:139] op_sel_hi:[1,0,1] neg_lo:[1,0,0] neg_hi:[1,0,0]
	v_pk_fma_f32 v[138:139], v[170:171], v[106:107], v[138:139] op_sel:[0,1,0] neg_lo:[1,0,0] neg_hi:[1,0,0]
	ds_read_b128 v[164:167], v228 offset:10016
	ds_read_b128 v[168:171], v228 offset:10032
	s_waitcnt lgkmcnt(14)
	v_pk_fma_f32 v[138:139], v[172:173], v[108:109], v[138:139] op_sel_hi:[1,0,1] neg_lo:[1,0,0] neg_hi:[1,0,0]
	v_pk_fma_f32 v[138:139], v[174:175], v[108:109], v[138:139] op_sel:[0,1,0] neg_lo:[1,0,0] neg_hi:[1,0,0]
	v_pk_fma_f32 v[138:139], v[176:177], v[110:111], v[138:139] op_sel_hi:[1,0,1] neg_lo:[1,0,0] neg_hi:[1,0,0]
	v_pk_fma_f32 v[138:139], v[178:179], v[110:111], v[138:139] op_sel:[0,1,0] neg_lo:[1,0,0] neg_hi:[1,0,0]
	ds_read_b128 v[172:175], v228 offset:10240
	ds_read_b128 v[176:179], v228 offset:10256
	s_waitcnt lgkmcnt(14)
	v_pk_fma_f32 v[138:139], v[180:181], v[112:113], v[138:139] op_sel_hi:[1,0,1] neg_lo:[1,0,0] neg_hi:[1,0,0]
	v_pk_fma_f32 v[138:139], v[182:183], v[112:113], v[138:139] op_sel:[0,1,0] neg_lo:[1,0,0] neg_hi:[1,0,0]
	v_pk_fma_f32 v[138:139], v[184:185], v[114:115], v[138:139] op_sel_hi:[1,0,1] neg_lo:[1,0,0] neg_hi:[1,0,0]
	v_pk_fma_f32 v[138:139], v[186:187], v[114:115], v[138:139] op_sel:[0,1,0] neg_lo:[1,0,0] neg_hi:[1,0,0]
	ds_read_b128 v[180:183], v228 offset:10272
	ds_read_b128 v[184:187], v228 offset:10288
	s_waitcnt lgkmcnt(14)
	v_pk_fma_f32 v[138:139], v[188:189], v[116:117], v[138:139] op_sel_hi:[1,0,1] neg_lo:[1,0,0] neg_hi:[1,0,0]
	v_pk_fma_f32 v[138:139], v[190:191], v[116:117], v[138:139] op_sel:[0,1,0] neg_lo:[1,0,0] neg_hi:[1,0,0]
	v_pk_fma_f32 v[138:139], v[192:193], v[118:119], v[138:139] op_sel_hi:[1,0,1] neg_lo:[1,0,0] neg_hi:[1,0,0]
	v_pk_fma_f32 v[138:139], v[194:195], v[118:119], v[138:139] op_sel:[0,1,0] neg_lo:[1,0,0] neg_hi:[1,0,0]
	ds_read_b128 v[188:191], v228 offset:10304
	ds_read_b128 v[192:195], v228 offset:10320
	s_waitcnt lgkmcnt(14)
	v_pk_fma_f32 v[138:139], v[196:197], v[120:121], v[138:139] op_sel_hi:[1,0,1] neg_lo:[1,0,0] neg_hi:[1,0,0]
	v_pk_fma_f32 v[138:139], v[198:199], v[120:121], v[138:139] op_sel:[0,1,0] neg_lo:[1,0,0] neg_hi:[1,0,0]
	v_pk_fma_f32 v[138:139], v[200:201], v[122:123], v[138:139] op_sel_hi:[1,0,1] neg_lo:[1,0,0] neg_hi:[1,0,0]
	v_pk_fma_f32 v[138:139], v[202:203], v[122:123], v[138:139] op_sel:[0,1,0] neg_lo:[1,0,0] neg_hi:[1,0,0]
	ds_read_b128 v[196:199], v228 offset:10336
	ds_read_b128 v[200:203], v228 offset:10352
	s_waitcnt lgkmcnt(14)
	v_pk_fma_f32 v[138:139], v[204:205], v[124:125], v[138:139] op_sel_hi:[1,0,1] neg_lo:[1,0,0] neg_hi:[1,0,0]
	v_pk_fma_f32 v[138:139], v[206:207], v[124:125], v[138:139] op_sel:[0,1,0] neg_lo:[1,0,0] neg_hi:[1,0,0]
	v_pk_fma_f32 v[138:139], v[208:209], v[126:127], v[138:139] op_sel_hi:[1,0,1] neg_lo:[1,0,0] neg_hi:[1,0,0]
	v_pk_fma_f32 v[138:139], v[210:211], v[126:127], v[138:139] op_sel:[0,1,0] neg_lo:[1,0,0] neg_hi:[1,0,0]
	ds_read_b128 v[204:207], v228 offset:10368
	ds_read_b128 v[208:211], v228 offset:10384
	s_waitcnt lgkmcnt(14)
	v_pk_fma_f32 v[138:139], v[212:213], v[128:129], v[138:139] op_sel_hi:[1,0,1] neg_lo:[1,0,0] neg_hi:[1,0,0]
	v_pk_fma_f32 v[138:139], v[214:215], v[128:129], v[138:139] op_sel:[0,1,0] neg_lo:[1,0,0] neg_hi:[1,0,0]
	v_pk_fma_f32 v[138:139], v[216:217], v[130:131], v[138:139] op_sel_hi:[1,0,1] neg_lo:[1,0,0] neg_hi:[1,0,0]
	v_pk_fma_f32 v[138:139], v[218:219], v[130:131], v[138:139] op_sel:[0,1,0] neg_lo:[1,0,0] neg_hi:[1,0,0]
	ds_read_b128 v[212:215], v228 offset:10400
	ds_read_b128 v[216:219], v228 offset:10416
	s_waitcnt lgkmcnt(14)
	v_pk_fma_f32 v[138:139], v[220:221], v[132:133], v[138:139] op_sel_hi:[1,0,1] neg_lo:[1,0,0] neg_hi:[1,0,0]
	v_pk_fma_f32 v[138:139], v[222:223], v[132:133], v[138:139] op_sel:[0,1,0] neg_lo:[1,0,0] neg_hi:[1,0,0]
	v_pk_fma_f32 v[138:139], v[224:225], v[134:135], v[138:139] op_sel_hi:[1,0,1] neg_lo:[1,0,0] neg_hi:[1,0,0]
	v_pk_fma_f32 v[138:139], v[226:227], v[134:135], v[138:139] op_sel:[0,1,0] neg_lo:[1,0,0] neg_hi:[1,0,0]
	ds_read_b128 v[220:223], v228 offset:10432
	ds_read_b128 v[224:227], v228 offset:10448
	s_waitcnt lgkmcnt(14)
	v_pk_fma_f32 v[138:139], v[164:165], v[136:137], v[138:139] op_sel_hi:[1,0,1] neg_lo:[1,0,0] neg_hi:[1,0,0]
	v_pk_fma_f32 v[138:139], v[166:167], v[136:137], v[138:139] op_sel:[0,1,0] neg_lo:[1,0,0] neg_hi:[1,0,0]
	v_fma_f32 v139, -v169, v138, v139
	ds_read_b128 v[164:167], v228 offset:10464
	ds_read_b128 v[168:171], v228 offset:10480
	s_waitcnt lgkmcnt(14)
	v_pk_fma_f32 v[140:141], v[172:173], v[100:101], v[140:141] op_sel_hi:[1,0,1] neg_lo:[1,0,0] neg_hi:[1,0,0]
	v_pk_fma_f32 v[140:141], v[174:175], v[100:101], v[140:141] op_sel:[0,1,0] neg_lo:[1,0,0] neg_hi:[1,0,0]
	v_pk_fma_f32 v[140:141], v[176:177], v[102:103], v[140:141] op_sel_hi:[1,0,1] neg_lo:[1,0,0] neg_hi:[1,0,0]
	v_pk_fma_f32 v[140:141], v[178:179], v[102:103], v[140:141] op_sel:[0,1,0] neg_lo:[1,0,0] neg_hi:[1,0,0]
	ds_read_b128 v[172:175], v228 offset:10496
	ds_read_b128 v[176:179], v228 offset:10512
	s_waitcnt lgkmcnt(14)
	v_pk_fma_f32 v[140:141], v[180:181], v[104:105], v[140:141] op_sel_hi:[1,0,1] neg_lo:[1,0,0] neg_hi:[1,0,0]
	v_pk_fma_f32 v[140:141], v[182:183], v[104:105], v[140:141] op_sel:[0,1,0] neg_lo:[1,0,0] neg_hi:[1,0,0]
	v_pk_fma_f32 v[140:141], v[184:185], v[106:107], v[140:141] op_sel_hi:[1,0,1] neg_lo:[1,0,0] neg_hi:[1,0,0]
	v_pk_fma_f32 v[140:141], v[186:187], v[106:107], v[140:141] op_sel:[0,1,0] neg_lo:[1,0,0] neg_hi:[1,0,0]
	ds_read_b128 v[180:183], v228 offset:10528
	ds_read_b128 v[184:187], v228 offset:10544
	s_waitcnt lgkmcnt(14)
	v_pk_fma_f32 v[140:141], v[188:189], v[108:109], v[140:141] op_sel_hi:[1,0,1] neg_lo:[1,0,0] neg_hi:[1,0,0]
	v_pk_fma_f32 v[140:141], v[190:191], v[108:109], v[140:141] op_sel:[0,1,0] neg_lo:[1,0,0] neg_hi:[1,0,0]
	v_pk_fma_f32 v[140:141], v[192:193], v[110:111], v[140:141] op_sel_hi:[1,0,1] neg_lo:[1,0,0] neg_hi:[1,0,0]
	v_pk_fma_f32 v[140:141], v[194:195], v[110:111], v[140:141] op_sel:[0,1,0] neg_lo:[1,0,0] neg_hi:[1,0,0]
	ds_read_b128 v[188:191], v228 offset:10560
	ds_read_b128 v[192:195], v228 offset:10752
	s_waitcnt lgkmcnt(14)
	v_pk_fma_f32 v[140:141], v[196:197], v[112:113], v[140:141] op_sel_hi:[1,0,1] neg_lo:[1,0,0] neg_hi:[1,0,0]
	v_pk_fma_f32 v[140:141], v[198:199], v[112:113], v[140:141] op_sel:[0,1,0] neg_lo:[1,0,0] neg_hi:[1,0,0]
	v_pk_fma_f32 v[140:141], v[200:201], v[114:115], v[140:141] op_sel_hi:[1,0,1] neg_lo:[1,0,0] neg_hi:[1,0,0]
	v_pk_fma_f32 v[140:141], v[202:203], v[114:115], v[140:141] op_sel:[0,1,0] neg_lo:[1,0,0] neg_hi:[1,0,0]
	ds_read_b128 v[196:199], v228 offset:10768
	ds_read_b128 v[200:203], v228 offset:10784
	s_waitcnt lgkmcnt(14)
	v_pk_fma_f32 v[140:141], v[204:205], v[116:117], v[140:141] op_sel_hi:[1,0,1] neg_lo:[1,0,0] neg_hi:[1,0,0]
	v_pk_fma_f32 v[140:141], v[206:207], v[116:117], v[140:141] op_sel:[0,1,0] neg_lo:[1,0,0] neg_hi:[1,0,0]
	v_pk_fma_f32 v[140:141], v[208:209], v[118:119], v[140:141] op_sel_hi:[1,0,1] neg_lo:[1,0,0] neg_hi:[1,0,0]
	v_pk_fma_f32 v[140:141], v[210:211], v[118:119], v[140:141] op_sel:[0,1,0] neg_lo:[1,0,0] neg_hi:[1,0,0]
	ds_read_b128 v[204:207], v228 offset:10800
	ds_read_b128 v[208:211], v228 offset:10816
	s_waitcnt lgkmcnt(14)
	v_pk_fma_f32 v[140:141], v[212:213], v[120:121], v[140:141] op_sel_hi:[1,0,1] neg_lo:[1,0,0] neg_hi:[1,0,0]
	v_pk_fma_f32 v[140:141], v[214:215], v[120:121], v[140:141] op_sel:[0,1,0] neg_lo:[1,0,0] neg_hi:[1,0,0]
	v_pk_fma_f32 v[140:141], v[216:217], v[122:123], v[140:141] op_sel_hi:[1,0,1] neg_lo:[1,0,0] neg_hi:[1,0,0]
	v_pk_fma_f32 v[140:141], v[218:219], v[122:123], v[140:141] op_sel:[0,1,0] neg_lo:[1,0,0] neg_hi:[1,0,0]
	ds_read_b128 v[212:215], v228 offset:10832
	ds_read_b128 v[216:219], v228 offset:10848
	s_waitcnt lgkmcnt(14)
	v_pk_fma_f32 v[140:141], v[220:221], v[124:125], v[140:141] op_sel_hi:[1,0,1] neg_lo:[1,0,0] neg_hi:[1,0,0]
	v_pk_fma_f32 v[140:141], v[222:223], v[124:125], v[140:141] op_sel:[0,1,0] neg_lo:[1,0,0] neg_hi:[1,0,0]
	v_pk_fma_f32 v[140:141], v[224:225], v[126:127], v[140:141] op_sel_hi:[1,0,1] neg_lo:[1,0,0] neg_hi:[1,0,0]
	v_pk_fma_f32 v[140:141], v[226:227], v[126:127], v[140:141] op_sel:[0,1,0] neg_lo:[1,0,0] neg_hi:[1,0,0]
	ds_read_b128 v[220:223], v228 offset:10864
	ds_read_b128 v[224:227], v228 offset:10880
	s_waitcnt lgkmcnt(14)
	v_pk_fma_f32 v[140:141], v[164:165], v[128:129], v[140:141] op_sel_hi:[1,0,1] neg_lo:[1,0,0] neg_hi:[1,0,0]
	v_pk_fma_f32 v[140:141], v[166:167], v[128:129], v[140:141] op_sel:[0,1,0] neg_lo:[1,0,0] neg_hi:[1,0,0]
	v_pk_fma_f32 v[140:141], v[168:169], v[130:131], v[140:141] op_sel_hi:[1,0,1] neg_lo:[1,0,0] neg_hi:[1,0,0]
	v_pk_fma_f32 v[140:141], v[170:171], v[130:131], v[140:141] op_sel:[0,1,0] neg_lo:[1,0,0] neg_hi:[1,0,0]
	ds_read_b128 v[164:167], v228 offset:10896
	ds_read_b128 v[168:171], v228 offset:10912
	s_waitcnt lgkmcnt(14)
	v_pk_fma_f32 v[140:141], v[172:173], v[132:133], v[140:141] op_sel_hi:[1,0,1] neg_lo:[1,0,0] neg_hi:[1,0,0]
	v_pk_fma_f32 v[140:141], v[174:175], v[132:133], v[140:141] op_sel:[0,1,0] neg_lo:[1,0,0] neg_hi:[1,0,0]
	v_pk_fma_f32 v[140:141], v[176:177], v[134:135], v[140:141] op_sel_hi:[1,0,1] neg_lo:[1,0,0] neg_hi:[1,0,0]
	v_pk_fma_f32 v[140:141], v[178:179], v[134:135], v[140:141] op_sel:[0,1,0] neg_lo:[1,0,0] neg_hi:[1,0,0]
	ds_read_b128 v[172:175], v228 offset:10928
	ds_read_b128 v[176:179], v228 offset:10944
	s_waitcnt lgkmcnt(14)
	v_pk_fma_f32 v[140:141], v[180:181], v[136:137], v[140:141] op_sel_hi:[1,0,1] neg_lo:[1,0,0] neg_hi:[1,0,0]
	v_pk_fma_f32 v[140:141], v[182:183], v[136:137], v[140:141] op_sel:[0,1,0] neg_lo:[1,0,0] neg_hi:[1,0,0]
	v_pk_fma_f32 v[140:141], v[184:185], v[138:139], v[140:141] op_sel_hi:[1,0,1] neg_lo:[1,0,0] neg_hi:[1,0,0]
	v_pk_fma_f32 v[140:141], v[186:187], v[138:139], v[140:141] op_sel:[0,1,0] neg_lo:[1,0,0] neg_hi:[1,0,0]
	ds_read_b128 v[180:183], v228 offset:10960
	ds_read_b128 v[184:187], v228 offset:10976
	s_waitcnt lgkmcnt(14)
	v_fma_f32 v141, -v189, v140, v141
	v_pk_fma_f32 v[142:143], v[192:193], v[100:101], v[142:143] op_sel_hi:[1,0,1] neg_lo:[1,0,0] neg_hi:[1,0,0]
	v_pk_fma_f32 v[142:143], v[194:195], v[100:101], v[142:143] op_sel:[0,1,0] neg_lo:[1,0,0] neg_hi:[1,0,0]
	ds_read_b128 v[188:191], v228 offset:10992
	ds_read_b128 v[192:195], v228 offset:11008
	s_waitcnt lgkmcnt(14)
	v_pk_fma_f32 v[142:143], v[196:197], v[102:103], v[142:143] op_sel_hi:[1,0,1] neg_lo:[1,0,0] neg_hi:[1,0,0]
	v_pk_fma_f32 v[142:143], v[198:199], v[102:103], v[142:143] op_sel:[0,1,0] neg_lo:[1,0,0] neg_hi:[1,0,0]
	v_pk_fma_f32 v[142:143], v[200:201], v[104:105], v[142:143] op_sel_hi:[1,0,1] neg_lo:[1,0,0] neg_hi:[1,0,0]
	v_pk_fma_f32 v[142:143], v[202:203], v[104:105], v[142:143] op_sel:[0,1,0] neg_lo:[1,0,0] neg_hi:[1,0,0]
	ds_read_b128 v[196:199], v228 offset:11024
	ds_read_b128 v[200:203], v228 offset:11040
	s_waitcnt lgkmcnt(14)
	v_pk_fma_f32 v[142:143], v[204:205], v[106:107], v[142:143] op_sel_hi:[1,0,1] neg_lo:[1,0,0] neg_hi:[1,0,0]
	v_pk_fma_f32 v[142:143], v[206:207], v[106:107], v[142:143] op_sel:[0,1,0] neg_lo:[1,0,0] neg_hi:[1,0,0]
	v_pk_fma_f32 v[142:143], v[208:209], v[108:109], v[142:143] op_sel_hi:[1,0,1] neg_lo:[1,0,0] neg_hi:[1,0,0]
	v_pk_fma_f32 v[142:143], v[210:211], v[108:109], v[142:143] op_sel:[0,1,0] neg_lo:[1,0,0] neg_hi:[1,0,0]
	ds_read_b128 v[204:207], v228 offset:11056
	ds_read_b128 v[208:211], v228 offset:11072
	s_waitcnt lgkmcnt(14)
	v_pk_fma_f32 v[142:143], v[212:213], v[110:111], v[142:143] op_sel_hi:[1,0,1] neg_lo:[1,0,0] neg_hi:[1,0,0]
	v_pk_fma_f32 v[142:143], v[214:215], v[110:111], v[142:143] op_sel:[0,1,0] neg_lo:[1,0,0] neg_hi:[1,0,0]
	v_pk_fma_f32 v[142:143], v[216:217], v[112:113], v[142:143] op_sel_hi:[1,0,1] neg_lo:[1,0,0] neg_hi:[1,0,0]
	v_pk_fma_f32 v[142:143], v[218:219], v[112:113], v[142:143] op_sel:[0,1,0] neg_lo:[1,0,0] neg_hi:[1,0,0]
	ds_read_b128 v[212:215], v228 offset:11088
	ds_read_b128 v[216:219], v228 offset:11264
	s_waitcnt lgkmcnt(14)
	v_pk_fma_f32 v[142:143], v[220:221], v[114:115], v[142:143] op_sel_hi:[1,0,1] neg_lo:[1,0,0] neg_hi:[1,0,0]
	v_pk_fma_f32 v[142:143], v[222:223], v[114:115], v[142:143] op_sel:[0,1,0] neg_lo:[1,0,0] neg_hi:[1,0,0]
	v_pk_fma_f32 v[142:143], v[224:225], v[116:117], v[142:143] op_sel_hi:[1,0,1] neg_lo:[1,0,0] neg_hi:[1,0,0]
	v_pk_fma_f32 v[142:143], v[226:227], v[116:117], v[142:143] op_sel:[0,1,0] neg_lo:[1,0,0] neg_hi:[1,0,0]
	ds_read_b128 v[220:223], v228 offset:11280
	ds_read_b128 v[224:227], v228 offset:11296
	s_waitcnt lgkmcnt(14)
	v_pk_fma_f32 v[142:143], v[164:165], v[118:119], v[142:143] op_sel_hi:[1,0,1] neg_lo:[1,0,0] neg_hi:[1,0,0]
	v_pk_fma_f32 v[142:143], v[166:167], v[118:119], v[142:143] op_sel:[0,1,0] neg_lo:[1,0,0] neg_hi:[1,0,0]
	v_pk_fma_f32 v[142:143], v[168:169], v[120:121], v[142:143] op_sel_hi:[1,0,1] neg_lo:[1,0,0] neg_hi:[1,0,0]
	v_pk_fma_f32 v[142:143], v[170:171], v[120:121], v[142:143] op_sel:[0,1,0] neg_lo:[1,0,0] neg_hi:[1,0,0]
	ds_read_b128 v[164:167], v228 offset:11312
	ds_read_b128 v[168:171], v228 offset:11328
	s_waitcnt lgkmcnt(14)
	v_pk_fma_f32 v[142:143], v[172:173], v[122:123], v[142:143] op_sel_hi:[1,0,1] neg_lo:[1,0,0] neg_hi:[1,0,0]
	v_pk_fma_f32 v[142:143], v[174:175], v[122:123], v[142:143] op_sel:[0,1,0] neg_lo:[1,0,0] neg_hi:[1,0,0]
	v_pk_fma_f32 v[142:143], v[176:177], v[124:125], v[142:143] op_sel_hi:[1,0,1] neg_lo:[1,0,0] neg_hi:[1,0,0]
	v_pk_fma_f32 v[142:143], v[178:179], v[124:125], v[142:143] op_sel:[0,1,0] neg_lo:[1,0,0] neg_hi:[1,0,0]
	ds_read_b128 v[172:175], v228 offset:11344
	ds_read_b128 v[176:179], v228 offset:11360
	s_waitcnt lgkmcnt(14)
	v_pk_fma_f32 v[142:143], v[180:181], v[126:127], v[142:143] op_sel_hi:[1,0,1] neg_lo:[1,0,0] neg_hi:[1,0,0]
	v_pk_fma_f32 v[142:143], v[182:183], v[126:127], v[142:143] op_sel:[0,1,0] neg_lo:[1,0,0] neg_hi:[1,0,0]
	v_pk_fma_f32 v[142:143], v[184:185], v[128:129], v[142:143] op_sel_hi:[1,0,1] neg_lo:[1,0,0] neg_hi:[1,0,0]
	v_pk_fma_f32 v[142:143], v[186:187], v[128:129], v[142:143] op_sel:[0,1,0] neg_lo:[1,0,0] neg_hi:[1,0,0]
	ds_read_b128 v[180:183], v228 offset:11376
	ds_read_b128 v[184:187], v228 offset:11392
	s_waitcnt lgkmcnt(14)
	v_pk_fma_f32 v[142:143], v[188:189], v[130:131], v[142:143] op_sel_hi:[1,0,1] neg_lo:[1,0,0] neg_hi:[1,0,0]
	v_pk_fma_f32 v[142:143], v[190:191], v[130:131], v[142:143] op_sel:[0,1,0] neg_lo:[1,0,0] neg_hi:[1,0,0]
	v_pk_fma_f32 v[142:143], v[192:193], v[132:133], v[142:143] op_sel_hi:[1,0,1] neg_lo:[1,0,0] neg_hi:[1,0,0]
	v_pk_fma_f32 v[142:143], v[194:195], v[132:133], v[142:143] op_sel:[0,1,0] neg_lo:[1,0,0] neg_hi:[1,0,0]
	ds_read_b128 v[188:191], v228 offset:11408
	ds_read_b128 v[192:195], v228 offset:11424
	s_waitcnt lgkmcnt(14)
	v_pk_fma_f32 v[142:143], v[196:197], v[134:135], v[142:143] op_sel_hi:[1,0,1] neg_lo:[1,0,0] neg_hi:[1,0,0]
	v_pk_fma_f32 v[142:143], v[198:199], v[134:135], v[142:143] op_sel:[0,1,0] neg_lo:[1,0,0] neg_hi:[1,0,0]
	v_pk_fma_f32 v[142:143], v[200:201], v[136:137], v[142:143] op_sel_hi:[1,0,1] neg_lo:[1,0,0] neg_hi:[1,0,0]
	v_pk_fma_f32 v[142:143], v[202:203], v[136:137], v[142:143] op_sel:[0,1,0] neg_lo:[1,0,0] neg_hi:[1,0,0]
	ds_read_b128 v[196:199], v228 offset:11440
	ds_read_b128 v[200:203], v228 offset:11456
	s_waitcnt lgkmcnt(14)
	v_pk_fma_f32 v[142:143], v[204:205], v[138:139], v[142:143] op_sel_hi:[1,0,1] neg_lo:[1,0,0] neg_hi:[1,0,0]
	v_pk_fma_f32 v[142:143], v[206:207], v[138:139], v[142:143] op_sel:[0,1,0] neg_lo:[1,0,0] neg_hi:[1,0,0]
	v_pk_fma_f32 v[142:143], v[208:209], v[140:141], v[142:143] op_sel_hi:[1,0,1] neg_lo:[1,0,0] neg_hi:[1,0,0]
	v_pk_fma_f32 v[142:143], v[210:211], v[140:141], v[142:143] op_sel:[0,1,0] neg_lo:[1,0,0] neg_hi:[1,0,0]
	ds_read_b128 v[204:207], v228 offset:11472
	ds_read_b128 v[208:211], v228 offset:11488
	s_waitcnt lgkmcnt(14)
	v_fma_f32 v143, -v213, v142, v143
	v_pk_fma_f32 v[144:145], v[216:217], v[100:101], v[144:145] op_sel_hi:[1,0,1] neg_lo:[1,0,0] neg_hi:[1,0,0]
	v_pk_fma_f32 v[144:145], v[218:219], v[100:101], v[144:145] op_sel:[0,1,0] neg_lo:[1,0,0] neg_hi:[1,0,0]
	ds_read_b128 v[212:215], v228 offset:11504
	ds_read_b128 v[216:219], v228 offset:11520
	s_waitcnt lgkmcnt(14)
	v_pk_fma_f32 v[144:145], v[220:221], v[102:103], v[144:145] op_sel_hi:[1,0,1] neg_lo:[1,0,0] neg_hi:[1,0,0]
	v_pk_fma_f32 v[144:145], v[222:223], v[102:103], v[144:145] op_sel:[0,1,0] neg_lo:[1,0,0] neg_hi:[1,0,0]
	v_pk_fma_f32 v[144:145], v[224:225], v[104:105], v[144:145] op_sel_hi:[1,0,1] neg_lo:[1,0,0] neg_hi:[1,0,0]
	v_pk_fma_f32 v[144:145], v[226:227], v[104:105], v[144:145] op_sel:[0,1,0] neg_lo:[1,0,0] neg_hi:[1,0,0]
	ds_read_b128 v[220:223], v228 offset:11536
	ds_read_b128 v[224:227], v228 offset:11552
	s_waitcnt lgkmcnt(14)
	v_pk_fma_f32 v[144:145], v[164:165], v[106:107], v[144:145] op_sel_hi:[1,0,1] neg_lo:[1,0,0] neg_hi:[1,0,0]
	v_pk_fma_f32 v[144:145], v[166:167], v[106:107], v[144:145] op_sel:[0,1,0] neg_lo:[1,0,0] neg_hi:[1,0,0]
	v_pk_fma_f32 v[144:145], v[168:169], v[108:109], v[144:145] op_sel_hi:[1,0,1] neg_lo:[1,0,0] neg_hi:[1,0,0]
	v_pk_fma_f32 v[144:145], v[170:171], v[108:109], v[144:145] op_sel:[0,1,0] neg_lo:[1,0,0] neg_hi:[1,0,0]
	ds_read_b128 v[164:167], v228 offset:11568
	ds_read_b128 v[168:171], v228 offset:11584
	s_waitcnt lgkmcnt(14)
	v_pk_fma_f32 v[144:145], v[172:173], v[110:111], v[144:145] op_sel_hi:[1,0,1] neg_lo:[1,0,0] neg_hi:[1,0,0]
	v_pk_fma_f32 v[144:145], v[174:175], v[110:111], v[144:145] op_sel:[0,1,0] neg_lo:[1,0,0] neg_hi:[1,0,0]
	v_pk_fma_f32 v[144:145], v[176:177], v[112:113], v[144:145] op_sel_hi:[1,0,1] neg_lo:[1,0,0] neg_hi:[1,0,0]
	v_pk_fma_f32 v[144:145], v[178:179], v[112:113], v[144:145] op_sel:[0,1,0] neg_lo:[1,0,0] neg_hi:[1,0,0]
	ds_read_b128 v[172:175], v228 offset:11600
	ds_read_b128 v[176:179], v228 offset:11616
	s_waitcnt lgkmcnt(14)
	v_pk_fma_f32 v[144:145], v[180:181], v[114:115], v[144:145] op_sel_hi:[1,0,1] neg_lo:[1,0,0] neg_hi:[1,0,0]
	v_pk_fma_f32 v[144:145], v[182:183], v[114:115], v[144:145] op_sel:[0,1,0] neg_lo:[1,0,0] neg_hi:[1,0,0]
	v_pk_fma_f32 v[144:145], v[184:185], v[116:117], v[144:145] op_sel_hi:[1,0,1] neg_lo:[1,0,0] neg_hi:[1,0,0]
	v_pk_fma_f32 v[144:145], v[186:187], v[116:117], v[144:145] op_sel:[0,1,0] neg_lo:[1,0,0] neg_hi:[1,0,0]
	ds_read_b128 v[180:183], v228 offset:11776
	ds_read_b128 v[184:187], v228 offset:11792
	s_waitcnt lgkmcnt(14)
	v_pk_fma_f32 v[144:145], v[188:189], v[118:119], v[144:145] op_sel_hi:[1,0,1] neg_lo:[1,0,0] neg_hi:[1,0,0]
	v_pk_fma_f32 v[144:145], v[190:191], v[118:119], v[144:145] op_sel:[0,1,0] neg_lo:[1,0,0] neg_hi:[1,0,0]
	v_pk_fma_f32 v[144:145], v[192:193], v[120:121], v[144:145] op_sel_hi:[1,0,1] neg_lo:[1,0,0] neg_hi:[1,0,0]
	v_pk_fma_f32 v[144:145], v[194:195], v[120:121], v[144:145] op_sel:[0,1,0] neg_lo:[1,0,0] neg_hi:[1,0,0]
	ds_read_b128 v[188:191], v228 offset:11808
	ds_read_b128 v[192:195], v228 offset:11824
	s_waitcnt lgkmcnt(14)
	v_pk_fma_f32 v[144:145], v[196:197], v[122:123], v[144:145] op_sel_hi:[1,0,1] neg_lo:[1,0,0] neg_hi:[1,0,0]
	v_pk_fma_f32 v[144:145], v[198:199], v[122:123], v[144:145] op_sel:[0,1,0] neg_lo:[1,0,0] neg_hi:[1,0,0]
	v_pk_fma_f32 v[144:145], v[200:201], v[124:125], v[144:145] op_sel_hi:[1,0,1] neg_lo:[1,0,0] neg_hi:[1,0,0]
	v_pk_fma_f32 v[144:145], v[202:203], v[124:125], v[144:145] op_sel:[0,1,0] neg_lo:[1,0,0] neg_hi:[1,0,0]
	ds_read_b128 v[196:199], v228 offset:11840
	ds_read_b128 v[200:203], v228 offset:11856
	s_waitcnt lgkmcnt(14)
	v_pk_fma_f32 v[144:145], v[204:205], v[126:127], v[144:145] op_sel_hi:[1,0,1] neg_lo:[1,0,0] neg_hi:[1,0,0]
	v_pk_fma_f32 v[144:145], v[206:207], v[126:127], v[144:145] op_sel:[0,1,0] neg_lo:[1,0,0] neg_hi:[1,0,0]
	v_pk_fma_f32 v[144:145], v[208:209], v[128:129], v[144:145] op_sel_hi:[1,0,1] neg_lo:[1,0,0] neg_hi:[1,0,0]
	v_pk_fma_f32 v[144:145], v[210:211], v[128:129], v[144:145] op_sel:[0,1,0] neg_lo:[1,0,0] neg_hi:[1,0,0]
	ds_read_b128 v[204:207], v228 offset:11872
	ds_read_b128 v[208:211], v228 offset:11888
	s_waitcnt lgkmcnt(14)
	v_pk_fma_f32 v[144:145], v[212:213], v[130:131], v[144:145] op_sel_hi:[1,0,1] neg_lo:[1,0,0] neg_hi:[1,0,0]
	v_pk_fma_f32 v[144:145], v[214:215], v[130:131], v[144:145] op_sel:[0,1,0] neg_lo:[1,0,0] neg_hi:[1,0,0]
	v_pk_fma_f32 v[144:145], v[216:217], v[132:133], v[144:145] op_sel_hi:[1,0,1] neg_lo:[1,0,0] neg_hi:[1,0,0]
	v_pk_fma_f32 v[144:145], v[218:219], v[132:133], v[144:145] op_sel:[0,1,0] neg_lo:[1,0,0] neg_hi:[1,0,0]
	ds_read_b128 v[212:215], v228 offset:11904
	ds_read_b128 v[216:219], v228 offset:11920
	s_waitcnt lgkmcnt(14)
	v_pk_fma_f32 v[144:145], v[220:221], v[134:135], v[144:145] op_sel_hi:[1,0,1] neg_lo:[1,0,0] neg_hi:[1,0,0]
	v_pk_fma_f32 v[144:145], v[222:223], v[134:135], v[144:145] op_sel:[0,1,0] neg_lo:[1,0,0] neg_hi:[1,0,0]
	v_pk_fma_f32 v[144:145], v[224:225], v[136:137], v[144:145] op_sel_hi:[1,0,1] neg_lo:[1,0,0] neg_hi:[1,0,0]
	v_pk_fma_f32 v[144:145], v[226:227], v[136:137], v[144:145] op_sel:[0,1,0] neg_lo:[1,0,0] neg_hi:[1,0,0]
	ds_read_b128 v[220:223], v228 offset:11936
	ds_read_b128 v[224:227], v228 offset:11952
	s_waitcnt lgkmcnt(14)
	v_pk_fma_f32 v[144:145], v[164:165], v[138:139], v[144:145] op_sel_hi:[1,0,1] neg_lo:[1,0,0] neg_hi:[1,0,0]
	v_pk_fma_f32 v[144:145], v[166:167], v[138:139], v[144:145] op_sel:[0,1,0] neg_lo:[1,0,0] neg_hi:[1,0,0]
	v_pk_fma_f32 v[144:145], v[168:169], v[140:141], v[144:145] op_sel_hi:[1,0,1] neg_lo:[1,0,0] neg_hi:[1,0,0]
	v_pk_fma_f32 v[144:145], v[170:171], v[140:141], v[144:145] op_sel:[0,1,0] neg_lo:[1,0,0] neg_hi:[1,0,0]
	ds_read_b128 v[164:167], v228 offset:11968
	ds_read_b128 v[168:171], v228 offset:11984
	s_waitcnt lgkmcnt(14)
	v_pk_fma_f32 v[144:145], v[172:173], v[142:143], v[144:145] op_sel_hi:[1,0,1] neg_lo:[1,0,0] neg_hi:[1,0,0]
	v_pk_fma_f32 v[144:145], v[174:175], v[142:143], v[144:145] op_sel:[0,1,0] neg_lo:[1,0,0] neg_hi:[1,0,0]
	v_fma_f32 v145, -v177, v144, v145
	ds_read_b128 v[172:175], v228 offset:12000
	ds_read_b128 v[176:179], v228 offset:12016
	s_waitcnt lgkmcnt(14)
	v_pk_fma_f32 v[146:147], v[180:181], v[100:101], v[146:147] op_sel_hi:[1,0,1] neg_lo:[1,0,0] neg_hi:[1,0,0]
	v_pk_fma_f32 v[146:147], v[182:183], v[100:101], v[146:147] op_sel:[0,1,0] neg_lo:[1,0,0] neg_hi:[1,0,0]
	v_pk_fma_f32 v[146:147], v[184:185], v[102:103], v[146:147] op_sel_hi:[1,0,1] neg_lo:[1,0,0] neg_hi:[1,0,0]
	v_pk_fma_f32 v[146:147], v[186:187], v[102:103], v[146:147] op_sel:[0,1,0] neg_lo:[1,0,0] neg_hi:[1,0,0]
	ds_read_b128 v[180:183], v228 offset:12032
	ds_read_b128 v[184:187], v228 offset:12048
	s_waitcnt lgkmcnt(14)
	v_pk_fma_f32 v[146:147], v[188:189], v[104:105], v[146:147] op_sel_hi:[1,0,1] neg_lo:[1,0,0] neg_hi:[1,0,0]
	v_pk_fma_f32 v[146:147], v[190:191], v[104:105], v[146:147] op_sel:[0,1,0] neg_lo:[1,0,0] neg_hi:[1,0,0]
	v_pk_fma_f32 v[146:147], v[192:193], v[106:107], v[146:147] op_sel_hi:[1,0,1] neg_lo:[1,0,0] neg_hi:[1,0,0]
	v_pk_fma_f32 v[146:147], v[194:195], v[106:107], v[146:147] op_sel:[0,1,0] neg_lo:[1,0,0] neg_hi:[1,0,0]
	ds_read_b128 v[188:191], v228 offset:12064
	ds_read_b128 v[192:195], v228 offset:12080
	s_waitcnt lgkmcnt(14)
	v_pk_fma_f32 v[146:147], v[196:197], v[108:109], v[146:147] op_sel_hi:[1,0,1] neg_lo:[1,0,0] neg_hi:[1,0,0]
	v_pk_fma_f32 v[146:147], v[198:199], v[108:109], v[146:147] op_sel:[0,1,0] neg_lo:[1,0,0] neg_hi:[1,0,0]
	v_pk_fma_f32 v[146:147], v[200:201], v[110:111], v[146:147] op_sel_hi:[1,0,1] neg_lo:[1,0,0] neg_hi:[1,0,0]
	v_pk_fma_f32 v[146:147], v[202:203], v[110:111], v[146:147] op_sel:[0,1,0] neg_lo:[1,0,0] neg_hi:[1,0,0]
	ds_read_b128 v[196:199], v228 offset:12096
	ds_read_b128 v[200:203], v228 offset:12112
	s_waitcnt lgkmcnt(14)
	v_pk_fma_f32 v[146:147], v[204:205], v[112:113], v[146:147] op_sel_hi:[1,0,1] neg_lo:[1,0,0] neg_hi:[1,0,0]
	v_pk_fma_f32 v[146:147], v[206:207], v[112:113], v[146:147] op_sel:[0,1,0] neg_lo:[1,0,0] neg_hi:[1,0,0]
	v_pk_fma_f32 v[146:147], v[208:209], v[114:115], v[146:147] op_sel_hi:[1,0,1] neg_lo:[1,0,0] neg_hi:[1,0,0]
	v_pk_fma_f32 v[146:147], v[210:211], v[114:115], v[146:147] op_sel:[0,1,0] neg_lo:[1,0,0] neg_hi:[1,0,0]
	ds_read_b128 v[204:207], v228 offset:12128
	ds_read_b128 v[208:211], v228 offset:12144
	s_waitcnt lgkmcnt(14)
	v_pk_fma_f32 v[146:147], v[212:213], v[116:117], v[146:147] op_sel_hi:[1,0,1] neg_lo:[1,0,0] neg_hi:[1,0,0]
	v_pk_fma_f32 v[146:147], v[214:215], v[116:117], v[146:147] op_sel:[0,1,0] neg_lo:[1,0,0] neg_hi:[1,0,0]
	v_pk_fma_f32 v[146:147], v[216:217], v[118:119], v[146:147] op_sel_hi:[1,0,1] neg_lo:[1,0,0] neg_hi:[1,0,0]
	v_pk_fma_f32 v[146:147], v[218:219], v[118:119], v[146:147] op_sel:[0,1,0] neg_lo:[1,0,0] neg_hi:[1,0,0]
	ds_read_b128 v[212:215], v228 offset:12288
	ds_read_b128 v[216:219], v228 offset:12304
	s_waitcnt lgkmcnt(14)
	v_pk_fma_f32 v[146:147], v[220:221], v[120:121], v[146:147] op_sel_hi:[1,0,1] neg_lo:[1,0,0] neg_hi:[1,0,0]
	v_pk_fma_f32 v[146:147], v[222:223], v[120:121], v[146:147] op_sel:[0,1,0] neg_lo:[1,0,0] neg_hi:[1,0,0]
	v_pk_fma_f32 v[146:147], v[224:225], v[122:123], v[146:147] op_sel_hi:[1,0,1] neg_lo:[1,0,0] neg_hi:[1,0,0]
	v_pk_fma_f32 v[146:147], v[226:227], v[122:123], v[146:147] op_sel:[0,1,0] neg_lo:[1,0,0] neg_hi:[1,0,0]
	ds_read_b128 v[220:223], v228 offset:12320
	ds_read_b128 v[224:227], v228 offset:12336
	s_waitcnt lgkmcnt(14)
	v_pk_fma_f32 v[146:147], v[164:165], v[124:125], v[146:147] op_sel_hi:[1,0,1] neg_lo:[1,0,0] neg_hi:[1,0,0]
	v_pk_fma_f32 v[146:147], v[166:167], v[124:125], v[146:147] op_sel:[0,1,0] neg_lo:[1,0,0] neg_hi:[1,0,0]
	v_pk_fma_f32 v[146:147], v[168:169], v[126:127], v[146:147] op_sel_hi:[1,0,1] neg_lo:[1,0,0] neg_hi:[1,0,0]
	v_pk_fma_f32 v[146:147], v[170:171], v[126:127], v[146:147] op_sel:[0,1,0] neg_lo:[1,0,0] neg_hi:[1,0,0]
	ds_read_b128 v[164:167], v228 offset:12352
	ds_read_b128 v[168:171], v228 offset:12368
	s_waitcnt lgkmcnt(14)
	v_pk_fma_f32 v[146:147], v[172:173], v[128:129], v[146:147] op_sel_hi:[1,0,1] neg_lo:[1,0,0] neg_hi:[1,0,0]
	v_pk_fma_f32 v[146:147], v[174:175], v[128:129], v[146:147] op_sel:[0,1,0] neg_lo:[1,0,0] neg_hi:[1,0,0]
	v_pk_fma_f32 v[146:147], v[176:177], v[130:131], v[146:147] op_sel_hi:[1,0,1] neg_lo:[1,0,0] neg_hi:[1,0,0]
	v_pk_fma_f32 v[146:147], v[178:179], v[130:131], v[146:147] op_sel:[0,1,0] neg_lo:[1,0,0] neg_hi:[1,0,0]
	ds_read_b128 v[172:175], v228 offset:12384
	ds_read_b128 v[176:179], v228 offset:12400
	s_waitcnt lgkmcnt(14)
	v_pk_fma_f32 v[146:147], v[180:181], v[132:133], v[146:147] op_sel_hi:[1,0,1] neg_lo:[1,0,0] neg_hi:[1,0,0]
	v_pk_fma_f32 v[146:147], v[182:183], v[132:133], v[146:147] op_sel:[0,1,0] neg_lo:[1,0,0] neg_hi:[1,0,0]
	v_pk_fma_f32 v[146:147], v[184:185], v[134:135], v[146:147] op_sel_hi:[1,0,1] neg_lo:[1,0,0] neg_hi:[1,0,0]
	v_pk_fma_f32 v[146:147], v[186:187], v[134:135], v[146:147] op_sel:[0,1,0] neg_lo:[1,0,0] neg_hi:[1,0,0]
	ds_read_b128 v[180:183], v228 offset:12416
	ds_read_b128 v[184:187], v228 offset:12432
	s_waitcnt lgkmcnt(14)
	v_pk_fma_f32 v[146:147], v[188:189], v[136:137], v[146:147] op_sel_hi:[1,0,1] neg_lo:[1,0,0] neg_hi:[1,0,0]
	v_pk_fma_f32 v[146:147], v[190:191], v[136:137], v[146:147] op_sel:[0,1,0] neg_lo:[1,0,0] neg_hi:[1,0,0]
	v_pk_fma_f32 v[146:147], v[192:193], v[138:139], v[146:147] op_sel_hi:[1,0,1] neg_lo:[1,0,0] neg_hi:[1,0,0]
	v_pk_fma_f32 v[146:147], v[194:195], v[138:139], v[146:147] op_sel:[0,1,0] neg_lo:[1,0,0] neg_hi:[1,0,0]
	ds_read_b128 v[188:191], v228 offset:12448
	ds_read_b128 v[192:195], v228 offset:12464
	s_waitcnt lgkmcnt(14)
	v_pk_fma_f32 v[146:147], v[196:197], v[140:141], v[146:147] op_sel_hi:[1,0,1] neg_lo:[1,0,0] neg_hi:[1,0,0]
	v_pk_fma_f32 v[146:147], v[198:199], v[140:141], v[146:147] op_sel:[0,1,0] neg_lo:[1,0,0] neg_hi:[1,0,0]
	v_pk_fma_f32 v[146:147], v[200:201], v[142:143], v[146:147] op_sel_hi:[1,0,1] neg_lo:[1,0,0] neg_hi:[1,0,0]
	v_pk_fma_f32 v[146:147], v[202:203], v[142:143], v[146:147] op_sel:[0,1,0] neg_lo:[1,0,0] neg_hi:[1,0,0]
	ds_read_b128 v[196:199], v228 offset:12480
	ds_read_b128 v[200:203], v228 offset:12496
	s_waitcnt lgkmcnt(14)
	v_pk_fma_f32 v[146:147], v[204:205], v[144:145], v[146:147] op_sel_hi:[1,0,1] neg_lo:[1,0,0] neg_hi:[1,0,0]
	v_pk_fma_f32 v[146:147], v[206:207], v[144:145], v[146:147] op_sel:[0,1,0] neg_lo:[1,0,0] neg_hi:[1,0,0]
	v_fma_f32 v147, -v209, v146, v147
	ds_read_b128 v[204:207], v228 offset:12512
	ds_read_b128 v[208:211], v228 offset:12528
	s_waitcnt lgkmcnt(14)
	v_pk_fma_f32 v[148:149], v[212:213], v[100:101], v[148:149] op_sel_hi:[1,0,1] neg_lo:[1,0,0] neg_hi:[1,0,0]
	v_pk_fma_f32 v[148:149], v[214:215], v[100:101], v[148:149] op_sel:[0,1,0] neg_lo:[1,0,0] neg_hi:[1,0,0]
	v_pk_fma_f32 v[148:149], v[216:217], v[102:103], v[148:149] op_sel_hi:[1,0,1] neg_lo:[1,0,0] neg_hi:[1,0,0]
	v_pk_fma_f32 v[148:149], v[218:219], v[102:103], v[148:149] op_sel:[0,1,0] neg_lo:[1,0,0] neg_hi:[1,0,0]
	ds_read_b128 v[212:215], v228 offset:12544
	ds_read_b128 v[216:219], v228 offset:12560
	s_waitcnt lgkmcnt(14)
	v_pk_fma_f32 v[148:149], v[220:221], v[104:105], v[148:149] op_sel_hi:[1,0,1] neg_lo:[1,0,0] neg_hi:[1,0,0]
	v_pk_fma_f32 v[148:149], v[222:223], v[104:105], v[148:149] op_sel:[0,1,0] neg_lo:[1,0,0] neg_hi:[1,0,0]
	v_pk_fma_f32 v[148:149], v[224:225], v[106:107], v[148:149] op_sel_hi:[1,0,1] neg_lo:[1,0,0] neg_hi:[1,0,0]
	v_pk_fma_f32 v[148:149], v[226:227], v[106:107], v[148:149] op_sel:[0,1,0] neg_lo:[1,0,0] neg_hi:[1,0,0]
	ds_read_b128 v[220:223], v228 offset:12576
	ds_read_b128 v[224:227], v228 offset:12592
	s_waitcnt lgkmcnt(14)
	v_pk_fma_f32 v[148:149], v[164:165], v[108:109], v[148:149] op_sel_hi:[1,0,1] neg_lo:[1,0,0] neg_hi:[1,0,0]
	v_pk_fma_f32 v[148:149], v[166:167], v[108:109], v[148:149] op_sel:[0,1,0] neg_lo:[1,0,0] neg_hi:[1,0,0]
	v_pk_fma_f32 v[148:149], v[168:169], v[110:111], v[148:149] op_sel_hi:[1,0,1] neg_lo:[1,0,0] neg_hi:[1,0,0]
	v_pk_fma_f32 v[148:149], v[170:171], v[110:111], v[148:149] op_sel:[0,1,0] neg_lo:[1,0,0] neg_hi:[1,0,0]
	ds_read_b128 v[164:167], v228 offset:12608
	ds_read_b128 v[168:171], v228 offset:12624
	s_waitcnt lgkmcnt(14)
	v_pk_fma_f32 v[148:149], v[172:173], v[112:113], v[148:149] op_sel_hi:[1,0,1] neg_lo:[1,0,0] neg_hi:[1,0,0]
	v_pk_fma_f32 v[148:149], v[174:175], v[112:113], v[148:149] op_sel:[0,1,0] neg_lo:[1,0,0] neg_hi:[1,0,0]
	v_pk_fma_f32 v[148:149], v[176:177], v[114:115], v[148:149] op_sel_hi:[1,0,1] neg_lo:[1,0,0] neg_hi:[1,0,0]
	v_pk_fma_f32 v[148:149], v[178:179], v[114:115], v[148:149] op_sel:[0,1,0] neg_lo:[1,0,0] neg_hi:[1,0,0]
	ds_read_b128 v[172:175], v228 offset:12640
	ds_read_b128 v[176:179], v228 offset:12656
	s_waitcnt lgkmcnt(14)
	v_pk_fma_f32 v[148:149], v[180:181], v[116:117], v[148:149] op_sel_hi:[1,0,1] neg_lo:[1,0,0] neg_hi:[1,0,0]
	v_pk_fma_f32 v[148:149], v[182:183], v[116:117], v[148:149] op_sel:[0,1,0] neg_lo:[1,0,0] neg_hi:[1,0,0]
	v_pk_fma_f32 v[148:149], v[184:185], v[118:119], v[148:149] op_sel_hi:[1,0,1] neg_lo:[1,0,0] neg_hi:[1,0,0]
	v_pk_fma_f32 v[148:149], v[186:187], v[118:119], v[148:149] op_sel:[0,1,0] neg_lo:[1,0,0] neg_hi:[1,0,0]
	ds_read_b128 v[180:183], v228 offset:12672
	ds_read_b128 v[184:187], v228 offset:12800
	s_waitcnt lgkmcnt(14)
	v_pk_fma_f32 v[148:149], v[188:189], v[120:121], v[148:149] op_sel_hi:[1,0,1] neg_lo:[1,0,0] neg_hi:[1,0,0]
	v_pk_fma_f32 v[148:149], v[190:191], v[120:121], v[148:149] op_sel:[0,1,0] neg_lo:[1,0,0] neg_hi:[1,0,0]
	v_pk_fma_f32 v[148:149], v[192:193], v[122:123], v[148:149] op_sel_hi:[1,0,1] neg_lo:[1,0,0] neg_hi:[1,0,0]
	v_pk_fma_f32 v[148:149], v[194:195], v[122:123], v[148:149] op_sel:[0,1,0] neg_lo:[1,0,0] neg_hi:[1,0,0]
	ds_read_b128 v[188:191], v228 offset:12816
	ds_read_b128 v[192:195], v228 offset:12832
	s_waitcnt lgkmcnt(14)
	v_pk_fma_f32 v[148:149], v[196:197], v[124:125], v[148:149] op_sel_hi:[1,0,1] neg_lo:[1,0,0] neg_hi:[1,0,0]
	v_pk_fma_f32 v[148:149], v[198:199], v[124:125], v[148:149] op_sel:[0,1,0] neg_lo:[1,0,0] neg_hi:[1,0,0]
	v_pk_fma_f32 v[148:149], v[200:201], v[126:127], v[148:149] op_sel_hi:[1,0,1] neg_lo:[1,0,0] neg_hi:[1,0,0]
	v_pk_fma_f32 v[148:149], v[202:203], v[126:127], v[148:149] op_sel:[0,1,0] neg_lo:[1,0,0] neg_hi:[1,0,0]
	ds_read_b128 v[196:199], v228 offset:12848
	ds_read_b128 v[200:203], v228 offset:12864
	s_waitcnt lgkmcnt(14)
	v_pk_fma_f32 v[148:149], v[204:205], v[128:129], v[148:149] op_sel_hi:[1,0,1] neg_lo:[1,0,0] neg_hi:[1,0,0]
	v_pk_fma_f32 v[148:149], v[206:207], v[128:129], v[148:149] op_sel:[0,1,0] neg_lo:[1,0,0] neg_hi:[1,0,0]
	v_pk_fma_f32 v[148:149], v[208:209], v[130:131], v[148:149] op_sel_hi:[1,0,1] neg_lo:[1,0,0] neg_hi:[1,0,0]
	v_pk_fma_f32 v[148:149], v[210:211], v[130:131], v[148:149] op_sel:[0,1,0] neg_lo:[1,0,0] neg_hi:[1,0,0]
	ds_read_b128 v[204:207], v228 offset:12880
	ds_read_b128 v[208:211], v228 offset:12896
	s_waitcnt lgkmcnt(14)
	v_pk_fma_f32 v[148:149], v[212:213], v[132:133], v[148:149] op_sel_hi:[1,0,1] neg_lo:[1,0,0] neg_hi:[1,0,0]
	v_pk_fma_f32 v[148:149], v[214:215], v[132:133], v[148:149] op_sel:[0,1,0] neg_lo:[1,0,0] neg_hi:[1,0,0]
	v_pk_fma_f32 v[148:149], v[216:217], v[134:135], v[148:149] op_sel_hi:[1,0,1] neg_lo:[1,0,0] neg_hi:[1,0,0]
	v_pk_fma_f32 v[148:149], v[218:219], v[134:135], v[148:149] op_sel:[0,1,0] neg_lo:[1,0,0] neg_hi:[1,0,0]
	ds_read_b128 v[212:215], v228 offset:12912
	ds_read_b128 v[216:219], v228 offset:12928
	s_waitcnt lgkmcnt(14)
	v_pk_fma_f32 v[148:149], v[220:221], v[136:137], v[148:149] op_sel_hi:[1,0,1] neg_lo:[1,0,0] neg_hi:[1,0,0]
	v_pk_fma_f32 v[148:149], v[222:223], v[136:137], v[148:149] op_sel:[0,1,0] neg_lo:[1,0,0] neg_hi:[1,0,0]
	v_pk_fma_f32 v[148:149], v[224:225], v[138:139], v[148:149] op_sel_hi:[1,0,1] neg_lo:[1,0,0] neg_hi:[1,0,0]
	v_pk_fma_f32 v[148:149], v[226:227], v[138:139], v[148:149] op_sel:[0,1,0] neg_lo:[1,0,0] neg_hi:[1,0,0]
	ds_read_b128 v[220:223], v228 offset:12944
	ds_read_b128 v[224:227], v228 offset:12960
	s_waitcnt lgkmcnt(14)
	v_pk_fma_f32 v[148:149], v[164:165], v[140:141], v[148:149] op_sel_hi:[1,0,1] neg_lo:[1,0,0] neg_hi:[1,0,0]
	v_pk_fma_f32 v[148:149], v[166:167], v[140:141], v[148:149] op_sel:[0,1,0] neg_lo:[1,0,0] neg_hi:[1,0,0]
	v_pk_fma_f32 v[148:149], v[168:169], v[142:143], v[148:149] op_sel_hi:[1,0,1] neg_lo:[1,0,0] neg_hi:[1,0,0]
	v_pk_fma_f32 v[148:149], v[170:171], v[142:143], v[148:149] op_sel:[0,1,0] neg_lo:[1,0,0] neg_hi:[1,0,0]
	ds_read_b128 v[164:167], v228 offset:12976
	ds_read_b128 v[168:171], v228 offset:12992
	s_waitcnt lgkmcnt(14)
	v_pk_fma_f32 v[148:149], v[172:173], v[144:145], v[148:149] op_sel_hi:[1,0,1] neg_lo:[1,0,0] neg_hi:[1,0,0]
	v_pk_fma_f32 v[148:149], v[174:175], v[144:145], v[148:149] op_sel:[0,1,0] neg_lo:[1,0,0] neg_hi:[1,0,0]
	v_pk_fma_f32 v[148:149], v[176:177], v[146:147], v[148:149] op_sel_hi:[1,0,1] neg_lo:[1,0,0] neg_hi:[1,0,0]
	v_pk_fma_f32 v[148:149], v[178:179], v[146:147], v[148:149] op_sel:[0,1,0] neg_lo:[1,0,0] neg_hi:[1,0,0]
	ds_read_b128 v[172:175], v228 offset:13008
	ds_read_b128 v[176:179], v228 offset:13024
	s_waitcnt lgkmcnt(14)
	v_fma_f32 v149, -v181, v148, v149
	v_pk_fma_f32 v[150:151], v[184:185], v[100:101], v[150:151] op_sel_hi:[1,0,1] neg_lo:[1,0,0] neg_hi:[1,0,0]
	v_pk_fma_f32 v[150:151], v[186:187], v[100:101], v[150:151] op_sel:[0,1,0] neg_lo:[1,0,0] neg_hi:[1,0,0]
	ds_read_b128 v[180:183], v228 offset:13040
	ds_read_b128 v[184:187], v228 offset:13056
	s_waitcnt lgkmcnt(14)
	v_pk_fma_f32 v[150:151], v[188:189], v[102:103], v[150:151] op_sel_hi:[1,0,1] neg_lo:[1,0,0] neg_hi:[1,0,0]
	v_pk_fma_f32 v[150:151], v[190:191], v[102:103], v[150:151] op_sel:[0,1,0] neg_lo:[1,0,0] neg_hi:[1,0,0]
	v_pk_fma_f32 v[150:151], v[192:193], v[104:105], v[150:151] op_sel_hi:[1,0,1] neg_lo:[1,0,0] neg_hi:[1,0,0]
	v_pk_fma_f32 v[150:151], v[194:195], v[104:105], v[150:151] op_sel:[0,1,0] neg_lo:[1,0,0] neg_hi:[1,0,0]
	ds_read_b128 v[188:191], v228 offset:13072
	ds_read_b128 v[192:195], v228 offset:13088
	s_waitcnt lgkmcnt(14)
	v_pk_fma_f32 v[150:151], v[196:197], v[106:107], v[150:151] op_sel_hi:[1,0,1] neg_lo:[1,0,0] neg_hi:[1,0,0]
	v_pk_fma_f32 v[150:151], v[198:199], v[106:107], v[150:151] op_sel:[0,1,0] neg_lo:[1,0,0] neg_hi:[1,0,0]
	v_pk_fma_f32 v[150:151], v[200:201], v[108:109], v[150:151] op_sel_hi:[1,0,1] neg_lo:[1,0,0] neg_hi:[1,0,0]
	v_pk_fma_f32 v[150:151], v[202:203], v[108:109], v[150:151] op_sel:[0,1,0] neg_lo:[1,0,0] neg_hi:[1,0,0]
	ds_read_b128 v[196:199], v228 offset:13104
	ds_read_b128 v[200:203], v228 offset:13120
	s_waitcnt lgkmcnt(14)
	v_pk_fma_f32 v[150:151], v[204:205], v[110:111], v[150:151] op_sel_hi:[1,0,1] neg_lo:[1,0,0] neg_hi:[1,0,0]
	v_pk_fma_f32 v[150:151], v[206:207], v[110:111], v[150:151] op_sel:[0,1,0] neg_lo:[1,0,0] neg_hi:[1,0,0]
	v_pk_fma_f32 v[150:151], v[208:209], v[112:113], v[150:151] op_sel_hi:[1,0,1] neg_lo:[1,0,0] neg_hi:[1,0,0]
	v_pk_fma_f32 v[150:151], v[210:211], v[112:113], v[150:151] op_sel:[0,1,0] neg_lo:[1,0,0] neg_hi:[1,0,0]
	ds_read_b128 v[204:207], v228 offset:13136
	ds_read_b128 v[208:211], v228 offset:13152
	s_waitcnt lgkmcnt(14)
	v_pk_fma_f32 v[150:151], v[212:213], v[114:115], v[150:151] op_sel_hi:[1,0,1] neg_lo:[1,0,0] neg_hi:[1,0,0]
	v_pk_fma_f32 v[150:151], v[214:215], v[114:115], v[150:151] op_sel:[0,1,0] neg_lo:[1,0,0] neg_hi:[1,0,0]
	v_pk_fma_f32 v[150:151], v[216:217], v[116:117], v[150:151] op_sel_hi:[1,0,1] neg_lo:[1,0,0] neg_hi:[1,0,0]
	v_pk_fma_f32 v[150:151], v[218:219], v[116:117], v[150:151] op_sel:[0,1,0] neg_lo:[1,0,0] neg_hi:[1,0,0]
	ds_read_b128 v[212:215], v228 offset:13168
	ds_read_b128 v[216:219], v228 offset:13184
	s_waitcnt lgkmcnt(14)
	v_pk_fma_f32 v[150:151], v[220:221], v[118:119], v[150:151] op_sel_hi:[1,0,1] neg_lo:[1,0,0] neg_hi:[1,0,0]
	v_pk_fma_f32 v[150:151], v[222:223], v[118:119], v[150:151] op_sel:[0,1,0] neg_lo:[1,0,0] neg_hi:[1,0,0]
	v_pk_fma_f32 v[150:151], v[224:225], v[120:121], v[150:151] op_sel_hi:[1,0,1] neg_lo:[1,0,0] neg_hi:[1,0,0]
	v_pk_fma_f32 v[150:151], v[226:227], v[120:121], v[150:151] op_sel:[0,1,0] neg_lo:[1,0,0] neg_hi:[1,0,0]
	ds_read_b128 v[220:223], v228 offset:13200
	ds_read_b128 v[224:227], v228 offset:13312
	s_waitcnt lgkmcnt(14)
	v_pk_fma_f32 v[150:151], v[164:165], v[122:123], v[150:151] op_sel_hi:[1,0,1] neg_lo:[1,0,0] neg_hi:[1,0,0]
	v_pk_fma_f32 v[150:151], v[166:167], v[122:123], v[150:151] op_sel:[0,1,0] neg_lo:[1,0,0] neg_hi:[1,0,0]
	v_pk_fma_f32 v[150:151], v[168:169], v[124:125], v[150:151] op_sel_hi:[1,0,1] neg_lo:[1,0,0] neg_hi:[1,0,0]
	v_pk_fma_f32 v[150:151], v[170:171], v[124:125], v[150:151] op_sel:[0,1,0] neg_lo:[1,0,0] neg_hi:[1,0,0]
	ds_read_b128 v[164:167], v228 offset:13328
	ds_read_b128 v[168:171], v228 offset:13344
	s_waitcnt lgkmcnt(14)
	v_pk_fma_f32 v[150:151], v[172:173], v[126:127], v[150:151] op_sel_hi:[1,0,1] neg_lo:[1,0,0] neg_hi:[1,0,0]
	v_pk_fma_f32 v[150:151], v[174:175], v[126:127], v[150:151] op_sel:[0,1,0] neg_lo:[1,0,0] neg_hi:[1,0,0]
	v_pk_fma_f32 v[150:151], v[176:177], v[128:129], v[150:151] op_sel_hi:[1,0,1] neg_lo:[1,0,0] neg_hi:[1,0,0]
	v_pk_fma_f32 v[150:151], v[178:179], v[128:129], v[150:151] op_sel:[0,1,0] neg_lo:[1,0,0] neg_hi:[1,0,0]
	ds_read_b128 v[172:175], v228 offset:13360
	ds_read_b128 v[176:179], v228 offset:13376
	s_waitcnt lgkmcnt(14)
	v_pk_fma_f32 v[150:151], v[180:181], v[130:131], v[150:151] op_sel_hi:[1,0,1] neg_lo:[1,0,0] neg_hi:[1,0,0]
	v_pk_fma_f32 v[150:151], v[182:183], v[130:131], v[150:151] op_sel:[0,1,0] neg_lo:[1,0,0] neg_hi:[1,0,0]
	v_pk_fma_f32 v[150:151], v[184:185], v[132:133], v[150:151] op_sel_hi:[1,0,1] neg_lo:[1,0,0] neg_hi:[1,0,0]
	v_pk_fma_f32 v[150:151], v[186:187], v[132:133], v[150:151] op_sel:[0,1,0] neg_lo:[1,0,0] neg_hi:[1,0,0]
	ds_read_b128 v[180:183], v228 offset:13392
	ds_read_b128 v[184:187], v228 offset:13408
	s_waitcnt lgkmcnt(14)
	v_pk_fma_f32 v[150:151], v[188:189], v[134:135], v[150:151] op_sel_hi:[1,0,1] neg_lo:[1,0,0] neg_hi:[1,0,0]
	v_pk_fma_f32 v[150:151], v[190:191], v[134:135], v[150:151] op_sel:[0,1,0] neg_lo:[1,0,0] neg_hi:[1,0,0]
	v_pk_fma_f32 v[150:151], v[192:193], v[136:137], v[150:151] op_sel_hi:[1,0,1] neg_lo:[1,0,0] neg_hi:[1,0,0]
	v_pk_fma_f32 v[150:151], v[194:195], v[136:137], v[150:151] op_sel:[0,1,0] neg_lo:[1,0,0] neg_hi:[1,0,0]
	ds_read_b128 v[188:191], v228 offset:13424
	ds_read_b128 v[192:195], v228 offset:13440
	s_waitcnt lgkmcnt(14)
	v_pk_fma_f32 v[150:151], v[196:197], v[138:139], v[150:151] op_sel_hi:[1,0,1] neg_lo:[1,0,0] neg_hi:[1,0,0]
	v_pk_fma_f32 v[150:151], v[198:199], v[138:139], v[150:151] op_sel:[0,1,0] neg_lo:[1,0,0] neg_hi:[1,0,0]
	v_pk_fma_f32 v[150:151], v[200:201], v[140:141], v[150:151] op_sel_hi:[1,0,1] neg_lo:[1,0,0] neg_hi:[1,0,0]
	v_pk_fma_f32 v[150:151], v[202:203], v[140:141], v[150:151] op_sel:[0,1,0] neg_lo:[1,0,0] neg_hi:[1,0,0]
	ds_read_b128 v[196:199], v228 offset:13456
	ds_read_b128 v[200:203], v228 offset:13472
	s_waitcnt lgkmcnt(14)
	v_pk_fma_f32 v[150:151], v[204:205], v[142:143], v[150:151] op_sel_hi:[1,0,1] neg_lo:[1,0,0] neg_hi:[1,0,0]
	v_pk_fma_f32 v[150:151], v[206:207], v[142:143], v[150:151] op_sel:[0,1,0] neg_lo:[1,0,0] neg_hi:[1,0,0]
	v_pk_fma_f32 v[150:151], v[208:209], v[144:145], v[150:151] op_sel_hi:[1,0,1] neg_lo:[1,0,0] neg_hi:[1,0,0]
	v_pk_fma_f32 v[150:151], v[210:211], v[144:145], v[150:151] op_sel:[0,1,0] neg_lo:[1,0,0] neg_hi:[1,0,0]
	ds_read_b128 v[204:207], v228 offset:13488
	ds_read_b128 v[208:211], v228 offset:13504
	s_waitcnt lgkmcnt(14)
	v_pk_fma_f32 v[150:151], v[212:213], v[146:147], v[150:151] op_sel_hi:[1,0,1] neg_lo:[1,0,0] neg_hi:[1,0,0]
	v_pk_fma_f32 v[150:151], v[214:215], v[146:147], v[150:151] op_sel:[0,1,0] neg_lo:[1,0,0] neg_hi:[1,0,0]
	v_pk_fma_f32 v[150:151], v[216:217], v[148:149], v[150:151] op_sel_hi:[1,0,1] neg_lo:[1,0,0] neg_hi:[1,0,0]
	v_pk_fma_f32 v[150:151], v[218:219], v[148:149], v[150:151] op_sel:[0,1,0] neg_lo:[1,0,0] neg_hi:[1,0,0]
	ds_read_b128 v[212:215], v228 offset:13520
	ds_read_b128 v[216:219], v228 offset:13536
	s_waitcnt lgkmcnt(14)
	v_fma_f32 v151, -v221, v150, v151
	v_pk_fma_f32 v[152:153], v[224:225], v[100:101], v[152:153] op_sel_hi:[1,0,1] neg_lo:[1,0,0] neg_hi:[1,0,0]
	v_pk_fma_f32 v[152:153], v[226:227], v[100:101], v[152:153] op_sel:[0,1,0] neg_lo:[1,0,0] neg_hi:[1,0,0]
	ds_read_b128 v[220:223], v228 offset:13552
	ds_read_b128 v[224:227], v228 offset:13568
	s_waitcnt lgkmcnt(14)
	v_pk_fma_f32 v[152:153], v[164:165], v[102:103], v[152:153] op_sel_hi:[1,0,1] neg_lo:[1,0,0] neg_hi:[1,0,0]
	v_pk_fma_f32 v[152:153], v[166:167], v[102:103], v[152:153] op_sel:[0,1,0] neg_lo:[1,0,0] neg_hi:[1,0,0]
	v_pk_fma_f32 v[152:153], v[168:169], v[104:105], v[152:153] op_sel_hi:[1,0,1] neg_lo:[1,0,0] neg_hi:[1,0,0]
	v_pk_fma_f32 v[152:153], v[170:171], v[104:105], v[152:153] op_sel:[0,1,0] neg_lo:[1,0,0] neg_hi:[1,0,0]
	ds_read_b128 v[164:167], v228 offset:13584
	ds_read_b128 v[168:171], v228 offset:13600
	s_waitcnt lgkmcnt(14)
	v_pk_fma_f32 v[152:153], v[172:173], v[106:107], v[152:153] op_sel_hi:[1,0,1] neg_lo:[1,0,0] neg_hi:[1,0,0]
	v_pk_fma_f32 v[152:153], v[174:175], v[106:107], v[152:153] op_sel:[0,1,0] neg_lo:[1,0,0] neg_hi:[1,0,0]
	v_pk_fma_f32 v[152:153], v[176:177], v[108:109], v[152:153] op_sel_hi:[1,0,1] neg_lo:[1,0,0] neg_hi:[1,0,0]
	v_pk_fma_f32 v[152:153], v[178:179], v[108:109], v[152:153] op_sel:[0,1,0] neg_lo:[1,0,0] neg_hi:[1,0,0]
	ds_read_b128 v[172:175], v228 offset:13616
	ds_read_b128 v[176:179], v228 offset:13632
	s_waitcnt lgkmcnt(14)
	v_pk_fma_f32 v[152:153], v[180:181], v[110:111], v[152:153] op_sel_hi:[1,0,1] neg_lo:[1,0,0] neg_hi:[1,0,0]
	v_pk_fma_f32 v[152:153], v[182:183], v[110:111], v[152:153] op_sel:[0,1,0] neg_lo:[1,0,0] neg_hi:[1,0,0]
	v_pk_fma_f32 v[152:153], v[184:185], v[112:113], v[152:153] op_sel_hi:[1,0,1] neg_lo:[1,0,0] neg_hi:[1,0,0]
	v_pk_fma_f32 v[152:153], v[186:187], v[112:113], v[152:153] op_sel:[0,1,0] neg_lo:[1,0,0] neg_hi:[1,0,0]
	ds_read_b128 v[180:183], v228 offset:13648
	ds_read_b128 v[184:187], v228 offset:13664
	s_waitcnt lgkmcnt(14)
	v_pk_fma_f32 v[152:153], v[188:189], v[114:115], v[152:153] op_sel_hi:[1,0,1] neg_lo:[1,0,0] neg_hi:[1,0,0]
	v_pk_fma_f32 v[152:153], v[190:191], v[114:115], v[152:153] op_sel:[0,1,0] neg_lo:[1,0,0] neg_hi:[1,0,0]
	v_pk_fma_f32 v[152:153], v[192:193], v[116:117], v[152:153] op_sel_hi:[1,0,1] neg_lo:[1,0,0] neg_hi:[1,0,0]
	v_pk_fma_f32 v[152:153], v[194:195], v[116:117], v[152:153] op_sel:[0,1,0] neg_lo:[1,0,0] neg_hi:[1,0,0]
	ds_read_b128 v[188:191], v228 offset:13680
	ds_read_b128 v[192:195], v228 offset:13696
	s_waitcnt lgkmcnt(14)
	v_pk_fma_f32 v[152:153], v[196:197], v[118:119], v[152:153] op_sel_hi:[1,0,1] neg_lo:[1,0,0] neg_hi:[1,0,0]
	v_pk_fma_f32 v[152:153], v[198:199], v[118:119], v[152:153] op_sel:[0,1,0] neg_lo:[1,0,0] neg_hi:[1,0,0]
	v_pk_fma_f32 v[152:153], v[200:201], v[120:121], v[152:153] op_sel_hi:[1,0,1] neg_lo:[1,0,0] neg_hi:[1,0,0]
	v_pk_fma_f32 v[152:153], v[202:203], v[120:121], v[152:153] op_sel:[0,1,0] neg_lo:[1,0,0] neg_hi:[1,0,0]
	ds_read_b128 v[196:199], v228 offset:13712
	ds_read_b128 v[200:203], v228 offset:13728
	s_waitcnt lgkmcnt(14)
	v_pk_fma_f32 v[152:153], v[204:205], v[122:123], v[152:153] op_sel_hi:[1,0,1] neg_lo:[1,0,0] neg_hi:[1,0,0]
	v_pk_fma_f32 v[152:153], v[206:207], v[122:123], v[152:153] op_sel:[0,1,0] neg_lo:[1,0,0] neg_hi:[1,0,0]
	v_pk_fma_f32 v[152:153], v[208:209], v[124:125], v[152:153] op_sel_hi:[1,0,1] neg_lo:[1,0,0] neg_hi:[1,0,0]
	v_pk_fma_f32 v[152:153], v[210:211], v[124:125], v[152:153] op_sel:[0,1,0] neg_lo:[1,0,0] neg_hi:[1,0,0]
	ds_read_b128 v[204:207], v228 offset:13824
	ds_read_b128 v[208:211], v228 offset:13840
	s_waitcnt lgkmcnt(14)
	v_pk_fma_f32 v[152:153], v[212:213], v[126:127], v[152:153] op_sel_hi:[1,0,1] neg_lo:[1,0,0] neg_hi:[1,0,0]
	v_pk_fma_f32 v[152:153], v[214:215], v[126:127], v[152:153] op_sel:[0,1,0] neg_lo:[1,0,0] neg_hi:[1,0,0]
	v_pk_fma_f32 v[152:153], v[216:217], v[128:129], v[152:153] op_sel_hi:[1,0,1] neg_lo:[1,0,0] neg_hi:[1,0,0]
	v_pk_fma_f32 v[152:153], v[218:219], v[128:129], v[152:153] op_sel:[0,1,0] neg_lo:[1,0,0] neg_hi:[1,0,0]
	ds_read_b128 v[212:215], v228 offset:13856
	ds_read_b128 v[216:219], v228 offset:13872
	s_waitcnt lgkmcnt(14)
	v_pk_fma_f32 v[152:153], v[220:221], v[130:131], v[152:153] op_sel_hi:[1,0,1] neg_lo:[1,0,0] neg_hi:[1,0,0]
	v_pk_fma_f32 v[152:153], v[222:223], v[130:131], v[152:153] op_sel:[0,1,0] neg_lo:[1,0,0] neg_hi:[1,0,0]
	v_pk_fma_f32 v[152:153], v[224:225], v[132:133], v[152:153] op_sel_hi:[1,0,1] neg_lo:[1,0,0] neg_hi:[1,0,0]
	v_pk_fma_f32 v[152:153], v[226:227], v[132:133], v[152:153] op_sel:[0,1,0] neg_lo:[1,0,0] neg_hi:[1,0,0]
	ds_read_b128 v[220:223], v228 offset:13888
	ds_read_b128 v[224:227], v228 offset:13904
	s_waitcnt lgkmcnt(14)
	v_pk_fma_f32 v[152:153], v[164:165], v[134:135], v[152:153] op_sel_hi:[1,0,1] neg_lo:[1,0,0] neg_hi:[1,0,0]
	v_pk_fma_f32 v[152:153], v[166:167], v[134:135], v[152:153] op_sel:[0,1,0] neg_lo:[1,0,0] neg_hi:[1,0,0]
	v_pk_fma_f32 v[152:153], v[168:169], v[136:137], v[152:153] op_sel_hi:[1,0,1] neg_lo:[1,0,0] neg_hi:[1,0,0]
	v_pk_fma_f32 v[152:153], v[170:171], v[136:137], v[152:153] op_sel:[0,1,0] neg_lo:[1,0,0] neg_hi:[1,0,0]
	ds_read_b128 v[164:167], v228 offset:13920
	ds_read_b128 v[168:171], v228 offset:13936
	s_waitcnt lgkmcnt(14)
	v_pk_fma_f32 v[152:153], v[172:173], v[138:139], v[152:153] op_sel_hi:[1,0,1] neg_lo:[1,0,0] neg_hi:[1,0,0]
	v_pk_fma_f32 v[152:153], v[174:175], v[138:139], v[152:153] op_sel:[0,1,0] neg_lo:[1,0,0] neg_hi:[1,0,0]
	v_pk_fma_f32 v[152:153], v[176:177], v[140:141], v[152:153] op_sel_hi:[1,0,1] neg_lo:[1,0,0] neg_hi:[1,0,0]
	v_pk_fma_f32 v[152:153], v[178:179], v[140:141], v[152:153] op_sel:[0,1,0] neg_lo:[1,0,0] neg_hi:[1,0,0]
	ds_read_b128 v[172:175], v228 offset:13952
	ds_read_b128 v[176:179], v228 offset:13968
	s_waitcnt lgkmcnt(14)
	v_pk_fma_f32 v[152:153], v[180:181], v[142:143], v[152:153] op_sel_hi:[1,0,1] neg_lo:[1,0,0] neg_hi:[1,0,0]
	v_pk_fma_f32 v[152:153], v[182:183], v[142:143], v[152:153] op_sel:[0,1,0] neg_lo:[1,0,0] neg_hi:[1,0,0]
	v_pk_fma_f32 v[152:153], v[184:185], v[144:145], v[152:153] op_sel_hi:[1,0,1] neg_lo:[1,0,0] neg_hi:[1,0,0]
	v_pk_fma_f32 v[152:153], v[186:187], v[144:145], v[152:153] op_sel:[0,1,0] neg_lo:[1,0,0] neg_hi:[1,0,0]
	ds_read_b128 v[180:183], v228 offset:13984
	ds_read_b128 v[184:187], v228 offset:14000
	s_waitcnt lgkmcnt(14)
	v_pk_fma_f32 v[152:153], v[188:189], v[146:147], v[152:153] op_sel_hi:[1,0,1] neg_lo:[1,0,0] neg_hi:[1,0,0]
	v_pk_fma_f32 v[152:153], v[190:191], v[146:147], v[152:153] op_sel:[0,1,0] neg_lo:[1,0,0] neg_hi:[1,0,0]
	v_pk_fma_f32 v[152:153], v[192:193], v[148:149], v[152:153] op_sel_hi:[1,0,1] neg_lo:[1,0,0] neg_hi:[1,0,0]
	v_pk_fma_f32 v[152:153], v[194:195], v[148:149], v[152:153] op_sel:[0,1,0] neg_lo:[1,0,0] neg_hi:[1,0,0]
	ds_read_b128 v[188:191], v228 offset:14016
	ds_read_b128 v[192:195], v228 offset:14032
	s_waitcnt lgkmcnt(14)
	v_pk_fma_f32 v[152:153], v[196:197], v[150:151], v[152:153] op_sel_hi:[1,0,1] neg_lo:[1,0,0] neg_hi:[1,0,0]
	v_pk_fma_f32 v[152:153], v[198:199], v[150:151], v[152:153] op_sel:[0,1,0] neg_lo:[1,0,0] neg_hi:[1,0,0]
	v_fma_f32 v153, -v201, v152, v153
	ds_read_b128 v[196:199], v228 offset:14048
	ds_read_b128 v[200:203], v228 offset:14064
	s_waitcnt lgkmcnt(14)
	v_pk_fma_f32 v[154:155], v[204:205], v[100:101], v[154:155] op_sel_hi:[1,0,1] neg_lo:[1,0,0] neg_hi:[1,0,0]
	v_pk_fma_f32 v[154:155], v[206:207], v[100:101], v[154:155] op_sel:[0,1,0] neg_lo:[1,0,0] neg_hi:[1,0,0]
	v_pk_fma_f32 v[154:155], v[208:209], v[102:103], v[154:155] op_sel_hi:[1,0,1] neg_lo:[1,0,0] neg_hi:[1,0,0]
	v_pk_fma_f32 v[154:155], v[210:211], v[102:103], v[154:155] op_sel:[0,1,0] neg_lo:[1,0,0] neg_hi:[1,0,0]
	ds_read_b128 v[204:207], v228 offset:14080
	ds_read_b128 v[208:211], v228 offset:14096
	s_waitcnt lgkmcnt(14)
	v_pk_fma_f32 v[154:155], v[212:213], v[104:105], v[154:155] op_sel_hi:[1,0,1] neg_lo:[1,0,0] neg_hi:[1,0,0]
	v_pk_fma_f32 v[154:155], v[214:215], v[104:105], v[154:155] op_sel:[0,1,0] neg_lo:[1,0,0] neg_hi:[1,0,0]
	v_pk_fma_f32 v[154:155], v[216:217], v[106:107], v[154:155] op_sel_hi:[1,0,1] neg_lo:[1,0,0] neg_hi:[1,0,0]
	v_pk_fma_f32 v[154:155], v[218:219], v[106:107], v[154:155] op_sel:[0,1,0] neg_lo:[1,0,0] neg_hi:[1,0,0]
	ds_read_b128 v[212:215], v228 offset:14112
	ds_read_b128 v[216:219], v228 offset:14128
	s_waitcnt lgkmcnt(14)
	v_pk_fma_f32 v[154:155], v[220:221], v[108:109], v[154:155] op_sel_hi:[1,0,1] neg_lo:[1,0,0] neg_hi:[1,0,0]
	v_pk_fma_f32 v[154:155], v[222:223], v[108:109], v[154:155] op_sel:[0,1,0] neg_lo:[1,0,0] neg_hi:[1,0,0]
	v_pk_fma_f32 v[154:155], v[224:225], v[110:111], v[154:155] op_sel_hi:[1,0,1] neg_lo:[1,0,0] neg_hi:[1,0,0]
	v_pk_fma_f32 v[154:155], v[226:227], v[110:111], v[154:155] op_sel:[0,1,0] neg_lo:[1,0,0] neg_hi:[1,0,0]
	ds_read_b128 v[220:223], v228 offset:14144
	ds_read_b128 v[224:227], v228 offset:14160
	s_waitcnt lgkmcnt(14)
	v_pk_fma_f32 v[154:155], v[164:165], v[112:113], v[154:155] op_sel_hi:[1,0,1] neg_lo:[1,0,0] neg_hi:[1,0,0]
	v_pk_fma_f32 v[154:155], v[166:167], v[112:113], v[154:155] op_sel:[0,1,0] neg_lo:[1,0,0] neg_hi:[1,0,0]
	v_pk_fma_f32 v[154:155], v[168:169], v[114:115], v[154:155] op_sel_hi:[1,0,1] neg_lo:[1,0,0] neg_hi:[1,0,0]
	v_pk_fma_f32 v[154:155], v[170:171], v[114:115], v[154:155] op_sel:[0,1,0] neg_lo:[1,0,0] neg_hi:[1,0,0]
	ds_read_b128 v[164:167], v228 offset:14176
	ds_read_b128 v[168:171], v228 offset:14192
	s_waitcnt lgkmcnt(14)
	v_pk_fma_f32 v[154:155], v[172:173], v[116:117], v[154:155] op_sel_hi:[1,0,1] neg_lo:[1,0,0] neg_hi:[1,0,0]
	v_pk_fma_f32 v[154:155], v[174:175], v[116:117], v[154:155] op_sel:[0,1,0] neg_lo:[1,0,0] neg_hi:[1,0,0]
	v_pk_fma_f32 v[154:155], v[176:177], v[118:119], v[154:155] op_sel_hi:[1,0,1] neg_lo:[1,0,0] neg_hi:[1,0,0]
	v_pk_fma_f32 v[154:155], v[178:179], v[118:119], v[154:155] op_sel:[0,1,0] neg_lo:[1,0,0] neg_hi:[1,0,0]
	ds_read_b128 v[172:175], v228 offset:14208
	ds_read_b128 v[176:179], v228 offset:14224
	s_waitcnt lgkmcnt(14)
	v_pk_fma_f32 v[154:155], v[180:181], v[120:121], v[154:155] op_sel_hi:[1,0,1] neg_lo:[1,0,0] neg_hi:[1,0,0]
	v_pk_fma_f32 v[154:155], v[182:183], v[120:121], v[154:155] op_sel:[0,1,0] neg_lo:[1,0,0] neg_hi:[1,0,0]
	v_pk_fma_f32 v[154:155], v[184:185], v[122:123], v[154:155] op_sel_hi:[1,0,1] neg_lo:[1,0,0] neg_hi:[1,0,0]
	v_pk_fma_f32 v[154:155], v[186:187], v[122:123], v[154:155] op_sel:[0,1,0] neg_lo:[1,0,0] neg_hi:[1,0,0]
	ds_read_b128 v[180:183], v228 offset:14240
	ds_read_b128 v[184:187], v228 offset:14256
	s_waitcnt lgkmcnt(14)
	v_pk_fma_f32 v[154:155], v[188:189], v[124:125], v[154:155] op_sel_hi:[1,0,1] neg_lo:[1,0,0] neg_hi:[1,0,0]
	v_pk_fma_f32 v[154:155], v[190:191], v[124:125], v[154:155] op_sel:[0,1,0] neg_lo:[1,0,0] neg_hi:[1,0,0]
	v_pk_fma_f32 v[154:155], v[192:193], v[126:127], v[154:155] op_sel_hi:[1,0,1] neg_lo:[1,0,0] neg_hi:[1,0,0]
	v_pk_fma_f32 v[154:155], v[194:195], v[126:127], v[154:155] op_sel:[0,1,0] neg_lo:[1,0,0] neg_hi:[1,0,0]
	ds_read_b128 v[188:191], v228 offset:14336
	ds_read_b128 v[192:195], v228 offset:14352
	s_waitcnt lgkmcnt(14)
	v_pk_fma_f32 v[154:155], v[196:197], v[128:129], v[154:155] op_sel_hi:[1,0,1] neg_lo:[1,0,0] neg_hi:[1,0,0]
	v_pk_fma_f32 v[154:155], v[198:199], v[128:129], v[154:155] op_sel:[0,1,0] neg_lo:[1,0,0] neg_hi:[1,0,0]
	v_pk_fma_f32 v[154:155], v[200:201], v[130:131], v[154:155] op_sel_hi:[1,0,1] neg_lo:[1,0,0] neg_hi:[1,0,0]
	v_pk_fma_f32 v[154:155], v[202:203], v[130:131], v[154:155] op_sel:[0,1,0] neg_lo:[1,0,0] neg_hi:[1,0,0]
	ds_read_b128 v[196:199], v228 offset:14368
	ds_read_b128 v[200:203], v228 offset:14384
	s_waitcnt lgkmcnt(14)
	v_pk_fma_f32 v[154:155], v[204:205], v[132:133], v[154:155] op_sel_hi:[1,0,1] neg_lo:[1,0,0] neg_hi:[1,0,0]
	v_pk_fma_f32 v[154:155], v[206:207], v[132:133], v[154:155] op_sel:[0,1,0] neg_lo:[1,0,0] neg_hi:[1,0,0]
	v_pk_fma_f32 v[154:155], v[208:209], v[134:135], v[154:155] op_sel_hi:[1,0,1] neg_lo:[1,0,0] neg_hi:[1,0,0]
	v_pk_fma_f32 v[154:155], v[210:211], v[134:135], v[154:155] op_sel:[0,1,0] neg_lo:[1,0,0] neg_hi:[1,0,0]
	ds_read_b128 v[204:207], v228 offset:14400
	ds_read_b128 v[208:211], v228 offset:14416
	s_waitcnt lgkmcnt(14)
	v_pk_fma_f32 v[154:155], v[212:213], v[136:137], v[154:155] op_sel_hi:[1,0,1] neg_lo:[1,0,0] neg_hi:[1,0,0]
	v_pk_fma_f32 v[154:155], v[214:215], v[136:137], v[154:155] op_sel:[0,1,0] neg_lo:[1,0,0] neg_hi:[1,0,0]
	v_pk_fma_f32 v[154:155], v[216:217], v[138:139], v[154:155] op_sel_hi:[1,0,1] neg_lo:[1,0,0] neg_hi:[1,0,0]
	v_pk_fma_f32 v[154:155], v[218:219], v[138:139], v[154:155] op_sel:[0,1,0] neg_lo:[1,0,0] neg_hi:[1,0,0]
	ds_read_b128 v[212:215], v228 offset:14432
	ds_read_b128 v[216:219], v228 offset:14448
	s_waitcnt lgkmcnt(14)
	v_pk_fma_f32 v[154:155], v[220:221], v[140:141], v[154:155] op_sel_hi:[1,0,1] neg_lo:[1,0,0] neg_hi:[1,0,0]
	v_pk_fma_f32 v[154:155], v[222:223], v[140:141], v[154:155] op_sel:[0,1,0] neg_lo:[1,0,0] neg_hi:[1,0,0]
	v_pk_fma_f32 v[154:155], v[224:225], v[142:143], v[154:155] op_sel_hi:[1,0,1] neg_lo:[1,0,0] neg_hi:[1,0,0]
	v_pk_fma_f32 v[154:155], v[226:227], v[142:143], v[154:155] op_sel:[0,1,0] neg_lo:[1,0,0] neg_hi:[1,0,0]
	ds_read_b128 v[220:223], v228 offset:14464
	ds_read_b128 v[224:227], v228 offset:14480
	s_waitcnt lgkmcnt(14)
	v_pk_fma_f32 v[154:155], v[164:165], v[144:145], v[154:155] op_sel_hi:[1,0,1] neg_lo:[1,0,0] neg_hi:[1,0,0]
	v_pk_fma_f32 v[154:155], v[166:167], v[144:145], v[154:155] op_sel:[0,1,0] neg_lo:[1,0,0] neg_hi:[1,0,0]
	v_pk_fma_f32 v[154:155], v[168:169], v[146:147], v[154:155] op_sel_hi:[1,0,1] neg_lo:[1,0,0] neg_hi:[1,0,0]
	v_pk_fma_f32 v[154:155], v[170:171], v[146:147], v[154:155] op_sel:[0,1,0] neg_lo:[1,0,0] neg_hi:[1,0,0]
	ds_read_b128 v[164:167], v228 offset:14496
	ds_read_b128 v[168:171], v228 offset:14512
	s_waitcnt lgkmcnt(14)
	v_pk_fma_f32 v[154:155], v[172:173], v[148:149], v[154:155] op_sel_hi:[1,0,1] neg_lo:[1,0,0] neg_hi:[1,0,0]
	v_pk_fma_f32 v[154:155], v[174:175], v[148:149], v[154:155] op_sel:[0,1,0] neg_lo:[1,0,0] neg_hi:[1,0,0]
	v_pk_fma_f32 v[154:155], v[176:177], v[150:151], v[154:155] op_sel_hi:[1,0,1] neg_lo:[1,0,0] neg_hi:[1,0,0]
	v_pk_fma_f32 v[154:155], v[178:179], v[150:151], v[154:155] op_sel:[0,1,0] neg_lo:[1,0,0] neg_hi:[1,0,0]
	ds_read_b128 v[172:175], v228 offset:14528
	ds_read_b128 v[176:179], v228 offset:14544
	s_waitcnt lgkmcnt(14)
	v_pk_fma_f32 v[154:155], v[180:181], v[152:153], v[154:155] op_sel_hi:[1,0,1] neg_lo:[1,0,0] neg_hi:[1,0,0]
	v_pk_fma_f32 v[154:155], v[182:183], v[152:153], v[154:155] op_sel:[0,1,0] neg_lo:[1,0,0] neg_hi:[1,0,0]
	v_fma_f32 v155, -v185, v154, v155
	ds_read_b128 v[180:183], v228 offset:14560
	ds_read_b128 v[184:187], v228 offset:14576
	s_waitcnt lgkmcnt(14)
	v_pk_fma_f32 v[156:157], v[188:189], v[100:101], v[156:157] op_sel_hi:[1,0,1] neg_lo:[1,0,0] neg_hi:[1,0,0]
	v_pk_fma_f32 v[156:157], v[190:191], v[100:101], v[156:157] op_sel:[0,1,0] neg_lo:[1,0,0] neg_hi:[1,0,0]
	v_pk_fma_f32 v[156:157], v[192:193], v[102:103], v[156:157] op_sel_hi:[1,0,1] neg_lo:[1,0,0] neg_hi:[1,0,0]
	v_pk_fma_f32 v[156:157], v[194:195], v[102:103], v[156:157] op_sel:[0,1,0] neg_lo:[1,0,0] neg_hi:[1,0,0]
	ds_read_b128 v[188:191], v228 offset:14592
	ds_read_b128 v[192:195], v228 offset:14608
	s_waitcnt lgkmcnt(14)
	v_pk_fma_f32 v[156:157], v[196:197], v[104:105], v[156:157] op_sel_hi:[1,0,1] neg_lo:[1,0,0] neg_hi:[1,0,0]
	v_pk_fma_f32 v[156:157], v[198:199], v[104:105], v[156:157] op_sel:[0,1,0] neg_lo:[1,0,0] neg_hi:[1,0,0]
	v_pk_fma_f32 v[156:157], v[200:201], v[106:107], v[156:157] op_sel_hi:[1,0,1] neg_lo:[1,0,0] neg_hi:[1,0,0]
	v_pk_fma_f32 v[156:157], v[202:203], v[106:107], v[156:157] op_sel:[0,1,0] neg_lo:[1,0,0] neg_hi:[1,0,0]
	ds_read_b128 v[196:199], v228 offset:14624
	ds_read_b128 v[200:203], v228 offset:14640
	s_waitcnt lgkmcnt(14)
	v_pk_fma_f32 v[156:157], v[204:205], v[108:109], v[156:157] op_sel_hi:[1,0,1] neg_lo:[1,0,0] neg_hi:[1,0,0]
	v_pk_fma_f32 v[156:157], v[206:207], v[108:109], v[156:157] op_sel:[0,1,0] neg_lo:[1,0,0] neg_hi:[1,0,0]
	v_pk_fma_f32 v[156:157], v[208:209], v[110:111], v[156:157] op_sel_hi:[1,0,1] neg_lo:[1,0,0] neg_hi:[1,0,0]
	v_pk_fma_f32 v[156:157], v[210:211], v[110:111], v[156:157] op_sel:[0,1,0] neg_lo:[1,0,0] neg_hi:[1,0,0]
	ds_read_b128 v[204:207], v228 offset:14656
	ds_read_b128 v[208:211], v228 offset:14672
	s_waitcnt lgkmcnt(14)
	v_pk_fma_f32 v[156:157], v[212:213], v[112:113], v[156:157] op_sel_hi:[1,0,1] neg_lo:[1,0,0] neg_hi:[1,0,0]
	v_pk_fma_f32 v[156:157], v[214:215], v[112:113], v[156:157] op_sel:[0,1,0] neg_lo:[1,0,0] neg_hi:[1,0,0]
	v_pk_fma_f32 v[156:157], v[216:217], v[114:115], v[156:157] op_sel_hi:[1,0,1] neg_lo:[1,0,0] neg_hi:[1,0,0]
	v_pk_fma_f32 v[156:157], v[218:219], v[114:115], v[156:157] op_sel:[0,1,0] neg_lo:[1,0,0] neg_hi:[1,0,0]
	ds_read_b128 v[212:215], v228 offset:14688
	ds_read_b128 v[216:219], v228 offset:14704
	s_waitcnt lgkmcnt(14)
	v_pk_fma_f32 v[156:157], v[220:221], v[116:117], v[156:157] op_sel_hi:[1,0,1] neg_lo:[1,0,0] neg_hi:[1,0,0]
	v_pk_fma_f32 v[156:157], v[222:223], v[116:117], v[156:157] op_sel:[0,1,0] neg_lo:[1,0,0] neg_hi:[1,0,0]
	v_pk_fma_f32 v[156:157], v[224:225], v[118:119], v[156:157] op_sel_hi:[1,0,1] neg_lo:[1,0,0] neg_hi:[1,0,0]
	v_pk_fma_f32 v[156:157], v[226:227], v[118:119], v[156:157] op_sel:[0,1,0] neg_lo:[1,0,0] neg_hi:[1,0,0]
	ds_read_b128 v[220:223], v228 offset:14720
	ds_read_b128 v[224:227], v228 offset:14736
	s_waitcnt lgkmcnt(14)
	v_pk_fma_f32 v[156:157], v[164:165], v[120:121], v[156:157] op_sel_hi:[1,0,1] neg_lo:[1,0,0] neg_hi:[1,0,0]
	v_pk_fma_f32 v[156:157], v[166:167], v[120:121], v[156:157] op_sel:[0,1,0] neg_lo:[1,0,0] neg_hi:[1,0,0]
	v_pk_fma_f32 v[156:157], v[168:169], v[122:123], v[156:157] op_sel_hi:[1,0,1] neg_lo:[1,0,0] neg_hi:[1,0,0]
	v_pk_fma_f32 v[156:157], v[170:171], v[122:123], v[156:157] op_sel:[0,1,0] neg_lo:[1,0,0] neg_hi:[1,0,0]
	ds_read_b128 v[164:167], v228 offset:14752
	ds_read_b128 v[168:171], v228 offset:14768
	s_waitcnt lgkmcnt(14)
	v_pk_fma_f32 v[156:157], v[172:173], v[124:125], v[156:157] op_sel_hi:[1,0,1] neg_lo:[1,0,0] neg_hi:[1,0,0]
	v_pk_fma_f32 v[156:157], v[174:175], v[124:125], v[156:157] op_sel:[0,1,0] neg_lo:[1,0,0] neg_hi:[1,0,0]
	v_pk_fma_f32 v[156:157], v[176:177], v[126:127], v[156:157] op_sel_hi:[1,0,1] neg_lo:[1,0,0] neg_hi:[1,0,0]
	v_pk_fma_f32 v[156:157], v[178:179], v[126:127], v[156:157] op_sel:[0,1,0] neg_lo:[1,0,0] neg_hi:[1,0,0]
	ds_read_b128 v[172:175], v228 offset:14784
	ds_read_b128 v[176:179], v228 offset:14848
	s_waitcnt lgkmcnt(14)
	v_pk_fma_f32 v[156:157], v[180:181], v[128:129], v[156:157] op_sel_hi:[1,0,1] neg_lo:[1,0,0] neg_hi:[1,0,0]
	v_pk_fma_f32 v[156:157], v[182:183], v[128:129], v[156:157] op_sel:[0,1,0] neg_lo:[1,0,0] neg_hi:[1,0,0]
	v_pk_fma_f32 v[156:157], v[184:185], v[130:131], v[156:157] op_sel_hi:[1,0,1] neg_lo:[1,0,0] neg_hi:[1,0,0]
	v_pk_fma_f32 v[156:157], v[186:187], v[130:131], v[156:157] op_sel:[0,1,0] neg_lo:[1,0,0] neg_hi:[1,0,0]
	ds_read_b128 v[180:183], v228 offset:14864
	ds_read_b128 v[184:187], v228 offset:14880
	s_waitcnt lgkmcnt(14)
	v_pk_fma_f32 v[156:157], v[188:189], v[132:133], v[156:157] op_sel_hi:[1,0,1] neg_lo:[1,0,0] neg_hi:[1,0,0]
	v_pk_fma_f32 v[156:157], v[190:191], v[132:133], v[156:157] op_sel:[0,1,0] neg_lo:[1,0,0] neg_hi:[1,0,0]
	v_pk_fma_f32 v[156:157], v[192:193], v[134:135], v[156:157] op_sel_hi:[1,0,1] neg_lo:[1,0,0] neg_hi:[1,0,0]
	v_pk_fma_f32 v[156:157], v[194:195], v[134:135], v[156:157] op_sel:[0,1,0] neg_lo:[1,0,0] neg_hi:[1,0,0]
	ds_read_b128 v[188:191], v228 offset:14896
	ds_read_b128 v[192:195], v228 offset:14912
	s_waitcnt lgkmcnt(14)
	v_pk_fma_f32 v[156:157], v[196:197], v[136:137], v[156:157] op_sel_hi:[1,0,1] neg_lo:[1,0,0] neg_hi:[1,0,0]
	v_pk_fma_f32 v[156:157], v[198:199], v[136:137], v[156:157] op_sel:[0,1,0] neg_lo:[1,0,0] neg_hi:[1,0,0]
	v_pk_fma_f32 v[156:157], v[200:201], v[138:139], v[156:157] op_sel_hi:[1,0,1] neg_lo:[1,0,0] neg_hi:[1,0,0]
	v_pk_fma_f32 v[156:157], v[202:203], v[138:139], v[156:157] op_sel:[0,1,0] neg_lo:[1,0,0] neg_hi:[1,0,0]
	ds_read_b128 v[196:199], v228 offset:14928
	ds_read_b128 v[200:203], v228 offset:14944
	s_waitcnt lgkmcnt(14)
	v_pk_fma_f32 v[156:157], v[204:205], v[140:141], v[156:157] op_sel_hi:[1,0,1] neg_lo:[1,0,0] neg_hi:[1,0,0]
	v_pk_fma_f32 v[156:157], v[206:207], v[140:141], v[156:157] op_sel:[0,1,0] neg_lo:[1,0,0] neg_hi:[1,0,0]
	v_pk_fma_f32 v[156:157], v[208:209], v[142:143], v[156:157] op_sel_hi:[1,0,1] neg_lo:[1,0,0] neg_hi:[1,0,0]
	v_pk_fma_f32 v[156:157], v[210:211], v[142:143], v[156:157] op_sel:[0,1,0] neg_lo:[1,0,0] neg_hi:[1,0,0]
	ds_read_b128 v[204:207], v228 offset:14960
	ds_read_b128 v[208:211], v228 offset:14976
	s_waitcnt lgkmcnt(14)
	v_pk_fma_f32 v[156:157], v[212:213], v[144:145], v[156:157] op_sel_hi:[1,0,1] neg_lo:[1,0,0] neg_hi:[1,0,0]
	v_pk_fma_f32 v[156:157], v[214:215], v[144:145], v[156:157] op_sel:[0,1,0] neg_lo:[1,0,0] neg_hi:[1,0,0]
	v_pk_fma_f32 v[156:157], v[216:217], v[146:147], v[156:157] op_sel_hi:[1,0,1] neg_lo:[1,0,0] neg_hi:[1,0,0]
	v_pk_fma_f32 v[156:157], v[218:219], v[146:147], v[156:157] op_sel:[0,1,0] neg_lo:[1,0,0] neg_hi:[1,0,0]
	ds_read_b128 v[212:215], v228 offset:14992
	ds_read_b128 v[216:219], v228 offset:15008
	s_waitcnt lgkmcnt(14)
	v_pk_fma_f32 v[156:157], v[220:221], v[148:149], v[156:157] op_sel_hi:[1,0,1] neg_lo:[1,0,0] neg_hi:[1,0,0]
	v_pk_fma_f32 v[156:157], v[222:223], v[148:149], v[156:157] op_sel:[0,1,0] neg_lo:[1,0,0] neg_hi:[1,0,0]
	v_pk_fma_f32 v[156:157], v[224:225], v[150:151], v[156:157] op_sel_hi:[1,0,1] neg_lo:[1,0,0] neg_hi:[1,0,0]
	v_pk_fma_f32 v[156:157], v[226:227], v[150:151], v[156:157] op_sel:[0,1,0] neg_lo:[1,0,0] neg_hi:[1,0,0]
	ds_read_b128 v[220:223], v228 offset:15024
	ds_read_b128 v[224:227], v228 offset:15040
	s_waitcnt lgkmcnt(14)
	v_pk_fma_f32 v[156:157], v[164:165], v[152:153], v[156:157] op_sel_hi:[1,0,1] neg_lo:[1,0,0] neg_hi:[1,0,0]
	v_pk_fma_f32 v[156:157], v[166:167], v[152:153], v[156:157] op_sel:[0,1,0] neg_lo:[1,0,0] neg_hi:[1,0,0]
	v_pk_fma_f32 v[156:157], v[168:169], v[154:155], v[156:157] op_sel_hi:[1,0,1] neg_lo:[1,0,0] neg_hi:[1,0,0]
	v_pk_fma_f32 v[156:157], v[170:171], v[154:155], v[156:157] op_sel:[0,1,0] neg_lo:[1,0,0] neg_hi:[1,0,0]
	ds_read_b128 v[164:167], v228 offset:15056
	ds_read_b128 v[168:171], v228 offset:15072
	s_waitcnt lgkmcnt(14)
	v_fma_f32 v157, -v173, v156, v157
	v_pk_fma_f32 v[158:159], v[176:177], v[100:101], v[158:159] op_sel_hi:[1,0,1] neg_lo:[1,0,0] neg_hi:[1,0,0]
	v_pk_fma_f32 v[158:159], v[178:179], v[100:101], v[158:159] op_sel:[0,1,0] neg_lo:[1,0,0] neg_hi:[1,0,0]
	ds_read_b128 v[172:175], v228 offset:15088
	ds_read_b128 v[176:179], v228 offset:15104
	s_waitcnt lgkmcnt(14)
	v_pk_fma_f32 v[158:159], v[180:181], v[102:103], v[158:159] op_sel_hi:[1,0,1] neg_lo:[1,0,0] neg_hi:[1,0,0]
	v_pk_fma_f32 v[158:159], v[182:183], v[102:103], v[158:159] op_sel:[0,1,0] neg_lo:[1,0,0] neg_hi:[1,0,0]
	v_pk_fma_f32 v[158:159], v[184:185], v[104:105], v[158:159] op_sel_hi:[1,0,1] neg_lo:[1,0,0] neg_hi:[1,0,0]
	v_pk_fma_f32 v[158:159], v[186:187], v[104:105], v[158:159] op_sel:[0,1,0] neg_lo:[1,0,0] neg_hi:[1,0,0]
	ds_read_b128 v[180:183], v228 offset:15120
	ds_read_b128 v[184:187], v228 offset:15136
	s_waitcnt lgkmcnt(14)
	v_pk_fma_f32 v[158:159], v[188:189], v[106:107], v[158:159] op_sel_hi:[1,0,1] neg_lo:[1,0,0] neg_hi:[1,0,0]
	v_pk_fma_f32 v[158:159], v[190:191], v[106:107], v[158:159] op_sel:[0,1,0] neg_lo:[1,0,0] neg_hi:[1,0,0]
	v_pk_fma_f32 v[158:159], v[192:193], v[108:109], v[158:159] op_sel_hi:[1,0,1] neg_lo:[1,0,0] neg_hi:[1,0,0]
	v_pk_fma_f32 v[158:159], v[194:195], v[108:109], v[158:159] op_sel:[0,1,0] neg_lo:[1,0,0] neg_hi:[1,0,0]
	ds_read_b128 v[188:191], v228 offset:15152
	ds_read_b128 v[192:195], v228 offset:15168
	s_waitcnt lgkmcnt(14)
	v_pk_fma_f32 v[158:159], v[196:197], v[110:111], v[158:159] op_sel_hi:[1,0,1] neg_lo:[1,0,0] neg_hi:[1,0,0]
	v_pk_fma_f32 v[158:159], v[198:199], v[110:111], v[158:159] op_sel:[0,1,0] neg_lo:[1,0,0] neg_hi:[1,0,0]
	v_pk_fma_f32 v[158:159], v[200:201], v[112:113], v[158:159] op_sel_hi:[1,0,1] neg_lo:[1,0,0] neg_hi:[1,0,0]
	v_pk_fma_f32 v[158:159], v[202:203], v[112:113], v[158:159] op_sel:[0,1,0] neg_lo:[1,0,0] neg_hi:[1,0,0]
	ds_read_b128 v[196:199], v228 offset:15184
	ds_read_b128 v[200:203], v228 offset:15200
	s_waitcnt lgkmcnt(14)
	v_pk_fma_f32 v[158:159], v[204:205], v[114:115], v[158:159] op_sel_hi:[1,0,1] neg_lo:[1,0,0] neg_hi:[1,0,0]
	v_pk_fma_f32 v[158:159], v[206:207], v[114:115], v[158:159] op_sel:[0,1,0] neg_lo:[1,0,0] neg_hi:[1,0,0]
	v_pk_fma_f32 v[158:159], v[208:209], v[116:117], v[158:159] op_sel_hi:[1,0,1] neg_lo:[1,0,0] neg_hi:[1,0,0]
	v_pk_fma_f32 v[158:159], v[210:211], v[116:117], v[158:159] op_sel:[0,1,0] neg_lo:[1,0,0] neg_hi:[1,0,0]
	ds_read_b128 v[204:207], v228 offset:15216
	ds_read_b128 v[208:211], v228 offset:15232
	s_waitcnt lgkmcnt(14)
	v_pk_fma_f32 v[158:159], v[212:213], v[118:119], v[158:159] op_sel_hi:[1,0,1] neg_lo:[1,0,0] neg_hi:[1,0,0]
	v_pk_fma_f32 v[158:159], v[214:215], v[118:119], v[158:159] op_sel:[0,1,0] neg_lo:[1,0,0] neg_hi:[1,0,0]
	v_pk_fma_f32 v[158:159], v[216:217], v[120:121], v[158:159] op_sel_hi:[1,0,1] neg_lo:[1,0,0] neg_hi:[1,0,0]
	v_pk_fma_f32 v[158:159], v[218:219], v[120:121], v[158:159] op_sel:[0,1,0] neg_lo:[1,0,0] neg_hi:[1,0,0]
	ds_read_b128 v[212:215], v228 offset:15248
	ds_read_b128 v[216:219], v228 offset:15264
	s_waitcnt lgkmcnt(14)
	v_pk_fma_f32 v[158:159], v[220:221], v[122:123], v[158:159] op_sel_hi:[1,0,1] neg_lo:[1,0,0] neg_hi:[1,0,0]
	v_pk_fma_f32 v[158:159], v[222:223], v[122:123], v[158:159] op_sel:[0,1,0] neg_lo:[1,0,0] neg_hi:[1,0,0]
	v_pk_fma_f32 v[158:159], v[224:225], v[124:125], v[158:159] op_sel_hi:[1,0,1] neg_lo:[1,0,0] neg_hi:[1,0,0]
	v_pk_fma_f32 v[158:159], v[226:227], v[124:125], v[158:159] op_sel:[0,1,0] neg_lo:[1,0,0] neg_hi:[1,0,0]
	ds_read_b128 v[220:223], v228 offset:15280
	ds_read_b128 v[224:227], v228 offset:15296
	s_waitcnt lgkmcnt(14)
	v_pk_fma_f32 v[158:159], v[164:165], v[126:127], v[158:159] op_sel_hi:[1,0,1] neg_lo:[1,0,0] neg_hi:[1,0,0]
	v_pk_fma_f32 v[158:159], v[166:167], v[126:127], v[158:159] op_sel:[0,1,0] neg_lo:[1,0,0] neg_hi:[1,0,0]
	v_pk_fma_f32 v[158:159], v[168:169], v[128:129], v[158:159] op_sel_hi:[1,0,1] neg_lo:[1,0,0] neg_hi:[1,0,0]
	v_pk_fma_f32 v[158:159], v[170:171], v[128:129], v[158:159] op_sel:[0,1,0] neg_lo:[1,0,0] neg_hi:[1,0,0]
	ds_read_b128 v[164:167], v228 offset:15312
	ds_read_b128 v[168:171], v228 offset:15360
	s_waitcnt lgkmcnt(14)
	v_pk_fma_f32 v[158:159], v[172:173], v[130:131], v[158:159] op_sel_hi:[1,0,1] neg_lo:[1,0,0] neg_hi:[1,0,0]
	v_pk_fma_f32 v[158:159], v[174:175], v[130:131], v[158:159] op_sel:[0,1,0] neg_lo:[1,0,0] neg_hi:[1,0,0]
	v_pk_fma_f32 v[158:159], v[176:177], v[132:133], v[158:159] op_sel_hi:[1,0,1] neg_lo:[1,0,0] neg_hi:[1,0,0]
	v_pk_fma_f32 v[158:159], v[178:179], v[132:133], v[158:159] op_sel:[0,1,0] neg_lo:[1,0,0] neg_hi:[1,0,0]
	ds_read_b128 v[172:175], v228 offset:15376
	ds_read_b128 v[176:179], v228 offset:15392
	s_waitcnt lgkmcnt(14)
	v_pk_fma_f32 v[158:159], v[180:181], v[134:135], v[158:159] op_sel_hi:[1,0,1] neg_lo:[1,0,0] neg_hi:[1,0,0]
	v_pk_fma_f32 v[158:159], v[182:183], v[134:135], v[158:159] op_sel:[0,1,0] neg_lo:[1,0,0] neg_hi:[1,0,0]
	v_pk_fma_f32 v[158:159], v[184:185], v[136:137], v[158:159] op_sel_hi:[1,0,1] neg_lo:[1,0,0] neg_hi:[1,0,0]
	v_pk_fma_f32 v[158:159], v[186:187], v[136:137], v[158:159] op_sel:[0,1,0] neg_lo:[1,0,0] neg_hi:[1,0,0]
	ds_read_b128 v[180:183], v228 offset:15408
	ds_read_b128 v[184:187], v228 offset:15424
	s_waitcnt lgkmcnt(14)
	v_pk_fma_f32 v[158:159], v[188:189], v[138:139], v[158:159] op_sel_hi:[1,0,1] neg_lo:[1,0,0] neg_hi:[1,0,0]
	v_pk_fma_f32 v[158:159], v[190:191], v[138:139], v[158:159] op_sel:[0,1,0] neg_lo:[1,0,0] neg_hi:[1,0,0]
	v_pk_fma_f32 v[158:159], v[192:193], v[140:141], v[158:159] op_sel_hi:[1,0,1] neg_lo:[1,0,0] neg_hi:[1,0,0]
	v_pk_fma_f32 v[158:159], v[194:195], v[140:141], v[158:159] op_sel:[0,1,0] neg_lo:[1,0,0] neg_hi:[1,0,0]
	ds_read_b128 v[188:191], v228 offset:15440
	ds_read_b128 v[192:195], v228 offset:15456
	s_waitcnt lgkmcnt(14)
	v_pk_fma_f32 v[158:159], v[196:197], v[142:143], v[158:159] op_sel_hi:[1,0,1] neg_lo:[1,0,0] neg_hi:[1,0,0]
	v_pk_fma_f32 v[158:159], v[198:199], v[142:143], v[158:159] op_sel:[0,1,0] neg_lo:[1,0,0] neg_hi:[1,0,0]
	v_pk_fma_f32 v[158:159], v[200:201], v[144:145], v[158:159] op_sel_hi:[1,0,1] neg_lo:[1,0,0] neg_hi:[1,0,0]
	v_pk_fma_f32 v[158:159], v[202:203], v[144:145], v[158:159] op_sel:[0,1,0] neg_lo:[1,0,0] neg_hi:[1,0,0]
	ds_read_b128 v[196:199], v228 offset:15472
	ds_read_b128 v[200:203], v228 offset:15488
	s_waitcnt lgkmcnt(14)
	v_pk_fma_f32 v[158:159], v[204:205], v[146:147], v[158:159] op_sel_hi:[1,0,1] neg_lo:[1,0,0] neg_hi:[1,0,0]
	v_pk_fma_f32 v[158:159], v[206:207], v[146:147], v[158:159] op_sel:[0,1,0] neg_lo:[1,0,0] neg_hi:[1,0,0]
	v_pk_fma_f32 v[158:159], v[208:209], v[148:149], v[158:159] op_sel_hi:[1,0,1] neg_lo:[1,0,0] neg_hi:[1,0,0]
	v_pk_fma_f32 v[158:159], v[210:211], v[148:149], v[158:159] op_sel:[0,1,0] neg_lo:[1,0,0] neg_hi:[1,0,0]
	ds_read_b128 v[204:207], v228 offset:15504
	ds_read_b128 v[208:211], v228 offset:15520
	s_waitcnt lgkmcnt(14)
	v_pk_fma_f32 v[158:159], v[212:213], v[150:151], v[158:159] op_sel_hi:[1,0,1] neg_lo:[1,0,0] neg_hi:[1,0,0]
	v_pk_fma_f32 v[158:159], v[214:215], v[150:151], v[158:159] op_sel:[0,1,0] neg_lo:[1,0,0] neg_hi:[1,0,0]
	v_pk_fma_f32 v[158:159], v[216:217], v[152:153], v[158:159] op_sel_hi:[1,0,1] neg_lo:[1,0,0] neg_hi:[1,0,0]
	v_pk_fma_f32 v[158:159], v[218:219], v[152:153], v[158:159] op_sel:[0,1,0] neg_lo:[1,0,0] neg_hi:[1,0,0]
	ds_read_b128 v[212:215], v228 offset:15536
	ds_read_b128 v[216:219], v228 offset:15552
	s_waitcnt lgkmcnt(14)
	v_pk_fma_f32 v[158:159], v[220:221], v[154:155], v[158:159] op_sel_hi:[1,0,1] neg_lo:[1,0,0] neg_hi:[1,0,0]
	v_pk_fma_f32 v[158:159], v[222:223], v[154:155], v[158:159] op_sel:[0,1,0] neg_lo:[1,0,0] neg_hi:[1,0,0]
	v_pk_fma_f32 v[158:159], v[224:225], v[156:157], v[158:159] op_sel_hi:[1,0,1] neg_lo:[1,0,0] neg_hi:[1,0,0]
	v_pk_fma_f32 v[158:159], v[226:227], v[156:157], v[158:159] op_sel:[0,1,0] neg_lo:[1,0,0] neg_hi:[1,0,0]
	ds_read_b128 v[220:223], v228 offset:15568
	ds_read_b128 v[224:227], v228 offset:15584
	s_waitcnt lgkmcnt(14)
	v_fma_f32 v159, -v165, v158, v159
	v_pk_fma_f32 v[160:161], v[168:169], v[100:101], v[160:161] op_sel_hi:[1,0,1] neg_lo:[1,0,0] neg_hi:[1,0,0]
	v_pk_fma_f32 v[160:161], v[170:171], v[100:101], v[160:161] op_sel:[0,1,0] neg_lo:[1,0,0] neg_hi:[1,0,0]
	ds_read_b128 v[164:167], v228 offset:15600
	ds_read_b128 v[168:171], v228 offset:15616
	s_waitcnt lgkmcnt(14)
	v_pk_fma_f32 v[160:161], v[172:173], v[102:103], v[160:161] op_sel_hi:[1,0,1] neg_lo:[1,0,0] neg_hi:[1,0,0]
	v_pk_fma_f32 v[160:161], v[174:175], v[102:103], v[160:161] op_sel:[0,1,0] neg_lo:[1,0,0] neg_hi:[1,0,0]
	v_pk_fma_f32 v[160:161], v[176:177], v[104:105], v[160:161] op_sel_hi:[1,0,1] neg_lo:[1,0,0] neg_hi:[1,0,0]
	v_pk_fma_f32 v[160:161], v[178:179], v[104:105], v[160:161] op_sel:[0,1,0] neg_lo:[1,0,0] neg_hi:[1,0,0]
	ds_read_b128 v[172:175], v228 offset:15632
	ds_read_b128 v[176:179], v228 offset:15648
	s_waitcnt lgkmcnt(14)
	v_pk_fma_f32 v[160:161], v[180:181], v[106:107], v[160:161] op_sel_hi:[1,0,1] neg_lo:[1,0,0] neg_hi:[1,0,0]
	v_pk_fma_f32 v[160:161], v[182:183], v[106:107], v[160:161] op_sel:[0,1,0] neg_lo:[1,0,0] neg_hi:[1,0,0]
	v_pk_fma_f32 v[160:161], v[184:185], v[108:109], v[160:161] op_sel_hi:[1,0,1] neg_lo:[1,0,0] neg_hi:[1,0,0]
	v_pk_fma_f32 v[160:161], v[186:187], v[108:109], v[160:161] op_sel:[0,1,0] neg_lo:[1,0,0] neg_hi:[1,0,0]
	ds_read_b128 v[180:183], v228 offset:15664
	ds_read_b128 v[184:187], v228 offset:15680
	s_waitcnt lgkmcnt(14)
	v_pk_fma_f32 v[160:161], v[188:189], v[110:111], v[160:161] op_sel_hi:[1,0,1] neg_lo:[1,0,0] neg_hi:[1,0,0]
	v_pk_fma_f32 v[160:161], v[190:191], v[110:111], v[160:161] op_sel:[0,1,0] neg_lo:[1,0,0] neg_hi:[1,0,0]
	v_pk_fma_f32 v[160:161], v[192:193], v[112:113], v[160:161] op_sel_hi:[1,0,1] neg_lo:[1,0,0] neg_hi:[1,0,0]
	v_pk_fma_f32 v[160:161], v[194:195], v[112:113], v[160:161] op_sel:[0,1,0] neg_lo:[1,0,0] neg_hi:[1,0,0]
	ds_read_b128 v[188:191], v228 offset:15696
	ds_read_b128 v[192:195], v228 offset:15712
	s_waitcnt lgkmcnt(14)
	v_pk_fma_f32 v[160:161], v[196:197], v[114:115], v[160:161] op_sel_hi:[1,0,1] neg_lo:[1,0,0] neg_hi:[1,0,0]
	v_pk_fma_f32 v[160:161], v[198:199], v[114:115], v[160:161] op_sel:[0,1,0] neg_lo:[1,0,0] neg_hi:[1,0,0]
	v_pk_fma_f32 v[160:161], v[200:201], v[116:117], v[160:161] op_sel_hi:[1,0,1] neg_lo:[1,0,0] neg_hi:[1,0,0]
	v_pk_fma_f32 v[160:161], v[202:203], v[116:117], v[160:161] op_sel:[0,1,0] neg_lo:[1,0,0] neg_hi:[1,0,0]
	ds_read_b128 v[196:199], v228 offset:15728
	ds_read_b128 v[200:203], v228 offset:15744
	s_waitcnt lgkmcnt(14)
	v_pk_fma_f32 v[160:161], v[204:205], v[118:119], v[160:161] op_sel_hi:[1,0,1] neg_lo:[1,0,0] neg_hi:[1,0,0]
	v_pk_fma_f32 v[160:161], v[206:207], v[118:119], v[160:161] op_sel:[0,1,0] neg_lo:[1,0,0] neg_hi:[1,0,0]
	v_pk_fma_f32 v[160:161], v[208:209], v[120:121], v[160:161] op_sel_hi:[1,0,1] neg_lo:[1,0,0] neg_hi:[1,0,0]
	v_pk_fma_f32 v[160:161], v[210:211], v[120:121], v[160:161] op_sel:[0,1,0] neg_lo:[1,0,0] neg_hi:[1,0,0]
	ds_read_b128 v[204:207], v228 offset:15760
	ds_read_b128 v[208:211], v228 offset:15776
	s_waitcnt lgkmcnt(14)
	v_pk_fma_f32 v[160:161], v[212:213], v[122:123], v[160:161] op_sel_hi:[1,0,1] neg_lo:[1,0,0] neg_hi:[1,0,0]
	v_pk_fma_f32 v[160:161], v[214:215], v[122:123], v[160:161] op_sel:[0,1,0] neg_lo:[1,0,0] neg_hi:[1,0,0]
	v_pk_fma_f32 v[160:161], v[216:217], v[124:125], v[160:161] op_sel_hi:[1,0,1] neg_lo:[1,0,0] neg_hi:[1,0,0]
	v_pk_fma_f32 v[160:161], v[218:219], v[124:125], v[160:161] op_sel:[0,1,0] neg_lo:[1,0,0] neg_hi:[1,0,0]
	ds_read_b128 v[212:215], v228 offset:15792
	ds_read_b128 v[216:219], v228 offset:15808
	s_waitcnt lgkmcnt(14)
	v_pk_fma_f32 v[160:161], v[220:221], v[126:127], v[160:161] op_sel_hi:[1,0,1] neg_lo:[1,0,0] neg_hi:[1,0,0]
	v_pk_fma_f32 v[160:161], v[222:223], v[126:127], v[160:161] op_sel:[0,1,0] neg_lo:[1,0,0] neg_hi:[1,0,0]
	v_pk_fma_f32 v[160:161], v[224:225], v[128:129], v[160:161] op_sel_hi:[1,0,1] neg_lo:[1,0,0] neg_hi:[1,0,0]
	v_pk_fma_f32 v[160:161], v[226:227], v[128:129], v[160:161] op_sel:[0,1,0] neg_lo:[1,0,0] neg_hi:[1,0,0]
	ds_read_b128 v[220:223], v228 offset:15824
	ds_read_b128 v[224:227], v228 offset:15840
	s_waitcnt lgkmcnt(14)
	v_pk_fma_f32 v[160:161], v[164:165], v[130:131], v[160:161] op_sel_hi:[1,0,1] neg_lo:[1,0,0] neg_hi:[1,0,0]
	v_pk_fma_f32 v[160:161], v[166:167], v[130:131], v[160:161] op_sel:[0,1,0] neg_lo:[1,0,0] neg_hi:[1,0,0]
	v_pk_fma_f32 v[160:161], v[168:169], v[132:133], v[160:161] op_sel_hi:[1,0,1] neg_lo:[1,0,0] neg_hi:[1,0,0]
	v_pk_fma_f32 v[160:161], v[170:171], v[132:133], v[160:161] op_sel:[0,1,0] neg_lo:[1,0,0] neg_hi:[1,0,0]
	ds_read_b128 v[164:167], v228 offset:15872
	ds_read_b128 v[168:171], v228 offset:15888
	s_waitcnt lgkmcnt(14)
	v_pk_fma_f32 v[160:161], v[172:173], v[134:135], v[160:161] op_sel_hi:[1,0,1] neg_lo:[1,0,0] neg_hi:[1,0,0]
	v_pk_fma_f32 v[160:161], v[174:175], v[134:135], v[160:161] op_sel:[0,1,0] neg_lo:[1,0,0] neg_hi:[1,0,0]
	v_pk_fma_f32 v[160:161], v[176:177], v[136:137], v[160:161] op_sel_hi:[1,0,1] neg_lo:[1,0,0] neg_hi:[1,0,0]
	v_pk_fma_f32 v[160:161], v[178:179], v[136:137], v[160:161] op_sel:[0,1,0] neg_lo:[1,0,0] neg_hi:[1,0,0]
	ds_read_b128 v[172:175], v228 offset:15904
	ds_read_b128 v[176:179], v228 offset:15920
	s_waitcnt lgkmcnt(14)
	v_pk_fma_f32 v[160:161], v[180:181], v[138:139], v[160:161] op_sel_hi:[1,0,1] neg_lo:[1,0,0] neg_hi:[1,0,0]
	v_pk_fma_f32 v[160:161], v[182:183], v[138:139], v[160:161] op_sel:[0,1,0] neg_lo:[1,0,0] neg_hi:[1,0,0]
	v_pk_fma_f32 v[160:161], v[184:185], v[140:141], v[160:161] op_sel_hi:[1,0,1] neg_lo:[1,0,0] neg_hi:[1,0,0]
	v_pk_fma_f32 v[160:161], v[186:187], v[140:141], v[160:161] op_sel:[0,1,0] neg_lo:[1,0,0] neg_hi:[1,0,0]
	ds_read_b128 v[180:183], v228 offset:15936
	ds_read_b128 v[184:187], v228 offset:15952
	s_waitcnt lgkmcnt(14)
	v_pk_fma_f32 v[160:161], v[188:189], v[142:143], v[160:161] op_sel_hi:[1,0,1] neg_lo:[1,0,0] neg_hi:[1,0,0]
	v_pk_fma_f32 v[160:161], v[190:191], v[142:143], v[160:161] op_sel:[0,1,0] neg_lo:[1,0,0] neg_hi:[1,0,0]
	v_pk_fma_f32 v[160:161], v[192:193], v[144:145], v[160:161] op_sel_hi:[1,0,1] neg_lo:[1,0,0] neg_hi:[1,0,0]
	v_pk_fma_f32 v[160:161], v[194:195], v[144:145], v[160:161] op_sel:[0,1,0] neg_lo:[1,0,0] neg_hi:[1,0,0]
	ds_read_b128 v[188:191], v228 offset:15968
	ds_read_b128 v[192:195], v228 offset:15984
	s_waitcnt lgkmcnt(14)
	v_pk_fma_f32 v[160:161], v[196:197], v[146:147], v[160:161] op_sel_hi:[1,0,1] neg_lo:[1,0,0] neg_hi:[1,0,0]
	v_pk_fma_f32 v[160:161], v[198:199], v[146:147], v[160:161] op_sel:[0,1,0] neg_lo:[1,0,0] neg_hi:[1,0,0]
	v_pk_fma_f32 v[160:161], v[200:201], v[148:149], v[160:161] op_sel_hi:[1,0,1] neg_lo:[1,0,0] neg_hi:[1,0,0]
	v_pk_fma_f32 v[160:161], v[202:203], v[148:149], v[160:161] op_sel:[0,1,0] neg_lo:[1,0,0] neg_hi:[1,0,0]
	ds_read_b128 v[196:199], v228 offset:16000
	ds_read_b128 v[200:203], v228 offset:16016
	s_waitcnt lgkmcnt(14)
	v_pk_fma_f32 v[160:161], v[204:205], v[150:151], v[160:161] op_sel_hi:[1,0,1] neg_lo:[1,0,0] neg_hi:[1,0,0]
	v_pk_fma_f32 v[160:161], v[206:207], v[150:151], v[160:161] op_sel:[0,1,0] neg_lo:[1,0,0] neg_hi:[1,0,0]
	v_pk_fma_f32 v[160:161], v[208:209], v[152:153], v[160:161] op_sel_hi:[1,0,1] neg_lo:[1,0,0] neg_hi:[1,0,0]
	v_pk_fma_f32 v[160:161], v[210:211], v[152:153], v[160:161] op_sel:[0,1,0] neg_lo:[1,0,0] neg_hi:[1,0,0]
	ds_read_b128 v[204:207], v228 offset:16032
	ds_read_b128 v[208:211], v228 offset:16048
	s_waitcnt lgkmcnt(14)
	v_pk_fma_f32 v[160:161], v[212:213], v[154:155], v[160:161] op_sel_hi:[1,0,1] neg_lo:[1,0,0] neg_hi:[1,0,0]
	v_pk_fma_f32 v[160:161], v[214:215], v[154:155], v[160:161] op_sel:[0,1,0] neg_lo:[1,0,0] neg_hi:[1,0,0]
	v_pk_fma_f32 v[160:161], v[216:217], v[156:157], v[160:161] op_sel_hi:[1,0,1] neg_lo:[1,0,0] neg_hi:[1,0,0]
	v_pk_fma_f32 v[160:161], v[218:219], v[156:157], v[160:161] op_sel:[0,1,0] neg_lo:[1,0,0] neg_hi:[1,0,0]
	ds_read_b128 v[212:215], v228 offset:16064
	ds_read_b128 v[216:219], v228 offset:16080
	s_waitcnt lgkmcnt(14)
	v_pk_fma_f32 v[160:161], v[220:221], v[158:159], v[160:161] op_sel_hi:[1,0,1] neg_lo:[1,0,0] neg_hi:[1,0,0]
	v_pk_fma_f32 v[160:161], v[222:223], v[158:159], v[160:161] op_sel:[0,1,0] neg_lo:[1,0,0] neg_hi:[1,0,0]
	v_fma_f32 v161, -v225, v160, v161
	ds_read_b128 v[220:223], v228 offset:16096
	ds_read_b128 v[224:227], v228 offset:16112
	s_barrier
	s_waitcnt lgkmcnt(14)
	v_pk_fma_f32 v[162:163], v[164:165], v[100:101], v[162:163] op_sel_hi:[1,0,1] neg_lo:[1,0,0] neg_hi:[1,0,0]
	v_pk_fma_f32 v[162:163], v[166:167], v[100:101], v[162:163] op_sel:[0,1,0] neg_lo:[1,0,0] neg_hi:[1,0,0]
	v_pk_fma_f32 v[162:163], v[168:169], v[102:103], v[162:163] op_sel_hi:[1,0,1] neg_lo:[1,0,0] neg_hi:[1,0,0]
	v_pk_fma_f32 v[162:163], v[170:171], v[102:103], v[162:163] op_sel:[0,1,0] neg_lo:[1,0,0] neg_hi:[1,0,0]
	ds_read_b128 v[164:167], v228 offset:16128
	ds_read_b128 v[168:171], v228 offset:16144
	s_waitcnt lgkmcnt(14)
	v_pk_fma_f32 v[162:163], v[172:173], v[104:105], v[162:163] op_sel_hi:[1,0,1] neg_lo:[1,0,0] neg_hi:[1,0,0]
	v_pk_fma_f32 v[162:163], v[174:175], v[104:105], v[162:163] op_sel:[0,1,0] neg_lo:[1,0,0] neg_hi:[1,0,0]
	v_pk_fma_f32 v[162:163], v[176:177], v[106:107], v[162:163] op_sel_hi:[1,0,1] neg_lo:[1,0,0] neg_hi:[1,0,0]
	v_pk_fma_f32 v[162:163], v[178:179], v[106:107], v[162:163] op_sel:[0,1,0] neg_lo:[1,0,0] neg_hi:[1,0,0]
	ds_read_b128 v[172:175], v228 offset:16160
	ds_read_b128 v[176:179], v228 offset:16176
	s_waitcnt lgkmcnt(14)
	v_pk_fma_f32 v[162:163], v[180:181], v[108:109], v[162:163] op_sel_hi:[1,0,1] neg_lo:[1,0,0] neg_hi:[1,0,0]
	v_pk_fma_f32 v[162:163], v[182:183], v[108:109], v[162:163] op_sel:[0,1,0] neg_lo:[1,0,0] neg_hi:[1,0,0]
	v_pk_fma_f32 v[162:163], v[184:185], v[110:111], v[162:163] op_sel_hi:[1,0,1] neg_lo:[1,0,0] neg_hi:[1,0,0]
	v_pk_fma_f32 v[162:163], v[186:187], v[110:111], v[162:163] op_sel:[0,1,0] neg_lo:[1,0,0] neg_hi:[1,0,0]
	ds_read_b128 v[180:183], v228 offset:16192
	ds_read_b128 v[184:187], v228 offset:16208
	s_waitcnt lgkmcnt(14)
	v_pk_fma_f32 v[162:163], v[188:189], v[112:113], v[162:163] op_sel_hi:[1,0,1] neg_lo:[1,0,0] neg_hi:[1,0,0]
	v_pk_fma_f32 v[162:163], v[190:191], v[112:113], v[162:163] op_sel:[0,1,0] neg_lo:[1,0,0] neg_hi:[1,0,0]
	v_pk_fma_f32 v[162:163], v[192:193], v[114:115], v[162:163] op_sel_hi:[1,0,1] neg_lo:[1,0,0] neg_hi:[1,0,0]
	v_pk_fma_f32 v[162:163], v[194:195], v[114:115], v[162:163] op_sel:[0,1,0] neg_lo:[1,0,0] neg_hi:[1,0,0]
	ds_read_b128 v[188:191], v228 offset:16224
	ds_read_b128 v[192:195], v228 offset:16240
	s_waitcnt lgkmcnt(14)
	v_pk_fma_f32 v[162:163], v[196:197], v[116:117], v[162:163] op_sel_hi:[1,0,1] neg_lo:[1,0,0] neg_hi:[1,0,0]
	v_pk_fma_f32 v[162:163], v[198:199], v[116:117], v[162:163] op_sel:[0,1,0] neg_lo:[1,0,0] neg_hi:[1,0,0]
	v_pk_fma_f32 v[162:163], v[200:201], v[118:119], v[162:163] op_sel_hi:[1,0,1] neg_lo:[1,0,0] neg_hi:[1,0,0]
	v_pk_fma_f32 v[162:163], v[202:203], v[118:119], v[162:163] op_sel:[0,1,0] neg_lo:[1,0,0] neg_hi:[1,0,0]
	ds_read_b128 v[196:199], v228 offset:16256
	ds_read_b128 v[200:203], v228 offset:16272
	s_waitcnt lgkmcnt(14)
	v_pk_fma_f32 v[162:163], v[204:205], v[120:121], v[162:163] op_sel_hi:[1,0,1] neg_lo:[1,0,0] neg_hi:[1,0,0]
	v_pk_fma_f32 v[162:163], v[206:207], v[120:121], v[162:163] op_sel:[0,1,0] neg_lo:[1,0,0] neg_hi:[1,0,0]
	v_pk_fma_f32 v[162:163], v[208:209], v[122:123], v[162:163] op_sel_hi:[1,0,1] neg_lo:[1,0,0] neg_hi:[1,0,0]
	v_pk_fma_f32 v[162:163], v[210:211], v[122:123], v[162:163] op_sel:[0,1,0] neg_lo:[1,0,0] neg_hi:[1,0,0]
	ds_read_b128 v[204:207], v228 offset:16288
	ds_read_b128 v[208:211], v228 offset:16304
	s_waitcnt lgkmcnt(14)
	v_pk_fma_f32 v[162:163], v[212:213], v[124:125], v[162:163] op_sel_hi:[1,0,1] neg_lo:[1,0,0] neg_hi:[1,0,0]
	v_pk_fma_f32 v[162:163], v[214:215], v[124:125], v[162:163] op_sel:[0,1,0] neg_lo:[1,0,0] neg_hi:[1,0,0]
	v_pk_fma_f32 v[162:163], v[216:217], v[126:127], v[162:163] op_sel_hi:[1,0,1] neg_lo:[1,0,0] neg_hi:[1,0,0]
	v_pk_fma_f32 v[162:163], v[218:219], v[126:127], v[162:163] op_sel:[0,1,0] neg_lo:[1,0,0] neg_hi:[1,0,0]
	ds_read_b128 v[212:215], v228 offset:16320
	ds_read_b128 v[216:219], v228 offset:16336
	s_waitcnt lgkmcnt(14)
	v_pk_fma_f32 v[162:163], v[220:221], v[128:129], v[162:163] op_sel_hi:[1,0,1] neg_lo:[1,0,0] neg_hi:[1,0,0]
	v_pk_fma_f32 v[162:163], v[222:223], v[128:129], v[162:163] op_sel:[0,1,0] neg_lo:[1,0,0] neg_hi:[1,0,0]
	v_pk_fma_f32 v[162:163], v[224:225], v[130:131], v[162:163] op_sel_hi:[1,0,1] neg_lo:[1,0,0] neg_hi:[1,0,0]
	v_pk_fma_f32 v[162:163], v[226:227], v[130:131], v[162:163] op_sel:[0,1,0] neg_lo:[1,0,0] neg_hi:[1,0,0]
	ds_read_b128 v[220:223], v228 offset:16352
	ds_read_b128 v[224:227], v228 offset:16368
	s_waitcnt lgkmcnt(14)
	v_pk_fma_f32 v[162:163], v[164:165], v[132:133], v[162:163] op_sel_hi:[1,0,1] neg_lo:[1,0,0] neg_hi:[1,0,0]
	v_pk_fma_f32 v[162:163], v[166:167], v[132:133], v[162:163] op_sel:[0,1,0] neg_lo:[1,0,0] neg_hi:[1,0,0]
	v_pk_fma_f32 v[162:163], v[168:169], v[134:135], v[162:163] op_sel_hi:[1,0,1] neg_lo:[1,0,0] neg_hi:[1,0,0]
	v_pk_fma_f32 v[162:163], v[170:171], v[134:135], v[162:163] op_sel:[0,1,0] neg_lo:[1,0,0] neg_hi:[1,0,0]
	s_waitcnt lgkmcnt(12)
	v_pk_fma_f32 v[162:163], v[172:173], v[136:137], v[162:163] op_sel_hi:[1,0,1] neg_lo:[1,0,0] neg_hi:[1,0,0]
	v_pk_fma_f32 v[162:163], v[174:175], v[136:137], v[162:163] op_sel:[0,1,0] neg_lo:[1,0,0] neg_hi:[1,0,0]
	v_pk_fma_f32 v[162:163], v[176:177], v[138:139], v[162:163] op_sel_hi:[1,0,1] neg_lo:[1,0,0] neg_hi:[1,0,0]
	v_pk_fma_f32 v[162:163], v[178:179], v[138:139], v[162:163] op_sel:[0,1,0] neg_lo:[1,0,0] neg_hi:[1,0,0]
	s_waitcnt lgkmcnt(10)
	v_pk_fma_f32 v[162:163], v[180:181], v[140:141], v[162:163] op_sel_hi:[1,0,1] neg_lo:[1,0,0] neg_hi:[1,0,0]
	v_pk_fma_f32 v[162:163], v[182:183], v[140:141], v[162:163] op_sel:[0,1,0] neg_lo:[1,0,0] neg_hi:[1,0,0]
	v_pk_fma_f32 v[162:163], v[184:185], v[142:143], v[162:163] op_sel_hi:[1,0,1] neg_lo:[1,0,0] neg_hi:[1,0,0]
	v_pk_fma_f32 v[162:163], v[186:187], v[142:143], v[162:163] op_sel:[0,1,0] neg_lo:[1,0,0] neg_hi:[1,0,0]
	s_waitcnt lgkmcnt(8)
	v_pk_fma_f32 v[162:163], v[188:189], v[144:145], v[162:163] op_sel_hi:[1,0,1] neg_lo:[1,0,0] neg_hi:[1,0,0]
	v_pk_fma_f32 v[162:163], v[190:191], v[144:145], v[162:163] op_sel:[0,1,0] neg_lo:[1,0,0] neg_hi:[1,0,0]
	v_pk_fma_f32 v[162:163], v[192:193], v[146:147], v[162:163] op_sel_hi:[1,0,1] neg_lo:[1,0,0] neg_hi:[1,0,0]
	v_pk_fma_f32 v[162:163], v[194:195], v[146:147], v[162:163] op_sel:[0,1,0] neg_lo:[1,0,0] neg_hi:[1,0,0]
	s_waitcnt lgkmcnt(6)
	v_pk_fma_f32 v[162:163], v[196:197], v[148:149], v[162:163] op_sel_hi:[1,0,1] neg_lo:[1,0,0] neg_hi:[1,0,0]
	v_pk_fma_f32 v[162:163], v[198:199], v[148:149], v[162:163] op_sel:[0,1,0] neg_lo:[1,0,0] neg_hi:[1,0,0]
	v_pk_fma_f32 v[162:163], v[200:201], v[150:151], v[162:163] op_sel_hi:[1,0,1] neg_lo:[1,0,0] neg_hi:[1,0,0]
	v_pk_fma_f32 v[162:163], v[202:203], v[150:151], v[162:163] op_sel:[0,1,0] neg_lo:[1,0,0] neg_hi:[1,0,0]
	s_waitcnt lgkmcnt(4)
	v_pk_fma_f32 v[162:163], v[204:205], v[152:153], v[162:163] op_sel_hi:[1,0,1] neg_lo:[1,0,0] neg_hi:[1,0,0]
	v_pk_fma_f32 v[162:163], v[206:207], v[152:153], v[162:163] op_sel:[0,1,0] neg_lo:[1,0,0] neg_hi:[1,0,0]
	v_pk_fma_f32 v[162:163], v[208:209], v[154:155], v[162:163] op_sel_hi:[1,0,1] neg_lo:[1,0,0] neg_hi:[1,0,0]
	v_pk_fma_f32 v[162:163], v[210:211], v[154:155], v[162:163] op_sel:[0,1,0] neg_lo:[1,0,0] neg_hi:[1,0,0]
	s_waitcnt lgkmcnt(2)
	v_pk_fma_f32 v[162:163], v[212:213], v[156:157], v[162:163] op_sel_hi:[1,0,1] neg_lo:[1,0,0] neg_hi:[1,0,0]
	v_pk_fma_f32 v[162:163], v[214:215], v[156:157], v[162:163] op_sel:[0,1,0] neg_lo:[1,0,0] neg_hi:[1,0,0]
	v_pk_fma_f32 v[162:163], v[216:217], v[158:159], v[162:163] op_sel_hi:[1,0,1] neg_lo:[1,0,0] neg_hi:[1,0,0]
	v_pk_fma_f32 v[162:163], v[218:219], v[158:159], v[162:163] op_sel:[0,1,0] neg_lo:[1,0,0] neg_hi:[1,0,0]
	s_waitcnt lgkmcnt(0)
	v_pk_fma_f32 v[162:163], v[220:221], v[160:161], v[162:163] op_sel_hi:[1,0,1] neg_lo:[1,0,0] neg_hi:[1,0,0]
	v_pk_fma_f32 v[162:163], v[222:223], v[160:161], v[162:163] op_sel:[0,1,0] neg_lo:[1,0,0] neg_hi:[1,0,0]
	v_fma_f32 v163, -v225, v162, v163
	v_cvt_pk_bf16_f32 v35, v102, v103
	v_cvt_pk_bf16_f32 v34, v100, v101
	v_cvt_pk_bf16_f32 v32, v104, v105
	v_cvt_pk_bf16_f32 v33, v106, v107
	v_cvt_pk_bf16_f32 v30, v108, v109
	v_cvt_pk_bf16_f32 v31, v110, v111
	v_cvt_pk_bf16_f32 v28, v112, v113
	v_cvt_pk_bf16_f32 v29, v114, v115
	v_cvt_pk_bf16_f32 v26, v116, v117
	v_cvt_pk_bf16_f32 v27, v118, v119
	v_cvt_pk_bf16_f32 v24, v120, v121
	v_cvt_pk_bf16_f32 v25, v122, v123
	v_cvt_pk_bf16_f32 v18, v124, v125
	v_cvt_pk_bf16_f32 v19, v126, v127
	v_cvt_pk_bf16_f32 v16, v128, v129
	v_cvt_pk_bf16_f32 v17, v130, v131
	v_cvt_pk_bf16_f32 v14, v132, v133
	v_cvt_pk_bf16_f32 v15, v134, v135
	v_cvt_pk_bf16_f32 v12, v136, v137
	v_cvt_pk_bf16_f32 v13, v138, v139
	v_cvt_pk_bf16_f32 v10, v140, v141
	v_cvt_pk_bf16_f32 v11, v142, v143
	v_cvt_pk_bf16_f32 v8, v144, v145
	v_cvt_pk_bf16_f32 v9, v146, v147
	v_cvt_pk_bf16_f32 v6, v148, v149
	v_cvt_pk_bf16_f32 v7, v150, v151
	v_cvt_pk_bf16_f32 v4, v152, v153
	v_cvt_pk_bf16_f32 v5, v154, v155
	v_cvt_pk_bf16_f32 v2, v156, v157
	v_cvt_pk_bf16_f32 v3, v158, v159
	v_cvt_pk_bf16_f32 v0, v160, v161
	v_cvt_pk_bf16_f32 v1, v162, v163
	s_and_saveexec_b64 s[0:1], vcc
	s_xor_b64 s[0:1], exec, s[0:1]
	s_cbranch_execz .LBB0_419
	v_and_b32_e32 v39, 0x7ffffff0, v39
	v_lshlrev_b32_e32 v39, 1, v39
	v_lshlrev_b32_e32 v22, 1, v22
	v_add3_u32 v22, 0, v39, v22
	v_lshlrev_b32_e32 v39, 2, v77
	v_lshlrev_b32_e32 v38, 1, v38
	v_and_b32_e32 v39, 16, v39
	v_add3_u32 v22, v22, v38, v39
	ds_write_b16 v22, v34
	ds_write_b16_d16_hi v22, v34 offset:272
	ds_write_b16 v22, v35 offset:544
	ds_write_b16_d16_hi v22, v35 offset:816
	ds_write_b16 v22, v32 offset:1088
	ds_write_b16_d16_hi v22, v32 offset:1360
	ds_write_b16 v22, v33 offset:1632
	ds_write_b16_d16_hi v22, v33 offset:1904
	ds_write_b16 v22, v30 offset:2176
	ds_write_b16_d16_hi v22, v30 offset:2448
	ds_write_b16 v22, v31 offset:2720
	ds_write_b16_d16_hi v22, v31 offset:2992
	ds_write_b16 v22, v28 offset:3264
	ds_write_b16_d16_hi v22, v28 offset:3536
	ds_write_b16 v22, v29 offset:3808
	ds_write_b16_d16_hi v22, v29 offset:4080
	ds_write_b16 v22, v26 offset:4352
	ds_write_b16_d16_hi v22, v26 offset:4624
	ds_write_b16 v22, v27 offset:4896
	ds_write_b16_d16_hi v22, v27 offset:5168
	ds_write_b16 v22, v24 offset:5440
	ds_write_b16_d16_hi v22, v24 offset:5712
	ds_write_b16 v22, v25 offset:5984
	ds_write_b16_d16_hi v22, v25 offset:6256
	ds_write_b16 v22, v18 offset:6528
	ds_write_b16_d16_hi v22, v18 offset:6800
	ds_write_b16 v22, v19 offset:7072
	ds_write_b16_d16_hi v22, v19 offset:7344
	ds_write_b16 v22, v16 offset:7616
	ds_write_b16_d16_hi v22, v16 offset:7888
	ds_write_b16 v22, v17 offset:8160
	ds_write_b16_d16_hi v22, v17 offset:8432
	ds_write_b16 v22, v14 offset:8704
	ds_write_b16_d16_hi v22, v14 offset:8976
	ds_write_b16 v22, v15 offset:9248
	ds_write_b16_d16_hi v22, v15 offset:9520
	ds_write_b16 v22, v12 offset:9792
	ds_write_b16_d16_hi v22, v12 offset:10064
	ds_write_b16 v22, v13 offset:10336
	ds_write_b16_d16_hi v22, v13 offset:10608
	ds_write_b16 v22, v10 offset:10880
	ds_write_b16_d16_hi v22, v10 offset:11152
	ds_write_b16 v22, v11 offset:11424
	ds_write_b16_d16_hi v22, v11 offset:11696
	ds_write_b16 v22, v8 offset:11968
	ds_write_b16_d16_hi v22, v8 offset:12240
	ds_write_b16 v22, v9 offset:12512
	ds_write_b16_d16_hi v22, v9 offset:12784
	ds_write_b16 v22, v6 offset:13056
	ds_write_b16_d16_hi v22, v6 offset:13328
	ds_write_b16 v22, v7 offset:13600
	ds_write_b16_d16_hi v22, v7 offset:13872
	ds_write_b16 v22, v4 offset:14144
	ds_write_b16_d16_hi v22, v4 offset:14416
	ds_write_b16 v22, v5 offset:14688
	ds_write_b16_d16_hi v22, v5 offset:14960
	ds_write_b16 v22, v2 offset:15232
	ds_write_b16_d16_hi v22, v2 offset:15504
	ds_write_b16 v22, v3 offset:15776
	ds_write_b16_d16_hi v22, v3 offset:16048
	ds_write_b16 v22, v0 offset:16320
	ds_write_b16_d16_hi v22, v0 offset:16592
	ds_write_b16 v22, v1 offset:16864
	ds_write_b16_d16_hi v22, v1 offset:17136
